# GEMM phases: accumulator clears (127 v_mov per tile) dropped, peeled first K iteration takes C=0 on each accumulator's first MFMA
# speedup vs baseline: 1.0106x; 1.0093x over previous
; #define PG8_STAGE(bufoff, gbase, voff) do { _Pragma("unroll") for (int _i = 0; _i < 2; ++_i) \
;         __builtin_amdgcn_global_load_lds((const unsigned*)((const char*)(gbase) + (voff)[_i]), (LAS unsigned*)(lds + (bufoff) + ldsw + _i * 8192), 16, 0, 0); } while (0)
; #define PG8_LDA(dst, b, h) do { _Pragma("unroll") for (int m = 0; m < 4; ++m) _Pragma("unroll") for (int k = 0; k < 2; ++k) dst[m][k] = *(const LAS bf16x8*)(lds + PG8_SA(b, h) + aoff + m * 2048 + k * 1024); } while (0)
; #define PG8_LDB(dst, b, h) do { _Pragma("unroll") for (int n = 0; n < 2; ++n) _Pragma("unroll") for (int k = 0; k < 2; ++k) dst[n][k] = *(const LAS bf16x8*)(lds + PG8_SB(b, h) + boff + n * 2048 + k * 1024); } while (0)
; #define PG8_MMA(ai, bj, At, Bt) do { __builtin_amdgcn_s_setprio(1); _Pragma("unroll") for (int m = 0; m < 4; ++m) _Pragma("unroll") for (int n = 0; n < 2; ++n) _Pragma("unroll") for (int k = 0; k < 2; ++k) \
;         acc[ai][bj][m][n] = __builtin_amdgcn_mfma_f32_16x16x32_bf16(Bt[n][k], At[m][k], acc[ai][bj][m][n], 0, 0, 0); __builtin_amdgcn_s_setprio(0); } while (0)
; #define PG8_WAIT_V(n) asm volatile("s_waitcnt vmcnt(" #n ")" ::: "memory")
; #define PG8_WAIT_L(n) asm volatile("s_waitcnt lgkmcnt(" #n ")" ::: "memory")
; #define PG8_BAR __builtin_amdgcn_s_barrier()
; #define PG8_SCHED __builtin_amdgcn_sched_barrier(0)
; template <class Epi>
; DI void gemm_phase(LAS unsigned char* lds, const int wid, const Gemm g, const Order& S, const Epi& E) {
;     ...
;             PG8_LDB(B0, 0, 0); PG8_LDB(B1, 0, 1); PG8_SCHED; PG8_LDA(At, 0, 0); PG8_STAGE(PG8_SA(1, 1), a1 + hstepA, voffA);
;             PG8_WAIT_V(8); PG8_WAIT_L(0); PG8_BAR; PG8_MMA(0, 0, At, B0); PG8_MMA(0, 1, At, B1); PG8_BAR; PG8_SCHED;
;             PG8_LDA(At, 0, 1); PG8_STAGE(PG8_SB(0, 0), b2, voffB); PG8_STAGE(PG8_SB(0, 1), b2 + hstepB, voffB); PG8_STAGE(PG8_SA(0, 0), a2, voffA);
;             PG8_WAIT_V(8); PG8_WAIT_L(0); PG8_BAR; PG8_MMA(1, 0, At, B0); PG8_MMA(1, 1, At, B1); PG8_BAR; PG8_SCHED;
;     ...
;         for (int a = 0; a < 2; ++a)
; #pragma unroll
;             for (int b = 0; b < 2; ++b)
; #pragma unroll
;                 for (int m = 0; m < 4; ++m)
; #pragma unroll
;                     for (int n = 0; n < 2; ++n) acc[a][b][m][n] = (f32x4){0.f, 0.f, 0.f, 0.f};
.LBB0_227:
	s_ashr_i32 s31, s30, 31
	s_lshl_b64 s[36:37], s[30:31], 19
	s_add_u32 s36, s21, s36
	s_addc_u32 s37, s25, s37
	s_and_b64 s[38:39], s[6:7], exec
	s_cselect_b32 s31, s37, s43
	s_cselect_b32 s59, s36, s42
	s_ashr_i32 s35, s34, 31
	s_lshl_b64 s[38:39], s[34:35], 19
	s_add_u32 s38, s8, s38
	s_addc_u32 s39, s9, s39
	s_and_b64 s[46:47], s[6:7], exec
	s_cselect_b32 s35, s39, s45
	s_cselect_b32 s60, s38, s44
	s_add_u32 s42, s42, 0x40080
	s_addc_u32 s43, s43, 0
	s_add_u32 s61, s44, 0x100
	v_mov_b32_e32 v0, 0
	s_addc_u32 s62, s45, 0
	s_mov_b32 s63, -2
	ds_read_b128 v[164:167], v151
	ds_read_b128 v[168:171], v151 offset:1024
	ds_read_b128 v[172:175], v151 offset:2048
	ds_read_b128 v[176:179], v151 offset:3072
	ds_read_b128 v[180:183], v155
	ds_read_b128 v[184:187], v155 offset:1024
	ds_read_b128 v[188:191], v155 offset:2048
	ds_read_b128 v[192:195], v155 offset:3072
	s_add_u32 s44, s42, 0xfffc0080
	s_addc_u32 s45, s43, -1
	s_cmp_eq_u32 s63, 12
	s_cselect_b32 s47, s31, s45
	s_cselect_b32 s46, s59, s44
	s_cselect_b32 s45, s35, s62
	s_cselect_b32 s44, s60, s61
	v_lshl_add_u64 v[144:145], s[42:43], 0, v[136:137]
	s_add_i32 m0, s27, 0xc000
	ds_read_b128 v[196:199], v159
	ds_read_b128 v[200:203], v159 offset:1024
	ds_read_b128 v[204:207], v159 offset:2048
	ds_read_b128 v[208:211], v159 offset:3072
	ds_read_b128 v[216:219], v159 offset:4096
	ds_read_b128 v[220:223], v159 offset:5120
	ds_read_b128 v[224:227], v159 offset:6144
	ds_read_b128 v[228:231], v159 offset:7168
	global_load_lds_dwordx4 v[144:145], off
	v_lshl_add_u64 v[144:145], s[42:43], 0, v[138:139]
	s_add_i32 m0, s27, 0xe000
	s_nop 0
	global_load_lds_dwordx4 v[144:145], off
	s_waitcnt vmcnt(8)
	s_waitcnt lgkmcnt(0)
	s_barrier
	s_setprio 1
	s_waitcnt lgkmcnt(0)
	v_mfma_f32_16x16x32_bf16 v[124:127], v[164:167], v[196:199], 0
	v_mfma_f32_16x16x32_bf16 v[120:123], v[172:175], v[196:199], 0
	v_mfma_f32_16x16x32_bf16 v[108:111], v[164:167], v[204:207], 0
	v_mfma_f32_16x16x32_bf16 v[104:107], v[172:175], v[204:207], 0
	v_mfma_f32_16x16x32_bf16 v[92:95], v[164:167], v[216:219], 0
	v_mfma_f32_16x16x32_bf16 v[88:91], v[172:175], v[216:219], 0
	v_mfma_f32_16x16x32_bf16 v[76:79], v[164:167], v[224:227], 0
	v_mfma_f32_16x16x32_bf16 v[72:75], v[172:175], v[224:227], 0
	v_mfma_f32_16x16x32_bf16 v[124:127], v[168:171], v[200:203], v[124:127]
	v_mfma_f32_16x16x32_bf16 v[120:123], v[176:179], v[200:203], v[120:123]
	v_mfma_f32_16x16x32_bf16 v[108:111], v[168:171], v[208:211], v[108:111]
	v_mfma_f32_16x16x32_bf16 v[104:107], v[176:179], v[208:211], v[104:107]
	v_mfma_f32_16x16x32_bf16 v[92:95], v[168:171], v[220:223], v[92:95]
	v_mfma_f32_16x16x32_bf16 v[88:91], v[176:179], v[220:223], v[88:91]
	v_mfma_f32_16x16x32_bf16 v[76:79], v[168:171], v[228:231], v[76:79]
	v_mfma_f32_16x16x32_bf16 v[72:75], v[176:179], v[228:231], v[72:75]
	s_setprio 0
	s_setprio 1
	v_mfma_f32_16x16x32_bf16 v[116:119], v[180:183], v[196:199], 0
	v_mfma_f32_16x16x32_bf16 v[112:115], v[188:191], v[196:199], 0
	v_mfma_f32_16x16x32_bf16 v[100:103], v[180:183], v[204:207], 0
	v_mfma_f32_16x16x32_bf16 v[96:99], v[188:191], v[204:207], 0
	v_mfma_f32_16x16x32_bf16 v[84:87], v[180:183], v[216:219], 0
	v_mfma_f32_16x16x32_bf16 v[80:83], v[188:191], v[216:219], 0
	v_mfma_f32_16x16x32_bf16 v[68:71], v[180:183], v[224:227], 0
	v_mfma_f32_16x16x32_bf16 v[64:67], v[188:191], v[224:227], 0
	v_mfma_f32_16x16x32_bf16 v[116:119], v[184:187], v[200:203], v[116:119]
	v_mfma_f32_16x16x32_bf16 v[112:115], v[192:195], v[200:203], v[112:115]
	v_mfma_f32_16x16x32_bf16 v[100:103], v[184:187], v[208:211], v[100:103]
	v_mfma_f32_16x16x32_bf16 v[96:99], v[192:195], v[208:211], v[96:99]
	v_mfma_f32_16x16x32_bf16 v[84:87], v[184:187], v[220:223], v[84:87]
	v_mfma_f32_16x16x32_bf16 v[80:83], v[192:195], v[220:223], v[80:83]
	v_mfma_f32_16x16x32_bf16 v[68:71], v[184:187], v[228:231], v[68:71]
	v_mfma_f32_16x16x32_bf16 v[64:67], v[192:195], v[228:231], v[64:67]
	s_setprio 0
	s_barrier
	s_add_i32 s64, s56, s94
	v_lshl_add_u64 v[144:145], s[44:45], 0, v[132:133]
	s_mov_b32 m0, s64
	ds_read_b128 v[196:199], v159 offset:16384
	ds_read_b128 v[200:203], v159 offset:17408
	ds_read_b128 v[204:207], v159 offset:18432
	ds_read_b128 v[208:211], v159 offset:19456
	ds_read_b128 v[216:219], v159 offset:20480
	ds_read_b128 v[220:223], v159 offset:21504
	ds_read_b128 v[224:227], v159 offset:22528
	ds_read_b128 v[228:231], v159 offset:23552
	global_load_lds_dwordx4 v[144:145], off
	s_add_i32 m0, s64, 0x2000
	s_add_u32 s64, s44, 0x40000
	v_lshl_add_u64 v[148:149], s[44:45], 0, v[128:129]
	s_addc_u32 s65, s45, 0
	s_add_i32 s66, s57, s94
	global_load_lds_dwordx4 v[148:149], off
	v_lshl_add_u64 v[152:153], s[64:65], 0, v[132:133]
	s_mov_b32 m0, s66
	v_lshl_add_u64 v[156:157], s[46:47], 0, v[130:131]
	global_load_lds_dwordx4 v[152:153], off
	v_lshl_add_u64 v[152:153], s[64:65], 0, v[128:129]
	s_add_i32 m0, s66, 0x2000
	s_nop 0
	global_load_lds_dwordx4 v[152:153], off
	v_lshl_add_u64 v[152:153], s[46:47], 0, v[134:135]
	s_mov_b32 m0, s27
	s_nop 0
	global_load_lds_dwordx4 v[152:153], off
	s_mov_b32 m0, s41
	s_nop 0
	global_load_lds_dwordx4 v[156:157], off
	s_waitcnt vmcnt(8)
	s_waitcnt lgkmcnt(0)
	s_barrier
; #define PG8_STAGE(bufoff, gbase, voff) do { _Pragma("unroll") for (int _i = 0; _i < 2; ++_i) \
;         __builtin_amdgcn_global_load_lds((const unsigned*)((const char*)(gbase) + (voff)[_i]), (LAS unsigned*)(lds + (bufoff) + ldsw + _i * 8192), 16, 0, 0); } while (0)
; #define PG8_LDA(dst, b, h) do { _Pragma("unroll") for (int m = 0; m < 4; ++m) _Pragma("unroll") for (int k = 0; k < 2; ++k) dst[m][k] = *(const LAS bf16x8*)(lds + PG8_SA(b, h) + aoff + m * 2048 + k * 1024); } while (0)
; #define PG8_LDB(dst, b, h) do { _Pragma("unroll") for (int n = 0; n < 2; ++n) _Pragma("unroll") for (int k = 0; k < 2; ++k) dst[n][k] = *(const LAS bf16x8*)(lds + PG8_SB(b, h) + boff + n * 2048 + k * 1024); } while (0)
; #define PG8_MMA(ai, bj, At, Bt) do { __builtin_amdgcn_s_setprio(1); _Pragma("unroll") for (int m = 0; m < 4; ++m) _Pragma("unroll") for (int n = 0; n < 2; ++n) _Pragma("unroll") for (int k = 0; k < 2; ++k) \
;         acc[ai][bj][m][n] = __builtin_amdgcn_mfma_f32_16x16x32_bf16(Bt[n][k], At[m][k], acc[ai][bj][m][n], 0, 0, 0); __builtin_amdgcn_s_setprio(0); } while (0)
; #define PG8_WAIT_V(n) asm volatile("s_waitcnt vmcnt(" #n ")" ::: "memory")
; #define PG8_WAIT_L(n) asm volatile("s_waitcnt lgkmcnt(" #n ")" ::: "memory")
; #define PG8_BAR __builtin_amdgcn_s_barrier()
; #define PG8_SCHED __builtin_amdgcn_sched_barrier(0)
; template <class Epi>
; DI void gemm_phase(LAS unsigned char* lds, const int wid, const Gemm g, const Order& S, const Epi& E) {
;     ...
;             PG8_WAIT_V(8); PG8_WAIT_L(0); PG8_BAR; PG8_MMA(1, 0, At, B0); PG8_MMA(1, 1, At, B1); PG8_BAR; PG8_SCHED;
;             PG8_LDB(B0, 1, 0); PG8_LDB(B1, 1, 1); PG8_SCHED; PG8_LDA(At, 1, 0); PG8_STAGE(PG8_SA(0, 1), a2 + hstepA, voffA);
;             PG8_WAIT_V(8); PG8_WAIT_L(0); PG8_BAR; PG8_MMA(0, 0, At, B0); PG8_MMA(0, 1, At, B1); PG8_BAR; PG8_SCHED;
	s_setprio 1
	s_waitcnt lgkmcnt(0)
	v_mfma_f32_16x16x32_bf16 v[60:63], v[164:167], v[196:199], 0
	v_mfma_f32_16x16x32_bf16 v[56:59], v[172:175], v[196:199], 0
	v_mfma_f32_16x16x32_bf16 v[44:47], v[164:167], v[204:207], 0
	v_mfma_f32_16x16x32_bf16 v[40:43], v[172:175], v[204:207], 0
	v_mfma_f32_16x16x32_bf16 v[28:31], v[164:167], v[216:219], 0
	v_mfma_f32_16x16x32_bf16 v[24:27], v[172:175], v[216:219], 0
	v_mfma_f32_16x16x32_bf16 v[12:15], v[164:167], v[224:227], 0
	v_mfma_f32_16x16x32_bf16 v[8:11], v[172:175], v[224:227], 0
	v_mfma_f32_16x16x32_bf16 v[60:63], v[168:171], v[200:203], v[60:63]
	v_mfma_f32_16x16x32_bf16 v[56:59], v[176:179], v[200:203], v[56:59]
	v_mfma_f32_16x16x32_bf16 v[44:47], v[168:171], v[208:211], v[44:47]
	v_mfma_f32_16x16x32_bf16 v[40:43], v[176:179], v[208:211], v[40:43]
	v_mfma_f32_16x16x32_bf16 v[28:31], v[168:171], v[220:223], v[28:31]
	v_mfma_f32_16x16x32_bf16 v[24:27], v[176:179], v[220:223], v[24:27]
	v_mfma_f32_16x16x32_bf16 v[12:15], v[168:171], v[228:231], v[12:15]
	v_mfma_f32_16x16x32_bf16 v[8:11], v[176:179], v[228:231], v[8:11]
	s_setprio 0
	s_setprio 1
	v_mfma_f32_16x16x32_bf16 v[52:55], v[180:183], v[196:199], 0
	v_mfma_f32_16x16x32_bf16 v[48:51], v[188:191], v[196:199], 0
	v_mfma_f32_16x16x32_bf16 v[36:39], v[180:183], v[204:207], 0
	v_mfma_f32_16x16x32_bf16 v[32:35], v[188:191], v[204:207], 0
	v_mfma_f32_16x16x32_bf16 v[20:23], v[180:183], v[216:219], 0
	v_mfma_f32_16x16x32_bf16 v[16:19], v[188:191], v[216:219], 0
	v_mfma_f32_16x16x32_bf16 v[4:7], v[180:183], v[224:227], 0
	v_mfma_f32_16x16x32_bf16 v[0:3], v[188:191], v[224:227], 0
	v_mfma_f32_16x16x32_bf16 v[52:55], v[184:187], v[200:203], v[52:55]
	v_mfma_f32_16x16x32_bf16 v[48:51], v[192:195], v[200:203], v[48:51]
	v_mfma_f32_16x16x32_bf16 v[36:39], v[184:187], v[208:211], v[36:39]
	v_mfma_f32_16x16x32_bf16 v[32:35], v[192:195], v[208:211], v[32:35]
	v_mfma_f32_16x16x32_bf16 v[20:23], v[184:187], v[220:223], v[20:23]
	v_mfma_f32_16x16x32_bf16 v[16:19], v[192:195], v[220:223], v[16:19]
	v_mfma_f32_16x16x32_bf16 v[4:7], v[184:187], v[228:231], v[4:7]
	v_mfma_f32_16x16x32_bf16 v[0:3], v[192:195], v[228:231], v[0:3]
	s_setprio 0
	s_barrier
	s_add_i32 s64, 0, 0x18000
	v_add_u32_e32 v146, s64, v147
	s_add_i32 s65, 0, 0x1c000
	ds_read_b128 v[164:167], v146
	ds_read_b128 v[168:171], v146 offset:1024
	ds_read_b128 v[172:175], v146 offset:2048
	ds_read_b128 v[176:179], v146 offset:3072
	v_add_u32_e32 v146, s65, v147
	ds_read_b128 v[180:183], v146
	ds_read_b128 v[184:187], v146 offset:1024
	ds_read_b128 v[188:191], v146 offset:2048
	ds_read_b128 v[192:195], v146 offset:3072
	s_add_u32 s46, s46, 0x40000
	s_addc_u32 s47, s47, 0
	s_mov_b32 m0, s48
	v_lshl_add_u64 v[160:161], s[46:47], 0, v[134:135]
	ds_read_b128 v[196:199], v159 offset:32768
	ds_read_b128 v[200:203], v159 offset:33792
	ds_read_b128 v[204:207], v159 offset:34816
	ds_read_b128 v[208:211], v159 offset:35840
	ds_read_b128 v[216:219], v159 offset:36864
	ds_read_b128 v[220:223], v159 offset:37888
	ds_read_b128 v[224:227], v159 offset:38912
	ds_read_b128 v[228:231], v159 offset:39936
	global_load_lds_dwordx4 v[160:161], off
	v_lshl_add_u64 v[160:161], s[46:47], 0, v[130:131]
	s_mov_b32 m0, s49
	s_nop 0
	global_load_lds_dwordx4 v[160:161], off
	s_waitcnt vmcnt(8)
	s_waitcnt lgkmcnt(0)
	s_barrier
	s_setprio 1
	s_waitcnt lgkmcnt(0)
	v_mfma_f32_16x16x32_bf16 v[124:127], v[164:167], v[196:199], v[124:127]
	v_mfma_f32_16x16x32_bf16 v[120:123], v[172:175], v[196:199], v[120:123]
	v_mfma_f32_16x16x32_bf16 v[108:111], v[164:167], v[204:207], v[108:111]
	v_mfma_f32_16x16x32_bf16 v[104:107], v[172:175], v[204:207], v[104:107]
	v_mfma_f32_16x16x32_bf16 v[92:95], v[164:167], v[216:219], v[92:95]
	v_mfma_f32_16x16x32_bf16 v[88:91], v[172:175], v[216:219], v[88:91]
	v_mfma_f32_16x16x32_bf16 v[76:79], v[164:167], v[224:227], v[76:79]
	v_mfma_f32_16x16x32_bf16 v[72:75], v[172:175], v[224:227], v[72:75]
	v_mfma_f32_16x16x32_bf16 v[124:127], v[168:171], v[200:203], v[124:127]
	v_mfma_f32_16x16x32_bf16 v[120:123], v[176:179], v[200:203], v[120:123]
	v_mfma_f32_16x16x32_bf16 v[108:111], v[168:171], v[208:211], v[108:111]
	v_mfma_f32_16x16x32_bf16 v[104:107], v[176:179], v[208:211], v[104:107]
	v_mfma_f32_16x16x32_bf16 v[92:95], v[168:171], v[220:223], v[92:95]
	v_mfma_f32_16x16x32_bf16 v[88:91], v[176:179], v[220:223], v[88:91]
	v_mfma_f32_16x16x32_bf16 v[76:79], v[168:171], v[228:231], v[76:79]
	v_mfma_f32_16x16x32_bf16 v[72:75], v[176:179], v[228:231], v[72:75]
	s_setprio 0
	s_setprio 1
	v_mfma_f32_16x16x32_bf16 v[116:119], v[180:183], v[196:199], v[116:119]
	v_mfma_f32_16x16x32_bf16 v[112:115], v[188:191], v[196:199], v[112:115]
	v_mfma_f32_16x16x32_bf16 v[100:103], v[180:183], v[204:207], v[100:103]
	v_mfma_f32_16x16x32_bf16 v[96:99], v[188:191], v[204:207], v[96:99]
	v_mfma_f32_16x16x32_bf16 v[84:87], v[180:183], v[216:219], v[84:87]
	v_mfma_f32_16x16x32_bf16 v[80:83], v[188:191], v[216:219], v[80:83]
	v_mfma_f32_16x16x32_bf16 v[68:71], v[180:183], v[224:227], v[68:71]
	v_mfma_f32_16x16x32_bf16 v[64:67], v[188:191], v[224:227], v[64:67]
	v_mfma_f32_16x16x32_bf16 v[116:119], v[184:187], v[200:203], v[116:119]
	v_mfma_f32_16x16x32_bf16 v[112:115], v[192:195], v[200:203], v[112:115]
	v_mfma_f32_16x16x32_bf16 v[100:103], v[184:187], v[208:211], v[100:103]
	v_mfma_f32_16x16x32_bf16 v[96:99], v[192:195], v[208:211], v[96:99]
	v_mfma_f32_16x16x32_bf16 v[84:87], v[184:187], v[220:223], v[84:87]
	v_mfma_f32_16x16x32_bf16 v[80:83], v[192:195], v[220:223], v[80:83]
	v_mfma_f32_16x16x32_bf16 v[68:71], v[184:187], v[228:231], v[68:71]
	v_mfma_f32_16x16x32_bf16 v[64:67], v[192:195], v[228:231], v[64:67]
	s_setprio 0
	s_barrier
; #define PG8_STAGE(bufoff, gbase, voff) do { _Pragma("unroll") for (int _i = 0; _i < 2; ++_i) \
;         __builtin_amdgcn_global_load_lds((const unsigned*)((const char*)(gbase) + (voff)[_i]), (LAS unsigned*)(lds + (bufoff) + ldsw + _i * 8192), 16, 0, 0); } while (0)
; #define PG8_LDA(dst, b, h) do { _Pragma("unroll") for (int m = 0; m < 4; ++m) _Pragma("unroll") for (int k = 0; k < 2; ++k) dst[m][k] = *(const LAS bf16x8*)(lds + PG8_SA(b, h) + aoff + m * 2048 + k * 1024); } while (0)
; #define PG8_MMA(ai, bj, At, Bt) do { __builtin_amdgcn_s_setprio(1); _Pragma("unroll") for (int m = 0; m < 4; ++m) _Pragma("unroll") for (int n = 0; n < 2; ++n) _Pragma("unroll") for (int k = 0; k < 2; ++k) \
;         acc[ai][bj][m][n] = __builtin_amdgcn_mfma_f32_16x16x32_bf16(Bt[n][k], At[m][k], acc[ai][bj][m][n], 0, 0, 0); __builtin_amdgcn_s_setprio(0); } while (0)
; #define PG8_WAIT_V(n) asm volatile("s_waitcnt vmcnt(" #n ")" ::: "memory")
; #define PG8_WAIT_L(n) asm volatile("s_waitcnt lgkmcnt(" #n ")" ::: "memory")
; #define PG8_BAR __builtin_amdgcn_s_barrier()
; #define PG8_SCHED __builtin_amdgcn_sched_barrier(0)
; template <class Epi>
; DI void gemm_phase(LAS unsigned char* lds, const int wid, const Gemm g, const Order& S, const Epi& E) {
;     ...
;         for (int t = 0; t < nt; t += 2) {
;     ...
;             PG8_LDA(At, 1, 1); PG8_STAGE(PG8_SB(1, 0), b3, voffB); PG8_STAGE(PG8_SB(1, 1), b3 + hstepB, voffB); PG8_STAGE(PG8_SA(1, 0), a3, voffA);
;             PG8_WAIT_V(8); PG8_WAIT_L(0); PG8_BAR; PG8_MMA(1, 0, At, B0); PG8_MMA(1, 1, At, B1); PG8_BAR; PG8_SCHED;
	s_add_i32 s46, s64, s94
	v_lshl_add_u64 v[144:145], v[144:145], 0, s[16:17]
	s_mov_b32 m0, s46
	ds_read_b128 v[196:199], v159 offset:49152
	ds_read_b128 v[200:203], v159 offset:50176
	ds_read_b128 v[204:207], v159 offset:51200
	ds_read_b128 v[208:211], v159 offset:52224
	ds_read_b128 v[216:219], v159 offset:53248
	ds_read_b128 v[220:223], v159 offset:54272
	ds_read_b128 v[224:227], v159 offset:55296
	ds_read_b128 v[228:231], v159 offset:56320
	global_load_lds_dwordx4 v[144:145], off
	s_add_i32 m0, s46, 0x2000
	s_add_u32 s44, s44, 0x40080
	v_lshl_add_u64 v[144:145], v[148:149], 0, s[16:17]
	s_addc_u32 s45, s45, 0
	s_add_i32 s46, s65, s94
	global_load_lds_dwordx4 v[144:145], off
	v_lshl_add_u64 v[144:145], s[44:45], 0, v[132:133]
	s_mov_b32 m0, s46
	s_nop 0
	global_load_lds_dwordx4 v[144:145], off
	v_lshl_add_u64 v[144:145], s[44:45], 0, v[128:129]
	s_add_i32 m0, s46, 0x2000
	s_nop 0
	global_load_lds_dwordx4 v[144:145], off
	v_lshl_add_u64 v[144:145], v[152:153], 0, s[16:17]
	s_mov_b32 m0, s51
	s_nop 0
	global_load_lds_dwordx4 v[144:145], off
	v_lshl_add_u64 v[144:145], v[156:157], 0, s[16:17]
	s_mov_b32 m0, s52
	s_nop 0
	global_load_lds_dwordx4 v[144:145], off
	s_waitcnt vmcnt(8)
	s_waitcnt lgkmcnt(0)
	s_barrier
	s_setprio 1
	s_waitcnt lgkmcnt(0)
	v_mfma_f32_16x16x32_bf16 v[60:63], v[164:167], v[196:199], v[60:63]
	v_mfma_f32_16x16x32_bf16 v[56:59], v[172:175], v[196:199], v[56:59]
	v_mfma_f32_16x16x32_bf16 v[44:47], v[164:167], v[204:207], v[44:47]
	v_mfma_f32_16x16x32_bf16 v[40:43], v[172:175], v[204:207], v[40:43]
	v_mfma_f32_16x16x32_bf16 v[28:31], v[164:167], v[216:219], v[28:31]
	v_mfma_f32_16x16x32_bf16 v[24:27], v[172:175], v[216:219], v[24:27]
	v_mfma_f32_16x16x32_bf16 v[12:15], v[164:167], v[224:227], v[12:15]
	v_mfma_f32_16x16x32_bf16 v[8:11], v[172:175], v[224:227], v[8:11]
	v_mfma_f32_16x16x32_bf16 v[60:63], v[168:171], v[200:203], v[60:63]
	v_mfma_f32_16x16x32_bf16 v[56:59], v[176:179], v[200:203], v[56:59]
	v_mfma_f32_16x16x32_bf16 v[44:47], v[168:171], v[208:211], v[44:47]
	v_mfma_f32_16x16x32_bf16 v[40:43], v[176:179], v[208:211], v[40:43]
	v_mfma_f32_16x16x32_bf16 v[28:31], v[168:171], v[220:223], v[28:31]
	v_mfma_f32_16x16x32_bf16 v[24:27], v[176:179], v[220:223], v[24:27]
	v_mfma_f32_16x16x32_bf16 v[12:15], v[168:171], v[228:231], v[12:15]
	v_mfma_f32_16x16x32_bf16 v[8:11], v[176:179], v[228:231], v[8:11]
	s_setprio 0
	s_setprio 1
	v_mfma_f32_16x16x32_bf16 v[52:55], v[180:183], v[196:199], v[52:55]
	v_mfma_f32_16x16x32_bf16 v[48:51], v[188:191], v[196:199], v[48:51]
	v_mfma_f32_16x16x32_bf16 v[36:39], v[180:183], v[204:207], v[36:39]
	v_mfma_f32_16x16x32_bf16 v[32:35], v[188:191], v[204:207], v[32:35]
	v_mfma_f32_16x16x32_bf16 v[20:23], v[180:183], v[216:219], v[20:23]
	v_mfma_f32_16x16x32_bf16 v[16:19], v[188:191], v[216:219], v[16:19]
	v_mfma_f32_16x16x32_bf16 v[4:7], v[180:183], v[224:227], v[4:7]
	v_mfma_f32_16x16x32_bf16 v[0:3], v[188:191], v[224:227], v[0:3]
	v_mfma_f32_16x16x32_bf16 v[52:55], v[184:187], v[200:203], v[52:55]
	v_mfma_f32_16x16x32_bf16 v[48:51], v[192:195], v[200:203], v[48:51]
	v_mfma_f32_16x16x32_bf16 v[36:39], v[184:187], v[208:211], v[36:39]
	v_mfma_f32_16x16x32_bf16 v[32:35], v[192:195], v[208:211], v[32:35]
	v_mfma_f32_16x16x32_bf16 v[20:23], v[184:187], v[220:223], v[20:23]
	v_mfma_f32_16x16x32_bf16 v[16:19], v[192:195], v[220:223], v[16:19]
	v_mfma_f32_16x16x32_bf16 v[4:7], v[184:187], v[228:231], v[4:7]
	v_mfma_f32_16x16x32_bf16 v[0:3], v[192:195], v[228:231], v[0:3]
	s_setprio 0
	s_barrier
	s_add_i32 s63, s63, 2
	s_add_u32 s42, s42, 0x100
	s_addc_u32 s43, s43, 0
	s_add_u32 s61, s61, 0x100
	s_addc_u32 s62, s62, 0
	s_cmp_gt_u32 s63, 13
	s_cbranch_scc0 .LBB0_228
	s_branch .Lpeel_exit_0

; #define PG8_BAR __builtin_amdgcn_s_barrier()
; template <class Epi>
; DI void gemm_phase(LAS unsigned char* lds, const int wid, const Gemm g, const Order& S, const Epi& E) {
;     ...
;         if (wr == 0) PG8_BAR;
.Lpeel_exit_0:
	s_and_b64 vcc, exec, s[28:29]
	s_cbranch_vccz .LBB0_231
	s_barrier

; #define PG8_STAGE(bufoff, gbase, voff) do { _Pragma("unroll") for (int _i = 0; _i < 2; ++_i) \
;         __builtin_amdgcn_global_load_lds((const unsigned*)((const char*)(gbase) + (voff)[_i]), (LAS unsigned*)(lds + (bufoff) + ldsw + _i * 8192), 16, 0, 0); } while (0)
; #define PG8_LDA(dst, b, h) do { _Pragma("unroll") for (int m = 0; m < 4; ++m) _Pragma("unroll") for (int k = 0; k < 2; ++k) dst[m][k] = *(const LAS bf16x8*)(lds + PG8_SA(b, h) + aoff + m * 2048 + k * 1024); } while (0)
; #define PG8_LDB(dst, b, h) do { _Pragma("unroll") for (int n = 0; n < 2; ++n) _Pragma("unroll") for (int k = 0; k < 2; ++k) dst[n][k] = *(const LAS bf16x8*)(lds + PG8_SB(b, h) + boff + n * 2048 + k * 1024); } while (0)
; #define PG8_MMA(ai, bj, At, Bt) do { __builtin_amdgcn_s_setprio(1); _Pragma("unroll") for (int m = 0; m < 4; ++m) _Pragma("unroll") for (int n = 0; n < 2; ++n) _Pragma("unroll") for (int k = 0; k < 2; ++k) \
;         acc[ai][bj][m][n] = __builtin_amdgcn_mfma_f32_16x16x32_bf16(Bt[n][k], At[m][k], acc[ai][bj][m][n], 0, 0, 0); __builtin_amdgcn_s_setprio(0); } while (0)
; #define PG8_WAIT_V(n) asm volatile("s_waitcnt vmcnt(" #n ")" ::: "memory")
; #define PG8_WAIT_L(n) asm volatile("s_waitcnt lgkmcnt(" #n ")" ::: "memory")
; #define PG8_BAR __builtin_amdgcn_s_barrier()
; template <class Epi>
; DI void gemm_phase(LAS unsigned char* lds, const int wid, const Gemm g, const Order& S, const Epi& E) {
;     ...
;             const bool last = (t == nt - 2);
;             const char* a1 = cA + (size_t)(t + 1) * kstep;
;             const char* a2 = last ? nA : cA + (size_t)(t + 2) * kstep; const char* b2 = last ? nB : cB + (size_t)(t + 2) * kstep;
;             const char* a3 = a2 + kstep; const char* b3 = b2 + kstep;
;             PG8_LDB(B0, 0, 0); PG8_LDB(B1, 0, 1); PG8_SCHED; PG8_LDA(At, 0, 0); PG8_STAGE(PG8_SA(1, 1), a1 + hstepA, voffA);
;             PG8_WAIT_V(8); PG8_WAIT_L(0); PG8_BAR; PG8_MMA(0, 0, At, B0); PG8_MMA(0, 1, At, B1); PG8_BAR; PG8_SCHED;
;             PG8_LDA(At, 0, 1); PG8_STAGE(PG8_SB(0, 0), b2, voffB); PG8_STAGE(PG8_SB(0, 1), b2 + hstepB, voffB); PG8_STAGE(PG8_SA(0, 0), a2, voffA);
;     ...
;         for (int a = 0; a < 2; ++a)
; #pragma unroll
;             for (int b = 0; b < 2; ++b)
; #pragma unroll
;                 for (int m = 0; m < 4; ++m)
; #pragma unroll
;                     for (int n = 0; n < 2; ++n) acc[a][b][m][n] = (f32x4){0.f, 0.f, 0.f, 0.f};
.LBB0_311:
	s_add_u32 s61, s44, 0x100
	v_mov_b32_e32 v0, 0
	s_addc_u32 s62, s45, 0
	s_mov_b32 s63, -2
	s_waitcnt lgkmcnt(0)
	ds_read_b128 v[128:131], v209
	ds_read_b128 v[132:135], v209 offset:1024
	ds_read_b128 v[136:139], v209 offset:2048
	ds_read_b128 v[140:143], v209 offset:3072
	ds_read_b128 v[144:147], v210
	ds_read_b128 v[148:151], v210 offset:1024
	ds_read_b128 v[152:155], v210 offset:2048
	ds_read_b128 v[156:159], v210 offset:3072
	s_add_u32 s10, s42, 0x100
	s_addc_u32 s11, s43, 0
	s_cmp_eq_u32 s63, 40
	s_cselect_b32 s47, s39, s11
	s_cselect_b32 s46, s38, s10
	s_cselect_b32 s45, s41, s62
	s_cselect_b32 s44, s40, s61
	v_lshl_add_u64 v[214:215], s[42:43], 0, v[184:185]
	s_add_i32 m0, s26, 0xc000
	ds_read_b128 v[160:163], v211
	ds_read_b128 v[164:167], v211 offset:1024
	ds_read_b128 v[168:171], v211 offset:2048
	ds_read_b128 v[172:175], v211 offset:3072
	ds_read_b128 v[192:195], v211 offset:4096
	ds_read_b128 v[196:199], v211 offset:5120
	ds_read_b128 v[200:203], v211 offset:6144
	ds_read_b128 v[204:207], v211 offset:7168
	global_load_lds_dwordx4 v[214:215], off
	v_lshl_add_u64 v[214:215], s[42:43], 0, v[186:187]
	s_add_i32 m0, s26, 0xe000
	s_nop 0
	global_load_lds_dwordx4 v[214:215], off
	s_waitcnt vmcnt(8)
	s_waitcnt lgkmcnt(0)
	s_barrier
	s_setprio 1
	s_waitcnt lgkmcnt(0)
	v_mfma_f32_16x16x32_bf16 v[124:127], v[128:131], v[160:163], 0
	v_mfma_f32_16x16x32_bf16 v[120:123], v[136:139], v[160:163], 0
	v_mfma_f32_16x16x32_bf16 v[108:111], v[128:131], v[168:171], 0
	v_mfma_f32_16x16x32_bf16 v[104:107], v[136:139], v[168:171], 0
	v_mfma_f32_16x16x32_bf16 v[92:95], v[128:131], v[192:195], 0
	v_mfma_f32_16x16x32_bf16 v[88:91], v[136:139], v[192:195], 0
	v_mfma_f32_16x16x32_bf16 v[76:79], v[128:131], v[200:203], 0
	v_mfma_f32_16x16x32_bf16 v[72:75], v[136:139], v[200:203], 0
	v_mfma_f32_16x16x32_bf16 v[124:127], v[132:135], v[164:167], v[124:127]
	v_mfma_f32_16x16x32_bf16 v[120:123], v[140:143], v[164:167], v[120:123]
	v_mfma_f32_16x16x32_bf16 v[108:111], v[132:135], v[172:175], v[108:111]
	v_mfma_f32_16x16x32_bf16 v[104:107], v[140:143], v[172:175], v[104:107]
	v_mfma_f32_16x16x32_bf16 v[92:95], v[132:135], v[196:199], v[92:95]
	v_mfma_f32_16x16x32_bf16 v[88:91], v[140:143], v[196:199], v[88:91]
	v_mfma_f32_16x16x32_bf16 v[76:79], v[132:135], v[204:207], v[76:79]
	v_mfma_f32_16x16x32_bf16 v[72:75], v[140:143], v[204:207], v[72:75]
	s_setprio 0
	s_setprio 1
	v_mfma_f32_16x16x32_bf16 v[116:119], v[144:147], v[160:163], 0
	v_mfma_f32_16x16x32_bf16 v[112:115], v[152:155], v[160:163], 0
	v_mfma_f32_16x16x32_bf16 v[100:103], v[144:147], v[168:171], 0
	v_mfma_f32_16x16x32_bf16 v[96:99], v[152:155], v[168:171], 0
	v_mfma_f32_16x16x32_bf16 v[84:87], v[144:147], v[192:195], 0
	v_mfma_f32_16x16x32_bf16 v[80:83], v[152:155], v[192:195], 0
	v_mfma_f32_16x16x32_bf16 v[68:71], v[144:147], v[200:203], 0
	v_mfma_f32_16x16x32_bf16 v[64:67], v[152:155], v[200:203], 0
	v_mfma_f32_16x16x32_bf16 v[116:119], v[148:151], v[164:167], v[116:119]
	v_mfma_f32_16x16x32_bf16 v[112:115], v[156:159], v[164:167], v[112:115]
	v_mfma_f32_16x16x32_bf16 v[100:103], v[148:151], v[172:175], v[100:103]
	v_mfma_f32_16x16x32_bf16 v[96:99], v[156:159], v[172:175], v[96:99]
	v_mfma_f32_16x16x32_bf16 v[84:87], v[148:151], v[196:199], v[84:87]
	v_mfma_f32_16x16x32_bf16 v[80:83], v[156:159], v[196:199], v[80:83]
	v_mfma_f32_16x16x32_bf16 v[68:71], v[148:151], v[204:207], v[68:71]
	v_mfma_f32_16x16x32_bf16 v[64:67], v[156:159], v[204:207], v[64:67]
	s_setprio 0
	s_barrier
	s_add_i32 s42, s55, s94
	v_lshl_add_u64 v[214:215], s[44:45], 0, v[178:179]
	s_mov_b32 m0, s42
	ds_read_b128 v[160:163], v211 offset:16384
	ds_read_b128 v[164:167], v211 offset:17408
	ds_read_b128 v[168:171], v211 offset:18432
	ds_read_b128 v[172:175], v211 offset:19456
	ds_read_b128 v[192:195], v211 offset:20480
	ds_read_b128 v[196:199], v211 offset:21504
	ds_read_b128 v[200:203], v211 offset:22528
	ds_read_b128 v[204:207], v211 offset:23552
	global_load_lds_dwordx4 v[214:215], off
	s_add_i32 m0, s42, 0x2000
	s_add_u32 s42, s44, 0xb0000
	v_lshl_add_u64 v[216:217], s[44:45], 0, v[182:183]
	s_addc_u32 s43, s45, 0
	s_add_i32 s64, s56, s94
	global_load_lds_dwordx4 v[216:217], off
	v_lshl_add_u64 v[218:219], s[42:43], 0, v[178:179]
	s_mov_b32 m0, s64
	v_lshl_add_u64 v[220:221], s[46:47], 0, v[180:181]
	global_load_lds_dwordx4 v[218:219], off
	v_lshl_add_u64 v[218:219], s[42:43], 0, v[182:183]
	s_add_i32 m0, s64, 0x2000
	s_nop 0
	global_load_lds_dwordx4 v[218:219], off
	v_lshl_add_u64 v[218:219], s[46:47], 0, v[176:177]
	s_mov_b32 m0, s26
	s_nop 0
	global_load_lds_dwordx4 v[218:219], off
	s_mov_b32 m0, s27
	s_nop 0
	global_load_lds_dwordx4 v[220:221], off
	s_waitcnt vmcnt(8)
	s_waitcnt lgkmcnt(0)
	s_barrier
; #define PG8_STAGE(bufoff, gbase, voff) do { _Pragma("unroll") for (int _i = 0; _i < 2; ++_i) \
;         __builtin_amdgcn_global_load_lds((const unsigned*)((const char*)(gbase) + (voff)[_i]), (LAS unsigned*)(lds + (bufoff) + ldsw + _i * 8192), 16, 0, 0); } while (0)
; #define PG8_LDA(dst, b, h) do { _Pragma("unroll") for (int m = 0; m < 4; ++m) _Pragma("unroll") for (int k = 0; k < 2; ++k) dst[m][k] = *(const LAS bf16x8*)(lds + PG8_SA(b, h) + aoff + m * 2048 + k * 1024); } while (0)
; #define PG8_LDB(dst, b, h) do { _Pragma("unroll") for (int n = 0; n < 2; ++n) _Pragma("unroll") for (int k = 0; k < 2; ++k) dst[n][k] = *(const LAS bf16x8*)(lds + PG8_SB(b, h) + boff + n * 2048 + k * 1024); } while (0)
; #define PG8_MMA(ai, bj, At, Bt) do { __builtin_amdgcn_s_setprio(1); _Pragma("unroll") for (int m = 0; m < 4; ++m) _Pragma("unroll") for (int n = 0; n < 2; ++n) _Pragma("unroll") for (int k = 0; k < 2; ++k) \
;         acc[ai][bj][m][n] = __builtin_amdgcn_mfma_f32_16x16x32_bf16(Bt[n][k], At[m][k], acc[ai][bj][m][n], 0, 0, 0); __builtin_amdgcn_s_setprio(0); } while (0)
; #define PG8_WAIT_V(n) asm volatile("s_waitcnt vmcnt(" #n ")" ::: "memory")
; #define PG8_WAIT_L(n) asm volatile("s_waitcnt lgkmcnt(" #n ")" ::: "memory")
; #define PG8_BAR __builtin_amdgcn_s_barrier()
; #define PG8_SCHED __builtin_amdgcn_sched_barrier(0)
; template <class Epi>
; DI void gemm_phase(LAS unsigned char* lds, const int wid, const Gemm g, const Order& S, const Epi& E) {
;     ...
;             PG8_WAIT_V(8); PG8_WAIT_L(0); PG8_BAR; PG8_MMA(1, 0, At, B0); PG8_MMA(1, 1, At, B1); PG8_BAR; PG8_SCHED;
;             PG8_LDB(B0, 1, 0); PG8_LDB(B1, 1, 1); PG8_SCHED; PG8_LDA(At, 1, 0); PG8_STAGE(PG8_SA(0, 1), a2 + hstepA, voffA);
;             PG8_WAIT_V(8); PG8_WAIT_L(0); PG8_BAR; PG8_MMA(0, 0, At, B0); PG8_MMA(0, 1, At, B1); PG8_BAR; PG8_SCHED;
	s_setprio 1
	s_waitcnt lgkmcnt(0)
	v_mfma_f32_16x16x32_bf16 v[60:63], v[128:131], v[160:163], 0
	v_mfma_f32_16x16x32_bf16 v[56:59], v[136:139], v[160:163], 0
	v_mfma_f32_16x16x32_bf16 v[44:47], v[128:131], v[168:171], 0
	v_mfma_f32_16x16x32_bf16 v[40:43], v[136:139], v[168:171], 0
	v_mfma_f32_16x16x32_bf16 v[28:31], v[128:131], v[192:195], 0
	v_mfma_f32_16x16x32_bf16 v[24:27], v[136:139], v[192:195], 0
	v_mfma_f32_16x16x32_bf16 v[12:15], v[128:131], v[200:203], 0
	v_mfma_f32_16x16x32_bf16 v[8:11], v[136:139], v[200:203], 0
	v_mfma_f32_16x16x32_bf16 v[60:63], v[132:135], v[164:167], v[60:63]
	v_mfma_f32_16x16x32_bf16 v[56:59], v[140:143], v[164:167], v[56:59]
	v_mfma_f32_16x16x32_bf16 v[44:47], v[132:135], v[172:175], v[44:47]
	v_mfma_f32_16x16x32_bf16 v[40:43], v[140:143], v[172:175], v[40:43]
	v_mfma_f32_16x16x32_bf16 v[28:31], v[132:135], v[196:199], v[28:31]
	v_mfma_f32_16x16x32_bf16 v[24:27], v[140:143], v[196:199], v[24:27]
	v_mfma_f32_16x16x32_bf16 v[12:15], v[132:135], v[204:207], v[12:15]
	v_mfma_f32_16x16x32_bf16 v[8:11], v[140:143], v[204:207], v[8:11]
	s_setprio 0
	s_setprio 1
	v_mfma_f32_16x16x32_bf16 v[52:55], v[144:147], v[160:163], 0
	v_mfma_f32_16x16x32_bf16 v[48:51], v[152:155], v[160:163], 0
	v_mfma_f32_16x16x32_bf16 v[36:39], v[144:147], v[168:171], 0
	v_mfma_f32_16x16x32_bf16 v[32:35], v[152:155], v[168:171], 0
	v_mfma_f32_16x16x32_bf16 v[20:23], v[144:147], v[192:195], 0
	v_mfma_f32_16x16x32_bf16 v[16:19], v[152:155], v[192:195], 0
	v_mfma_f32_16x16x32_bf16 v[4:7], v[144:147], v[200:203], 0
	v_mfma_f32_16x16x32_bf16 v[0:3], v[152:155], v[200:203], 0
	v_mfma_f32_16x16x32_bf16 v[52:55], v[148:151], v[164:167], v[52:55]
	v_mfma_f32_16x16x32_bf16 v[48:51], v[156:159], v[164:167], v[48:51]
	v_mfma_f32_16x16x32_bf16 v[36:39], v[148:151], v[172:175], v[36:39]
	v_mfma_f32_16x16x32_bf16 v[32:35], v[156:159], v[172:175], v[32:35]
	v_mfma_f32_16x16x32_bf16 v[20:23], v[148:151], v[196:199], v[20:23]
	v_mfma_f32_16x16x32_bf16 v[16:19], v[156:159], v[196:199], v[16:19]
	v_mfma_f32_16x16x32_bf16 v[4:7], v[148:151], v[204:207], v[4:7]
	v_mfma_f32_16x16x32_bf16 v[0:3], v[156:159], v[204:207], v[0:3]
	s_setprio 0
	s_barrier
	s_add_i32 s64, 0, 0x18000
	s_add_i32 s65, 0, 0x1c000
	v_add_u32_e32 v140, s64, v208
	v_add_u32_e32 v156, s65, v208
	ds_read_b128 v[128:131], v140
	ds_read_b128 v[132:135], v140 offset:1024
	ds_read_b128 v[136:139], v140 offset:2048
	ds_read_b128 v[140:143], v140 offset:3072
	ds_read_b128 v[144:147], v156
	ds_read_b128 v[148:151], v156 offset:1024
	ds_read_b128 v[152:155], v156 offset:2048
	ds_read_b128 v[156:159], v156 offset:3072
	s_add_u32 s42, s46, 0xb0000
	s_addc_u32 s43, s47, 0
	s_mov_b32 m0, s48
	v_lshl_add_u64 v[222:223], s[42:43], 0, v[176:177]
	ds_read_b128 v[160:163], v211 offset:32768
	ds_read_b128 v[164:167], v211 offset:33792
	ds_read_b128 v[168:171], v211 offset:34816
	ds_read_b128 v[172:175], v211 offset:35840
	ds_read_b128 v[192:195], v211 offset:36864
	ds_read_b128 v[196:199], v211 offset:37888
	ds_read_b128 v[200:203], v211 offset:38912
	ds_read_b128 v[204:207], v211 offset:39936
	global_load_lds_dwordx4 v[222:223], off
	v_lshl_add_u64 v[222:223], s[42:43], 0, v[180:181]
	s_mov_b32 m0, s49
	s_nop 0
	global_load_lds_dwordx4 v[222:223], off
	s_waitcnt vmcnt(8)
	s_waitcnt lgkmcnt(0)
	s_barrier
	s_setprio 1
	s_waitcnt lgkmcnt(0)
	v_mfma_f32_16x16x32_bf16 v[124:127], v[128:131], v[160:163], v[124:127]
	v_mfma_f32_16x16x32_bf16 v[120:123], v[136:139], v[160:163], v[120:123]
	v_mfma_f32_16x16x32_bf16 v[108:111], v[128:131], v[168:171], v[108:111]
	v_mfma_f32_16x16x32_bf16 v[104:107], v[136:139], v[168:171], v[104:107]
	v_mfma_f32_16x16x32_bf16 v[92:95], v[128:131], v[192:195], v[92:95]
	v_mfma_f32_16x16x32_bf16 v[88:91], v[136:139], v[192:195], v[88:91]
	v_mfma_f32_16x16x32_bf16 v[76:79], v[128:131], v[200:203], v[76:79]
	v_mfma_f32_16x16x32_bf16 v[72:75], v[136:139], v[200:203], v[72:75]
	v_mfma_f32_16x16x32_bf16 v[124:127], v[132:135], v[164:167], v[124:127]
	v_mfma_f32_16x16x32_bf16 v[120:123], v[140:143], v[164:167], v[120:123]
	v_mfma_f32_16x16x32_bf16 v[108:111], v[132:135], v[172:175], v[108:111]
	v_mfma_f32_16x16x32_bf16 v[104:107], v[140:143], v[172:175], v[104:107]
	v_mfma_f32_16x16x32_bf16 v[92:95], v[132:135], v[196:199], v[92:95]
	v_mfma_f32_16x16x32_bf16 v[88:91], v[140:143], v[196:199], v[88:91]
	v_mfma_f32_16x16x32_bf16 v[76:79], v[132:135], v[204:207], v[76:79]
	v_mfma_f32_16x16x32_bf16 v[72:75], v[140:143], v[204:207], v[72:75]
	s_setprio 0
	s_setprio 1
	v_mfma_f32_16x16x32_bf16 v[116:119], v[144:147], v[160:163], v[116:119]
	v_mfma_f32_16x16x32_bf16 v[112:115], v[152:155], v[160:163], v[112:115]
	v_mfma_f32_16x16x32_bf16 v[100:103], v[144:147], v[168:171], v[100:103]
	v_mfma_f32_16x16x32_bf16 v[96:99], v[152:155], v[168:171], v[96:99]
	v_mfma_f32_16x16x32_bf16 v[84:87], v[144:147], v[192:195], v[84:87]
	v_mfma_f32_16x16x32_bf16 v[80:83], v[152:155], v[192:195], v[80:83]
	v_mfma_f32_16x16x32_bf16 v[68:71], v[144:147], v[200:203], v[68:71]
	v_mfma_f32_16x16x32_bf16 v[64:67], v[152:155], v[200:203], v[64:67]
	v_mfma_f32_16x16x32_bf16 v[116:119], v[148:151], v[164:167], v[116:119]
	v_mfma_f32_16x16x32_bf16 v[112:115], v[156:159], v[164:167], v[112:115]
	v_mfma_f32_16x16x32_bf16 v[100:103], v[148:151], v[172:175], v[100:103]
	v_mfma_f32_16x16x32_bf16 v[96:99], v[156:159], v[172:175], v[96:99]
	v_mfma_f32_16x16x32_bf16 v[84:87], v[148:151], v[196:199], v[84:87]
	v_mfma_f32_16x16x32_bf16 v[80:83], v[156:159], v[196:199], v[80:83]
	v_mfma_f32_16x16x32_bf16 v[68:71], v[148:151], v[204:207], v[68:71]
	v_mfma_f32_16x16x32_bf16 v[64:67], v[156:159], v[204:207], v[64:67]
	s_setprio 0
	s_barrier
; #define PG8_STAGE(bufoff, gbase, voff) do { _Pragma("unroll") for (int _i = 0; _i < 2; ++_i) \
;         __builtin_amdgcn_global_load_lds((const unsigned*)((const char*)(gbase) + (voff)[_i]), (LAS unsigned*)(lds + (bufoff) + ldsw + _i * 8192), 16, 0, 0); } while (0)
; #define PG8_LDA(dst, b, h) do { _Pragma("unroll") for (int m = 0; m < 4; ++m) _Pragma("unroll") for (int k = 0; k < 2; ++k) dst[m][k] = *(const LAS bf16x8*)(lds + PG8_SA(b, h) + aoff + m * 2048 + k * 1024); } while (0)
; #define PG8_MMA(ai, bj, At, Bt) do { __builtin_amdgcn_s_setprio(1); _Pragma("unroll") for (int m = 0; m < 4; ++m) _Pragma("unroll") for (int n = 0; n < 2; ++n) _Pragma("unroll") for (int k = 0; k < 2; ++k) \
;         acc[ai][bj][m][n] = __builtin_amdgcn_mfma_f32_16x16x32_bf16(Bt[n][k], At[m][k], acc[ai][bj][m][n], 0, 0, 0); __builtin_amdgcn_s_setprio(0); } while (0)
; #define PG8_WAIT_V(n) asm volatile("s_waitcnt vmcnt(" #n ")" ::: "memory")
; #define PG8_WAIT_L(n) asm volatile("s_waitcnt lgkmcnt(" #n ")" ::: "memory")
; #define PG8_BAR __builtin_amdgcn_s_barrier()
; #define PG8_SCHED __builtin_amdgcn_sched_barrier(0)
; template <class Epi>
; DI void gemm_phase(LAS unsigned char* lds, const int wid, const Gemm g, const Order& S, const Epi& E) {
;     ...
;         for (int t = 0; t < nt; t += 2) {
;     ...
;             PG8_LDA(At, 1, 1); PG8_STAGE(PG8_SB(1, 0), b3, voffB); PG8_STAGE(PG8_SB(1, 1), b3 + hstepB, voffB); PG8_STAGE(PG8_SA(1, 0), a3, voffA);
;             PG8_WAIT_V(8); PG8_WAIT_L(0); PG8_BAR; PG8_MMA(1, 0, At, B0); PG8_MMA(1, 1, At, B1); PG8_BAR; PG8_SCHED;
	s_add_i32 s42, s64, s94
	v_lshl_add_u64 v[214:215], v[214:215], 0, s[34:35]
	s_mov_b32 m0, s42
	ds_read_b128 v[160:163], v211 offset:49152
	ds_read_b128 v[164:167], v211 offset:50176
	ds_read_b128 v[168:171], v211 offset:51200
	ds_read_b128 v[172:175], v211 offset:52224
	ds_read_b128 v[192:195], v211 offset:53248
	ds_read_b128 v[196:199], v211 offset:54272
	ds_read_b128 v[200:203], v211 offset:55296
	ds_read_b128 v[204:207], v211 offset:56320
	global_load_lds_dwordx4 v[214:215], off
	s_add_i32 m0, s42, 0x2000
	s_add_u32 s42, s44, 0xb0080
	v_lshl_add_u64 v[214:215], v[216:217], 0, s[34:35]
	s_addc_u32 s43, s45, 0
	s_add_i32 s44, s65, s94
	global_load_lds_dwordx4 v[214:215], off
	v_lshl_add_u64 v[214:215], s[42:43], 0, v[178:179]
	s_mov_b32 m0, s44
	s_nop 0
	global_load_lds_dwordx4 v[214:215], off
	v_lshl_add_u64 v[214:215], s[42:43], 0, v[182:183]
	s_add_i32 m0, s44, 0x2000
	s_nop 0
	global_load_lds_dwordx4 v[214:215], off
	v_lshl_add_u64 v[214:215], v[218:219], 0, s[34:35]
	s_mov_b32 m0, s51
	s_nop 0
	global_load_lds_dwordx4 v[214:215], off
	v_lshl_add_u64 v[214:215], v[220:221], 0, s[34:35]
	s_mov_b32 m0, s52
	s_nop 0
	global_load_lds_dwordx4 v[214:215], off
	s_waitcnt vmcnt(8)
	s_waitcnt lgkmcnt(0)
	s_barrier
	s_setprio 1
	s_waitcnt lgkmcnt(0)
	v_mfma_f32_16x16x32_bf16 v[60:63], v[128:131], v[160:163], v[60:63]
	v_mfma_f32_16x16x32_bf16 v[56:59], v[136:139], v[160:163], v[56:59]
	v_mfma_f32_16x16x32_bf16 v[44:47], v[128:131], v[168:171], v[44:47]
	v_mfma_f32_16x16x32_bf16 v[40:43], v[136:139], v[168:171], v[40:43]
	v_mfma_f32_16x16x32_bf16 v[28:31], v[128:131], v[192:195], v[28:31]
	v_mfma_f32_16x16x32_bf16 v[24:27], v[136:139], v[192:195], v[24:27]
	v_mfma_f32_16x16x32_bf16 v[12:15], v[128:131], v[200:203], v[12:15]
	v_mfma_f32_16x16x32_bf16 v[8:11], v[136:139], v[200:203], v[8:11]
	v_mfma_f32_16x16x32_bf16 v[60:63], v[132:135], v[164:167], v[60:63]
	v_mfma_f32_16x16x32_bf16 v[56:59], v[140:143], v[164:167], v[56:59]
	v_mfma_f32_16x16x32_bf16 v[44:47], v[132:135], v[172:175], v[44:47]
	v_mfma_f32_16x16x32_bf16 v[40:43], v[140:143], v[172:175], v[40:43]
	v_mfma_f32_16x16x32_bf16 v[28:31], v[132:135], v[196:199], v[28:31]
	v_mfma_f32_16x16x32_bf16 v[24:27], v[140:143], v[196:199], v[24:27]
	v_mfma_f32_16x16x32_bf16 v[12:15], v[132:135], v[204:207], v[12:15]
	v_mfma_f32_16x16x32_bf16 v[8:11], v[140:143], v[204:207], v[8:11]
	s_setprio 0
	s_setprio 1
	v_mfma_f32_16x16x32_bf16 v[52:55], v[144:147], v[160:163], v[52:55]
	v_mfma_f32_16x16x32_bf16 v[48:51], v[152:155], v[160:163], v[48:51]
	v_mfma_f32_16x16x32_bf16 v[36:39], v[144:147], v[168:171], v[36:39]
	v_mfma_f32_16x16x32_bf16 v[32:35], v[152:155], v[168:171], v[32:35]
	v_mfma_f32_16x16x32_bf16 v[20:23], v[144:147], v[192:195], v[20:23]
	v_mfma_f32_16x16x32_bf16 v[16:19], v[152:155], v[192:195], v[16:19]
	v_mfma_f32_16x16x32_bf16 v[4:7], v[144:147], v[200:203], v[4:7]
	v_mfma_f32_16x16x32_bf16 v[0:3], v[152:155], v[200:203], v[0:3]
	v_mfma_f32_16x16x32_bf16 v[52:55], v[148:151], v[164:167], v[52:55]
	v_mfma_f32_16x16x32_bf16 v[48:51], v[156:159], v[164:167], v[48:51]
	v_mfma_f32_16x16x32_bf16 v[36:39], v[148:151], v[172:175], v[36:39]
	v_mfma_f32_16x16x32_bf16 v[32:35], v[156:159], v[172:175], v[32:35]
	v_mfma_f32_16x16x32_bf16 v[20:23], v[148:151], v[196:199], v[20:23]
	v_mfma_f32_16x16x32_bf16 v[16:19], v[156:159], v[196:199], v[16:19]
	v_mfma_f32_16x16x32_bf16 v[4:7], v[148:151], v[204:207], v[4:7]
	v_mfma_f32_16x16x32_bf16 v[0:3], v[156:159], v[204:207], v[0:3]
	s_setprio 0
	s_barrier
	s_add_i32 s63, s63, 2
	s_add_u32 s61, s61, 0x100
	s_addc_u32 s62, s62, 0
	s_cmp_gt_u32 s63, 41
	s_mov_b64 s[42:43], s[10:11]
	s_cbranch_scc0 .LBB0_312
	s_branch .Lpeel_exit_1

; #define PG8_BAR __builtin_amdgcn_s_barrier()
; template <class Epi>
; DI void gemm_phase(LAS unsigned char* lds, const int wid, const Gemm g, const Order& S, const Epi& E) {
;     ...
;         if (wr == 0) PG8_BAR;
.Lpeel_exit_1:
	s_and_b64 vcc, exec, s[36:37]
	s_cbranch_vccz .LBB0_315
	s_barrier

; #define PG8_STAGE(bufoff, gbase, voff) do { _Pragma("unroll") for (int _i = 0; _i < 2; ++_i) \
;         __builtin_amdgcn_global_load_lds((const unsigned*)((const char*)(gbase) + (voff)[_i]), (LAS unsigned*)(lds + (bufoff) + ldsw + _i * 8192), 16, 0, 0); } while (0)
; #define PG8_LDA(dst, b, h) do { _Pragma("unroll") for (int m = 0; m < 4; ++m) _Pragma("unroll") for (int k = 0; k < 2; ++k) dst[m][k] = *(const LAS bf16x8*)(lds + PG8_SA(b, h) + aoff + m * 2048 + k * 1024); } while (0)
; #define PG8_LDB(dst, b, h) do { _Pragma("unroll") for (int n = 0; n < 2; ++n) _Pragma("unroll") for (int k = 0; k < 2; ++k) dst[n][k] = *(const LAS bf16x8*)(lds + PG8_SB(b, h) + boff + n * 2048 + k * 1024); } while (0)
; #define PG8_MMA(ai, bj, At, Bt) do { __builtin_amdgcn_s_setprio(1); _Pragma("unroll") for (int m = 0; m < 4; ++m) _Pragma("unroll") for (int n = 0; n < 2; ++n) _Pragma("unroll") for (int k = 0; k < 2; ++k) \
;         acc[ai][bj][m][n] = __builtin_amdgcn_mfma_f32_16x16x32_bf16(Bt[n][k], At[m][k], acc[ai][bj][m][n], 0, 0, 0); __builtin_amdgcn_s_setprio(0); } while (0)
; #define PG8_WAIT_V(n) asm volatile("s_waitcnt vmcnt(" #n ")" ::: "memory")
; #define PG8_WAIT_L(n) asm volatile("s_waitcnt lgkmcnt(" #n ")" ::: "memory")
; template <class Epi>
; DI void gemm_phase(LAS unsigned char* lds, const int wid, const Gemm g, const Order& S, const Epi& E) {
;     ...
;         const char* nA = has_next ? (const char*)(g.A + (size_t)nxt.g * g.gsA + (size_t)nxt.pm * BM * g.lda) : cA;
;         const char* nB = has_next ? (const char*)(g.Bt + (size_t)nxt.g * g.gsB + (size_t)nxt.pn * BM * g.ldb) : cB;
;         for (int t = 0; t < nt; t += 2) {
;             const bool last = (t == nt - 2);
;             const char* a1 = cA + (size_t)(t + 1) * kstep;
;             const char* a2 = last ? nA : cA + (size_t)(t + 2) * kstep; const char* b2 = last ? nB : cB + (size_t)(t + 2) * kstep;
;             const char* a3 = a2 + kstep; const char* b3 = b2 + kstep;
;             PG8_LDB(B0, 0, 0); PG8_LDB(B1, 0, 1); PG8_SCHED; PG8_LDA(At, 0, 0); PG8_STAGE(PG8_SA(1, 1), a1 + hstepA, voffA);
;             PG8_WAIT_V(8); PG8_WAIT_L(0); PG8_BAR; PG8_MMA(0, 0, At, B0); PG8_MMA(0, 1, At, B1); PG8_BAR; PG8_SCHED;
;             PG8_LDA(At, 0, 1); PG8_STAGE(PG8_SB(0, 0), b2, voffB); PG8_STAGE(PG8_SB(0, 1), b2 + hstepB, voffB); PG8_STAGE(PG8_SA(0, 0), a2, voffA);
.LBB0_399:
	s_ashr_i32 s57, s56, 31
	s_lshl_b64 s[60:61], s[56:57], 19
	s_add_u32 s60, s73, s60
	s_addc_u32 s61, s74, s61
	s_and_b64 s[62:63], s[8:9], exec
	s_cselect_b32 s11, s61, s13
	s_cselect_b32 s16, s60, s12
	s_ashr_i32 s59, s58, 31
	s_lshl_b64 s[62:63], s[58:59], 19
	s_add_u32 s62, s75, s62
	s_addc_u32 s63, s76, s63
	s_and_b64 s[66:67], s[8:9], exec
	s_cselect_b32 s57, s63, s65
	s_cselect_b32 s59, s62, s64
	s_add_u32 s12, s12, 0x40080
	s_addc_u32 s13, s13, 0
	s_add_u32 s68, s64, 0x100
	v_mov_b32_e32 v0, 0
	s_addc_u32 s69, s65, 0
	s_mov_b32 s70, -2
	s_waitcnt lgkmcnt(0)
	ds_read_b128 v[146:149], v163
	ds_read_b128 v[150:153], v163 offset:1024
	ds_read_b128 v[154:157], v163 offset:2048
	ds_read_b128 v[158:161], v163 offset:3072
	ds_read_b128 v[168:171], v164
	ds_read_b128 v[172:175], v164 offset:1024
	ds_read_b128 v[176:179], v164 offset:2048
	ds_read_b128 v[180:183], v164 offset:3072
	s_add_u32 s64, s12, 0xfffc0080
	s_addc_u32 s65, s13, -1
	s_cmp_eq_u32 s70, 12
	s_cselect_b32 s67, s11, s65
	s_cselect_b32 s66, s16, s64
	s_cselect_b32 s65, s57, s69
	s_cselect_b32 s64, s59, s68
	v_lshl_add_u64 v[212:213], s[12:13], 0, v[138:139]
	s_add_i32 m0, s6, 0xc000
	ds_read_b128 v[184:187], v165
	ds_read_b128 v[188:191], v165 offset:1024
	ds_read_b128 v[192:195], v165 offset:2048
	ds_read_b128 v[196:199], v165 offset:3072
	ds_read_b128 v[200:203], v165 offset:4096
	ds_read_b128 v[204:207], v165 offset:5120
	ds_read_b128 v[208:211], v165 offset:6144
	ds_read_b128 v[216:219], v165 offset:7168
	global_load_lds_dwordx4 v[212:213], off
	v_lshl_add_u64 v[212:213], s[12:13], 0, v[140:141]
	s_add_i32 m0, s6, 0xe000
	s_nop 0
	global_load_lds_dwordx4 v[212:213], off
	s_waitcnt vmcnt(8)
	s_waitcnt lgkmcnt(0)
	s_barrier
	s_setprio 1
	s_waitcnt lgkmcnt(0)
	v_mfma_f32_16x16x32_bf16 v[124:127], v[146:149], v[184:187], 0
	v_mfma_f32_16x16x32_bf16 v[120:123], v[154:157], v[184:187], 0
	v_mfma_f32_16x16x32_bf16 v[108:111], v[146:149], v[192:195], 0
	v_mfma_f32_16x16x32_bf16 v[104:107], v[154:157], v[192:195], 0
	v_mfma_f32_16x16x32_bf16 v[92:95], v[146:149], v[200:203], 0
	v_mfma_f32_16x16x32_bf16 v[88:91], v[154:157], v[200:203], 0
	v_mfma_f32_16x16x32_bf16 v[76:79], v[146:149], v[208:211], 0
	v_mfma_f32_16x16x32_bf16 v[72:75], v[154:157], v[208:211], 0
	v_mfma_f32_16x16x32_bf16 v[124:127], v[150:153], v[188:191], v[124:127]
	v_mfma_f32_16x16x32_bf16 v[120:123], v[158:161], v[188:191], v[120:123]
	v_mfma_f32_16x16x32_bf16 v[108:111], v[150:153], v[196:199], v[108:111]
	v_mfma_f32_16x16x32_bf16 v[104:107], v[158:161], v[196:199], v[104:107]
	v_mfma_f32_16x16x32_bf16 v[92:95], v[150:153], v[204:207], v[92:95]
	v_mfma_f32_16x16x32_bf16 v[88:91], v[158:161], v[204:207], v[88:91]
	v_mfma_f32_16x16x32_bf16 v[76:79], v[150:153], v[216:219], v[76:79]
	v_mfma_f32_16x16x32_bf16 v[72:75], v[158:161], v[216:219], v[72:75]
	s_setprio 0
	s_setprio 1
	v_mfma_f32_16x16x32_bf16 v[116:119], v[168:171], v[184:187], 0
	v_mfma_f32_16x16x32_bf16 v[112:115], v[176:179], v[184:187], 0
	v_mfma_f32_16x16x32_bf16 v[100:103], v[168:171], v[192:195], 0
	v_mfma_f32_16x16x32_bf16 v[96:99], v[176:179], v[192:195], 0
	v_mfma_f32_16x16x32_bf16 v[84:87], v[168:171], v[200:203], 0
	v_mfma_f32_16x16x32_bf16 v[80:83], v[176:179], v[200:203], 0
	v_mfma_f32_16x16x32_bf16 v[68:71], v[168:171], v[208:211], 0
	v_mfma_f32_16x16x32_bf16 v[64:67], v[176:179], v[208:211], 0
	v_mfma_f32_16x16x32_bf16 v[116:119], v[172:175], v[188:191], v[116:119]
	v_mfma_f32_16x16x32_bf16 v[112:115], v[180:183], v[188:191], v[112:115]
	v_mfma_f32_16x16x32_bf16 v[100:103], v[172:175], v[196:199], v[100:103]
	v_mfma_f32_16x16x32_bf16 v[96:99], v[180:183], v[196:199], v[96:99]
	v_mfma_f32_16x16x32_bf16 v[84:87], v[172:175], v[204:207], v[84:87]
	v_mfma_f32_16x16x32_bf16 v[80:83], v[180:183], v[204:207], v[80:83]
	v_mfma_f32_16x16x32_bf16 v[68:71], v[172:175], v[216:219], v[68:71]
	v_mfma_f32_16x16x32_bf16 v[64:67], v[180:183], v[216:219], v[64:67]
	s_setprio 0
	s_barrier
	s_add_i32 s71, s82, s94
	v_lshl_add_u64 v[212:213], s[64:65], 0, v[130:131]
	s_mov_b32 m0, s71
	ds_read_b128 v[184:187], v165 offset:16384
	ds_read_b128 v[188:191], v165 offset:17408
	ds_read_b128 v[192:195], v165 offset:18432
	ds_read_b128 v[196:199], v165 offset:19456
	ds_read_b128 v[200:203], v165 offset:20480
	ds_read_b128 v[204:207], v165 offset:21504
	ds_read_b128 v[208:211], v165 offset:22528
	ds_read_b128 v[216:219], v165 offset:23552
	global_load_lds_dwordx4 v[212:213], off
	s_add_i32 m0, s71, 0x2000
	s_add_u32 s86, s64, 0x40000
	v_lshl_add_u64 v[214:215], s[64:65], 0, v[134:135]
	s_addc_u32 s87, s65, 0
	s_add_i32 s71, s83, s94
	global_load_lds_dwordx4 v[214:215], off
	v_lshl_add_u64 v[220:221], s[86:87], 0, v[130:131]
	s_mov_b32 m0, s71
	v_lshl_add_u64 v[222:223], s[66:67], 0, v[132:133]
	global_load_lds_dwordx4 v[220:221], off
	v_lshl_add_u64 v[220:221], s[86:87], 0, v[134:135]
	s_add_i32 m0, s71, 0x2000
	s_nop 0
	global_load_lds_dwordx4 v[220:221], off
	v_lshl_add_u64 v[220:221], s[66:67], 0, v[128:129]
	s_mov_b32 m0, s6
	s_nop 0
	global_load_lds_dwordx4 v[220:221], off
	s_mov_b32 m0, s7
	s_nop 0
	global_load_lds_dwordx4 v[222:223], off
	s_waitcnt vmcnt(8)
	s_waitcnt lgkmcnt(0)
	s_barrier
; #define PG8_STAGE(bufoff, gbase, voff) do { _Pragma("unroll") for (int _i = 0; _i < 2; ++_i) \
;         __builtin_amdgcn_global_load_lds((const unsigned*)((const char*)(gbase) + (voff)[_i]), (LAS unsigned*)(lds + (bufoff) + ldsw + _i * 8192), 16, 0, 0); } while (0)
; #define PG8_LDA(dst, b, h) do { _Pragma("unroll") for (int m = 0; m < 4; ++m) _Pragma("unroll") for (int k = 0; k < 2; ++k) dst[m][k] = *(const LAS bf16x8*)(lds + PG8_SA(b, h) + aoff + m * 2048 + k * 1024); } while (0)
; #define PG8_LDB(dst, b, h) do { _Pragma("unroll") for (int n = 0; n < 2; ++n) _Pragma("unroll") for (int k = 0; k < 2; ++k) dst[n][k] = *(const LAS bf16x8*)(lds + PG8_SB(b, h) + boff + n * 2048 + k * 1024); } while (0)
; #define PG8_MMA(ai, bj, At, Bt) do { __builtin_amdgcn_s_setprio(1); _Pragma("unroll") for (int m = 0; m < 4; ++m) _Pragma("unroll") for (int n = 0; n < 2; ++n) _Pragma("unroll") for (int k = 0; k < 2; ++k) \
;         acc[ai][bj][m][n] = __builtin_amdgcn_mfma_f32_16x16x32_bf16(Bt[n][k], At[m][k], acc[ai][bj][m][n], 0, 0, 0); __builtin_amdgcn_s_setprio(0); } while (0)
; #define PG8_WAIT_V(n) asm volatile("s_waitcnt vmcnt(" #n ")" ::: "memory")
; #define PG8_WAIT_L(n) asm volatile("s_waitcnt lgkmcnt(" #n ")" ::: "memory")
; #define PG8_BAR __builtin_amdgcn_s_barrier()
; #define PG8_SCHED __builtin_amdgcn_sched_barrier(0)
; template <class Epi>
; DI void gemm_phase(LAS unsigned char* lds, const int wid, const Gemm g, const Order& S, const Epi& E) {
;     ...
;             PG8_WAIT_V(8); PG8_WAIT_L(0); PG8_BAR; PG8_MMA(1, 0, At, B0); PG8_MMA(1, 1, At, B1); PG8_BAR; PG8_SCHED;
;             PG8_LDB(B0, 1, 0); PG8_LDB(B1, 1, 1); PG8_SCHED; PG8_LDA(At, 1, 0); PG8_STAGE(PG8_SA(0, 1), a2 + hstepA, voffA);
;             PG8_WAIT_V(8); PG8_WAIT_L(0); PG8_BAR; PG8_MMA(0, 0, At, B0); PG8_MMA(0, 1, At, B1); PG8_BAR; PG8_SCHED;
	s_setprio 1
	s_waitcnt lgkmcnt(0)
	v_mfma_f32_16x16x32_bf16 v[60:63], v[146:149], v[184:187], 0
	v_mfma_f32_16x16x32_bf16 v[56:59], v[154:157], v[184:187], 0
	v_mfma_f32_16x16x32_bf16 v[44:47], v[146:149], v[192:195], 0
	v_mfma_f32_16x16x32_bf16 v[40:43], v[154:157], v[192:195], 0
	v_mfma_f32_16x16x32_bf16 v[28:31], v[146:149], v[200:203], 0
	v_mfma_f32_16x16x32_bf16 v[24:27], v[154:157], v[200:203], 0
	v_mfma_f32_16x16x32_bf16 v[12:15], v[146:149], v[208:211], 0
	v_mfma_f32_16x16x32_bf16 v[8:11], v[154:157], v[208:211], 0
	v_mfma_f32_16x16x32_bf16 v[60:63], v[150:153], v[188:191], v[60:63]
	v_mfma_f32_16x16x32_bf16 v[56:59], v[158:161], v[188:191], v[56:59]
	v_mfma_f32_16x16x32_bf16 v[44:47], v[150:153], v[196:199], v[44:47]
	v_mfma_f32_16x16x32_bf16 v[40:43], v[158:161], v[196:199], v[40:43]
	v_mfma_f32_16x16x32_bf16 v[28:31], v[150:153], v[204:207], v[28:31]
	v_mfma_f32_16x16x32_bf16 v[24:27], v[158:161], v[204:207], v[24:27]
	v_mfma_f32_16x16x32_bf16 v[12:15], v[150:153], v[216:219], v[12:15]
	v_mfma_f32_16x16x32_bf16 v[8:11], v[158:161], v[216:219], v[8:11]
	s_setprio 0
	s_setprio 1
	v_mfma_f32_16x16x32_bf16 v[52:55], v[168:171], v[184:187], 0
	v_mfma_f32_16x16x32_bf16 v[48:51], v[176:179], v[184:187], 0
	v_mfma_f32_16x16x32_bf16 v[36:39], v[168:171], v[192:195], 0
	v_mfma_f32_16x16x32_bf16 v[32:35], v[176:179], v[192:195], 0
	v_mfma_f32_16x16x32_bf16 v[20:23], v[168:171], v[200:203], 0
	v_mfma_f32_16x16x32_bf16 v[16:19], v[176:179], v[200:203], 0
	v_mfma_f32_16x16x32_bf16 v[4:7], v[168:171], v[208:211], 0
	v_mfma_f32_16x16x32_bf16 v[0:3], v[176:179], v[208:211], 0
	v_mfma_f32_16x16x32_bf16 v[52:55], v[172:175], v[188:191], v[52:55]
	v_mfma_f32_16x16x32_bf16 v[48:51], v[180:183], v[188:191], v[48:51]
	v_mfma_f32_16x16x32_bf16 v[36:39], v[172:175], v[196:199], v[36:39]
	v_mfma_f32_16x16x32_bf16 v[32:35], v[180:183], v[196:199], v[32:35]
	v_mfma_f32_16x16x32_bf16 v[20:23], v[172:175], v[204:207], v[20:23]
	v_mfma_f32_16x16x32_bf16 v[16:19], v[180:183], v[204:207], v[16:19]
	v_mfma_f32_16x16x32_bf16 v[4:7], v[172:175], v[216:219], v[4:7]
	v_mfma_f32_16x16x32_bf16 v[0:3], v[180:183], v[216:219], v[0:3]
	s_setprio 0
	s_barrier
	s_add_i32 s71, 0, 0x18000
	v_add_u32_e32 v136, s71, v162
	s_add_i32 s86, 0, 0x1c000
	ds_read_b128 v[146:149], v136
	ds_read_b128 v[150:153], v136 offset:1024
	ds_read_b128 v[154:157], v136 offset:2048
	ds_read_b128 v[158:161], v136 offset:3072
	v_add_u32_e32 v136, s86, v162
	ds_read_b128 v[168:171], v136
	ds_read_b128 v[172:175], v136 offset:1024
	ds_read_b128 v[176:179], v136 offset:2048
	ds_read_b128 v[180:183], v136 offset:3072
	s_add_u32 s66, s66, 0x40000
	s_addc_u32 s67, s67, 0
	s_mov_b32 m0, s21
	v_lshl_add_u64 v[224:225], s[66:67], 0, v[128:129]
	ds_read_b128 v[184:187], v165 offset:32768
	ds_read_b128 v[188:191], v165 offset:33792
	ds_read_b128 v[192:195], v165 offset:34816
	ds_read_b128 v[196:199], v165 offset:35840
	ds_read_b128 v[200:203], v165 offset:36864
	ds_read_b128 v[204:207], v165 offset:37888
	ds_read_b128 v[208:211], v165 offset:38912
	ds_read_b128 v[216:219], v165 offset:39936
	global_load_lds_dwordx4 v[224:225], off
	v_lshl_add_u64 v[224:225], s[66:67], 0, v[132:133]
	s_mov_b32 m0, s26
	s_nop 0
	global_load_lds_dwordx4 v[224:225], off
	s_waitcnt vmcnt(8)
	s_waitcnt lgkmcnt(0)
	s_barrier
	s_setprio 1
	s_waitcnt lgkmcnt(0)
	v_mfma_f32_16x16x32_bf16 v[124:127], v[146:149], v[184:187], v[124:127]
	v_mfma_f32_16x16x32_bf16 v[120:123], v[154:157], v[184:187], v[120:123]
	v_mfma_f32_16x16x32_bf16 v[108:111], v[146:149], v[192:195], v[108:111]
	v_mfma_f32_16x16x32_bf16 v[104:107], v[154:157], v[192:195], v[104:107]
	v_mfma_f32_16x16x32_bf16 v[92:95], v[146:149], v[200:203], v[92:95]
	v_mfma_f32_16x16x32_bf16 v[88:91], v[154:157], v[200:203], v[88:91]
	v_mfma_f32_16x16x32_bf16 v[76:79], v[146:149], v[208:211], v[76:79]
	v_mfma_f32_16x16x32_bf16 v[72:75], v[154:157], v[208:211], v[72:75]
	v_mfma_f32_16x16x32_bf16 v[124:127], v[150:153], v[188:191], v[124:127]
	v_mfma_f32_16x16x32_bf16 v[120:123], v[158:161], v[188:191], v[120:123]
	v_mfma_f32_16x16x32_bf16 v[108:111], v[150:153], v[196:199], v[108:111]
	v_mfma_f32_16x16x32_bf16 v[104:107], v[158:161], v[196:199], v[104:107]
	v_mfma_f32_16x16x32_bf16 v[92:95], v[150:153], v[204:207], v[92:95]
	v_mfma_f32_16x16x32_bf16 v[88:91], v[158:161], v[204:207], v[88:91]
	v_mfma_f32_16x16x32_bf16 v[76:79], v[150:153], v[216:219], v[76:79]
	v_mfma_f32_16x16x32_bf16 v[72:75], v[158:161], v[216:219], v[72:75]
	s_setprio 0
	s_setprio 1
	v_mfma_f32_16x16x32_bf16 v[116:119], v[168:171], v[184:187], v[116:119]
	v_mfma_f32_16x16x32_bf16 v[112:115], v[176:179], v[184:187], v[112:115]
	v_mfma_f32_16x16x32_bf16 v[100:103], v[168:171], v[192:195], v[100:103]
	v_mfma_f32_16x16x32_bf16 v[96:99], v[176:179], v[192:195], v[96:99]
	v_mfma_f32_16x16x32_bf16 v[84:87], v[168:171], v[200:203], v[84:87]
	v_mfma_f32_16x16x32_bf16 v[80:83], v[176:179], v[200:203], v[80:83]
	v_mfma_f32_16x16x32_bf16 v[68:71], v[168:171], v[208:211], v[68:71]
	v_mfma_f32_16x16x32_bf16 v[64:67], v[176:179], v[208:211], v[64:67]
	v_mfma_f32_16x16x32_bf16 v[116:119], v[172:175], v[188:191], v[116:119]
	v_mfma_f32_16x16x32_bf16 v[112:115], v[180:183], v[188:191], v[112:115]
	v_mfma_f32_16x16x32_bf16 v[100:103], v[172:175], v[196:199], v[100:103]
	v_mfma_f32_16x16x32_bf16 v[96:99], v[180:183], v[196:199], v[96:99]
	v_mfma_f32_16x16x32_bf16 v[84:87], v[172:175], v[204:207], v[84:87]
	v_mfma_f32_16x16x32_bf16 v[80:83], v[180:183], v[204:207], v[80:83]
	v_mfma_f32_16x16x32_bf16 v[68:71], v[172:175], v[216:219], v[68:71]
	v_mfma_f32_16x16x32_bf16 v[64:67], v[180:183], v[216:219], v[64:67]
	s_setprio 0
	s_barrier
; #define PG8_STAGE(bufoff, gbase, voff) do { _Pragma("unroll") for (int _i = 0; _i < 2; ++_i) \
;         __builtin_amdgcn_global_load_lds((const unsigned*)((const char*)(gbase) + (voff)[_i]), (LAS unsigned*)(lds + (bufoff) + ldsw + _i * 8192), 16, 0, 0); } while (0)
; #define PG8_LDA(dst, b, h) do { _Pragma("unroll") for (int m = 0; m < 4; ++m) _Pragma("unroll") for (int k = 0; k < 2; ++k) dst[m][k] = *(const LAS bf16x8*)(lds + PG8_SA(b, h) + aoff + m * 2048 + k * 1024); } while (0)
; #define PG8_MMA(ai, bj, At, Bt) do { __builtin_amdgcn_s_setprio(1); _Pragma("unroll") for (int m = 0; m < 4; ++m) _Pragma("unroll") for (int n = 0; n < 2; ++n) _Pragma("unroll") for (int k = 0; k < 2; ++k) \
;         acc[ai][bj][m][n] = __builtin_amdgcn_mfma_f32_16x16x32_bf16(Bt[n][k], At[m][k], acc[ai][bj][m][n], 0, 0, 0); __builtin_amdgcn_s_setprio(0); } while (0)
; #define PG8_WAIT_V(n) asm volatile("s_waitcnt vmcnt(" #n ")" ::: "memory")
; #define PG8_WAIT_L(n) asm volatile("s_waitcnt lgkmcnt(" #n ")" ::: "memory")
; #define PG8_BAR __builtin_amdgcn_s_barrier()
; #define PG8_SCHED __builtin_amdgcn_sched_barrier(0)
; template <class Epi>
; DI void gemm_phase(LAS unsigned char* lds, const int wid, const Gemm g, const Order& S, const Epi& E) {
;     ...
;         for (int t = 0; t < nt; t += 2) {
;     ...
;             PG8_LDA(At, 1, 1); PG8_STAGE(PG8_SB(1, 0), b3, voffB); PG8_STAGE(PG8_SB(1, 1), b3 + hstepB, voffB); PG8_STAGE(PG8_SA(1, 0), a3, voffA);
;             PG8_WAIT_V(8); PG8_WAIT_L(0); PG8_BAR; PG8_MMA(1, 0, At, B0); PG8_MMA(1, 1, At, B1); PG8_BAR; PG8_SCHED;
	s_add_i32 s66, s71, s94
	v_lshl_add_u64 v[212:213], v[212:213], 0, s[34:35]
	s_mov_b32 m0, s66
	ds_read_b128 v[184:187], v165 offset:49152
	ds_read_b128 v[188:191], v165 offset:50176
	ds_read_b128 v[192:195], v165 offset:51200
	ds_read_b128 v[196:199], v165 offset:52224
	ds_read_b128 v[200:203], v165 offset:53248
	ds_read_b128 v[204:207], v165 offset:54272
	ds_read_b128 v[208:211], v165 offset:55296
	ds_read_b128 v[216:219], v165 offset:56320
	global_load_lds_dwordx4 v[212:213], off
	s_add_i32 m0, s66, 0x2000
	s_add_u32 s64, s64, 0x40080
	v_lshl_add_u64 v[212:213], v[214:215], 0, s[34:35]
	s_addc_u32 s65, s65, 0
	s_add_i32 s66, s86, s94
	global_load_lds_dwordx4 v[212:213], off
	v_lshl_add_u64 v[212:213], s[64:65], 0, v[130:131]
	s_mov_b32 m0, s66
	s_nop 0
	global_load_lds_dwordx4 v[212:213], off
	v_lshl_add_u64 v[212:213], s[64:65], 0, v[134:135]
	s_add_i32 m0, s66, 0x2000
	s_nop 0
	global_load_lds_dwordx4 v[212:213], off
	v_lshl_add_u64 v[212:213], v[220:221], 0, s[34:35]
	s_mov_b32 m0, s27
	s_nop 0
	global_load_lds_dwordx4 v[212:213], off
	v_lshl_add_u64 v[212:213], v[222:223], 0, s[34:35]
	s_mov_b32 m0, s55
	s_nop 0
	global_load_lds_dwordx4 v[212:213], off
	s_waitcnt vmcnt(8)
	s_waitcnt lgkmcnt(0)
	s_barrier
	s_setprio 1
	s_waitcnt lgkmcnt(0)
	v_mfma_f32_16x16x32_bf16 v[60:63], v[146:149], v[184:187], v[60:63]
	v_mfma_f32_16x16x32_bf16 v[56:59], v[154:157], v[184:187], v[56:59]
	v_mfma_f32_16x16x32_bf16 v[44:47], v[146:149], v[192:195], v[44:47]
	v_mfma_f32_16x16x32_bf16 v[40:43], v[154:157], v[192:195], v[40:43]
	v_mfma_f32_16x16x32_bf16 v[28:31], v[146:149], v[200:203], v[28:31]
	v_mfma_f32_16x16x32_bf16 v[24:27], v[154:157], v[200:203], v[24:27]
	v_mfma_f32_16x16x32_bf16 v[12:15], v[146:149], v[208:211], v[12:15]
	v_mfma_f32_16x16x32_bf16 v[8:11], v[154:157], v[208:211], v[8:11]
	v_mfma_f32_16x16x32_bf16 v[60:63], v[150:153], v[188:191], v[60:63]
	v_mfma_f32_16x16x32_bf16 v[56:59], v[158:161], v[188:191], v[56:59]
	v_mfma_f32_16x16x32_bf16 v[44:47], v[150:153], v[196:199], v[44:47]
	v_mfma_f32_16x16x32_bf16 v[40:43], v[158:161], v[196:199], v[40:43]
	v_mfma_f32_16x16x32_bf16 v[28:31], v[150:153], v[204:207], v[28:31]
	v_mfma_f32_16x16x32_bf16 v[24:27], v[158:161], v[204:207], v[24:27]
	v_mfma_f32_16x16x32_bf16 v[12:15], v[150:153], v[216:219], v[12:15]
	v_mfma_f32_16x16x32_bf16 v[8:11], v[158:161], v[216:219], v[8:11]
	s_setprio 0
	s_setprio 1
	v_mfma_f32_16x16x32_bf16 v[52:55], v[168:171], v[184:187], v[52:55]
	v_mfma_f32_16x16x32_bf16 v[48:51], v[176:179], v[184:187], v[48:51]
	v_mfma_f32_16x16x32_bf16 v[36:39], v[168:171], v[192:195], v[36:39]
	v_mfma_f32_16x16x32_bf16 v[32:35], v[176:179], v[192:195], v[32:35]
	v_mfma_f32_16x16x32_bf16 v[20:23], v[168:171], v[200:203], v[20:23]
	v_mfma_f32_16x16x32_bf16 v[16:19], v[176:179], v[200:203], v[16:19]
	v_mfma_f32_16x16x32_bf16 v[4:7], v[168:171], v[208:211], v[4:7]
	v_mfma_f32_16x16x32_bf16 v[0:3], v[176:179], v[208:211], v[0:3]
	v_mfma_f32_16x16x32_bf16 v[52:55], v[172:175], v[188:191], v[52:55]
	v_mfma_f32_16x16x32_bf16 v[48:51], v[180:183], v[188:191], v[48:51]
	v_mfma_f32_16x16x32_bf16 v[36:39], v[172:175], v[196:199], v[36:39]
	v_mfma_f32_16x16x32_bf16 v[32:35], v[180:183], v[196:199], v[32:35]
	v_mfma_f32_16x16x32_bf16 v[20:23], v[172:175], v[204:207], v[20:23]
	v_mfma_f32_16x16x32_bf16 v[16:19], v[180:183], v[204:207], v[16:19]
	v_mfma_f32_16x16x32_bf16 v[4:7], v[172:175], v[216:219], v[4:7]
	v_mfma_f32_16x16x32_bf16 v[0:3], v[180:183], v[216:219], v[0:3]
	s_setprio 0
	s_barrier
	s_add_i32 s70, s70, 2
	s_add_u32 s12, s12, 0x100
	s_addc_u32 s13, s13, 0
	s_add_u32 s68, s68, 0x100
	s_addc_u32 s69, s69, 0
	s_cmp_gt_u32 s70, 13
	s_cbranch_scc0 .LBB0_400
	s_branch .Lpeel_exit_2

; #define PG8_STAGE(bufoff, gbase, voff) do { _Pragma("unroll") for (int _i = 0; _i < 2; ++_i) \
;         __builtin_amdgcn_global_load_lds((const unsigned*)((const char*)(gbase) + (voff)[_i]), (LAS unsigned*)(lds + (bufoff) + ldsw + _i * 8192), 16, 0, 0); } while (0)
; #define PG8_LDA(dst, b, h) do { _Pragma("unroll") for (int m = 0; m < 4; ++m) _Pragma("unroll") for (int k = 0; k < 2; ++k) dst[m][k] = *(const LAS bf16x8*)(lds + PG8_SA(b, h) + aoff + m * 2048 + k * 1024); } while (0)
; #define PG8_LDB(dst, b, h) do { _Pragma("unroll") for (int n = 0; n < 2; ++n) _Pragma("unroll") for (int k = 0; k < 2; ++k) dst[n][k] = *(const LAS bf16x8*)(lds + PG8_SB(b, h) + boff + n * 2048 + k * 1024); } while (0)
; #define PG8_MMA(ai, bj, At, Bt) do { __builtin_amdgcn_s_setprio(1); _Pragma("unroll") for (int m = 0; m < 4; ++m) _Pragma("unroll") for (int n = 0; n < 2; ++n) _Pragma("unroll") for (int k = 0; k < 2; ++k) \
;         acc[ai][bj][m][n] = __builtin_amdgcn_mfma_f32_16x16x32_bf16(Bt[n][k], At[m][k], acc[ai][bj][m][n], 0, 0, 0); __builtin_amdgcn_s_setprio(0); } while (0)
; #define PG8_WAIT_V(n) asm volatile("s_waitcnt vmcnt(" #n ")" ::: "memory")
; #define PG8_WAIT_L(n) asm volatile("s_waitcnt lgkmcnt(" #n ")" ::: "memory")
; template <class Epi>
; DI void gemm_phase(LAS unsigned char* lds, const int wid, const Gemm g, const Order& S, const Epi& E) {
;     ...
;         const char* nA = has_next ? (const char*)(g.A + (size_t)nxt.g * g.gsA + (size_t)nxt.pm * BM * g.lda) : cA;
;         const char* nB = has_next ? (const char*)(g.Bt + (size_t)nxt.g * g.gsB + (size_t)nxt.pn * BM * g.ldb) : cB;
;         for (int t = 0; t < nt; t += 2) {
;             const bool last = (t == nt - 2);
;             const char* a1 = cA + (size_t)(t + 1) * kstep;
;             const char* a2 = last ? nA : cA + (size_t)(t + 2) * kstep; const char* b2 = last ? nB : cB + (size_t)(t + 2) * kstep;
;             const char* a3 = a2 + kstep; const char* b3 = b2 + kstep;
;             PG8_LDB(B0, 0, 0); PG8_LDB(B1, 0, 1); PG8_SCHED; PG8_LDA(At, 0, 0); PG8_STAGE(PG8_SA(1, 1), a1 + hstepA, voffA);
;             PG8_WAIT_V(8); PG8_WAIT_L(0); PG8_BAR; PG8_MMA(0, 0, At, B0); PG8_MMA(0, 1, At, B1); PG8_BAR; PG8_SCHED;
;             PG8_LDA(At, 0, 1); PG8_STAGE(PG8_SB(0, 0), b2, voffB); PG8_STAGE(PG8_SB(0, 1), b2 + hstepB, voffB); PG8_STAGE(PG8_SA(0, 0), a2, voffA);
.LBB0_789:
	s_lshl_b64 s[42:43], s[36:37], 18
	s_add_u32 s29, s8, s42
	s_addc_u32 s37, s9, s43
	s_ashr_i32 s39, s38, 31
	s_lshl_b64 s[42:43], s[38:39], 18
	s_add_u32 s42, s29, s42
	s_addc_u32 s43, s37, s43
	s_and_b64 s[12:13], s[12:13], exec
	s_cselect_b32 s29, s43, s47
	s_cselect_b32 s37, s42, s46
	s_add_u32 s39, s46, 0x100
	v_mov_b32_e32 v0, 0
	s_addc_u32 s61, s47, 0
	s_mov_b32 s62, -2
	ds_read_b128 v[148:151], v145
	ds_read_b128 v[152:155], v145 offset:1024
	ds_read_b128 v[156:159], v145 offset:2048
	ds_read_b128 v[160:163], v145 offset:3072
	ds_read_b128 v[164:167], v146
	ds_read_b128 v[168:171], v146 offset:1024
	ds_read_b128 v[172:175], v146 offset:2048
	ds_read_b128 v[176:179], v146 offset:3072
	s_add_u32 s12, s44, 0x100
	s_addc_u32 s13, s45, 0
	s_cmp_eq_u32 s62, 4
	s_cselect_b32 s49, s41, s13
	s_cselect_b32 s48, s40, s12
	s_cselect_b32 s47, s29, s61
	s_cselect_b32 s46, s37, s39
	v_lshl_add_u64 v[212:213], s[44:45], 0, v[136:137]
	s_add_i32 m0, s21, 0xc000
	ds_read_b128 v[180:183], v147
	ds_read_b128 v[184:187], v147 offset:1024
	ds_read_b128 v[188:191], v147 offset:2048
	ds_read_b128 v[192:195], v147 offset:3072
	ds_read_b128 v[196:199], v147 offset:4096
	ds_read_b128 v[200:203], v147 offset:5120
	ds_read_b128 v[204:207], v147 offset:6144
	ds_read_b128 v[208:211], v147 offset:7168
	global_load_lds_dwordx4 v[212:213], off
	v_lshl_add_u64 v[212:213], s[44:45], 0, v[138:139]
	s_add_i32 m0, s21, 0xe000
	s_nop 0
	global_load_lds_dwordx4 v[212:213], off
	s_waitcnt vmcnt(8)
	s_waitcnt lgkmcnt(0)
	s_barrier
	s_setprio 1
	s_waitcnt lgkmcnt(0)
	v_mfma_f32_16x16x32_bf16 v[124:127], v[148:151], v[180:183], 0
	v_mfma_f32_16x16x32_bf16 v[120:123], v[156:159], v[180:183], 0
	v_mfma_f32_16x16x32_bf16 v[116:119], v[148:151], v[188:191], 0
	v_mfma_f32_16x16x32_bf16 v[112:115], v[156:159], v[188:191], 0
	v_mfma_f32_16x16x32_bf16 v[100:103], v[148:151], v[196:199], 0
	v_mfma_f32_16x16x32_bf16 v[96:99], v[156:159], v[196:199], 0
	v_mfma_f32_16x16x32_bf16 v[84:87], v[148:151], v[204:207], 0
	v_mfma_f32_16x16x32_bf16 v[80:83], v[156:159], v[204:207], 0
	v_mfma_f32_16x16x32_bf16 v[124:127], v[152:155], v[184:187], v[124:127]
	v_mfma_f32_16x16x32_bf16 v[120:123], v[160:163], v[184:187], v[120:123]
	v_mfma_f32_16x16x32_bf16 v[116:119], v[152:155], v[192:195], v[116:119]
	v_mfma_f32_16x16x32_bf16 v[112:115], v[160:163], v[192:195], v[112:115]
	v_mfma_f32_16x16x32_bf16 v[100:103], v[152:155], v[200:203], v[100:103]
	v_mfma_f32_16x16x32_bf16 v[96:99], v[160:163], v[200:203], v[96:99]
	v_mfma_f32_16x16x32_bf16 v[84:87], v[152:155], v[208:211], v[84:87]
	v_mfma_f32_16x16x32_bf16 v[80:83], v[160:163], v[208:211], v[80:83]
	s_setprio 0
	s_setprio 1
	v_mfma_f32_16x16x32_bf16 v[108:111], v[164:167], v[180:183], 0
	v_mfma_f32_16x16x32_bf16 v[104:107], v[172:175], v[180:183], 0
	v_mfma_f32_16x16x32_bf16 v[92:95], v[164:167], v[188:191], 0
	v_mfma_f32_16x16x32_bf16 v[88:91], v[172:175], v[188:191], 0
	v_mfma_f32_16x16x32_bf16 v[76:79], v[164:167], v[196:199], 0
	v_mfma_f32_16x16x32_bf16 v[72:75], v[172:175], v[196:199], 0
	v_mfma_f32_16x16x32_bf16 v[68:71], v[164:167], v[204:207], 0
	v_mfma_f32_16x16x32_bf16 v[64:67], v[172:175], v[204:207], 0
	v_mfma_f32_16x16x32_bf16 v[108:111], v[168:171], v[184:187], v[108:111]
	v_mfma_f32_16x16x32_bf16 v[104:107], v[176:179], v[184:187], v[104:107]
	v_mfma_f32_16x16x32_bf16 v[92:95], v[168:171], v[192:195], v[92:95]
	v_mfma_f32_16x16x32_bf16 v[88:91], v[176:179], v[192:195], v[88:91]
	v_mfma_f32_16x16x32_bf16 v[76:79], v[168:171], v[200:203], v[76:79]
	v_mfma_f32_16x16x32_bf16 v[72:75], v[176:179], v[200:203], v[72:75]
	v_mfma_f32_16x16x32_bf16 v[68:71], v[168:171], v[208:211], v[68:71]
	v_mfma_f32_16x16x32_bf16 v[64:67], v[176:179], v[208:211], v[64:67]
	s_setprio 0
	s_barrier
	s_add_i32 s44, s57, s94
	v_lshl_add_u64 v[212:213], s[46:47], 0, v[132:133]
	s_mov_b32 m0, s44
	ds_read_b128 v[180:183], v147 offset:16384
	ds_read_b128 v[184:187], v147 offset:17408
	ds_read_b128 v[188:191], v147 offset:18432
	ds_read_b128 v[192:195], v147 offset:19456
	ds_read_b128 v[196:199], v147 offset:20480
	ds_read_b128 v[200:203], v147 offset:21504
	ds_read_b128 v[204:207], v147 offset:22528
	ds_read_b128 v[208:211], v147 offset:23552
	global_load_lds_dwordx4 v[212:213], off
	s_add_i32 m0, s44, 0x2000
	s_add_u32 s44, s46, 0x20000
	v_lshl_add_u64 v[214:215], s[46:47], 0, v[128:129]
	s_addc_u32 s45, s47, 0
	s_add_i32 s63, s58, s94
	global_load_lds_dwordx4 v[214:215], off
	v_lshl_add_u64 v[216:217], s[44:45], 0, v[132:133]
	s_mov_b32 m0, s63
	v_lshl_add_u64 v[218:219], s[48:49], 0, v[130:131]
	global_load_lds_dwordx4 v[216:217], off
	v_lshl_add_u64 v[216:217], s[44:45], 0, v[128:129]
	s_add_i32 m0, s63, 0x2000
	s_nop 0
	global_load_lds_dwordx4 v[216:217], off
	v_lshl_add_u64 v[216:217], s[48:49], 0, v[134:135]
	s_mov_b32 m0, s21
	s_nop 0
	global_load_lds_dwordx4 v[216:217], off
	s_mov_b32 m0, s25
	s_nop 0
	global_load_lds_dwordx4 v[218:219], off
	s_waitcnt vmcnt(8)
	s_waitcnt lgkmcnt(0)
	s_barrier
; #define PG8_STAGE(bufoff, gbase, voff) do { _Pragma("unroll") for (int _i = 0; _i < 2; ++_i) \
;         __builtin_amdgcn_global_load_lds((const unsigned*)((const char*)(gbase) + (voff)[_i]), (LAS unsigned*)(lds + (bufoff) + ldsw + _i * 8192), 16, 0, 0); } while (0)
; #define PG8_LDA(dst, b, h) do { _Pragma("unroll") for (int m = 0; m < 4; ++m) _Pragma("unroll") for (int k = 0; k < 2; ++k) dst[m][k] = *(const LAS bf16x8*)(lds + PG8_SA(b, h) + aoff + m * 2048 + k * 1024); } while (0)
; #define PG8_LDB(dst, b, h) do { _Pragma("unroll") for (int n = 0; n < 2; ++n) _Pragma("unroll") for (int k = 0; k < 2; ++k) dst[n][k] = *(const LAS bf16x8*)(lds + PG8_SB(b, h) + boff + n * 2048 + k * 1024); } while (0)
; #define PG8_MMA(ai, bj, At, Bt) do { __builtin_amdgcn_s_setprio(1); _Pragma("unroll") for (int m = 0; m < 4; ++m) _Pragma("unroll") for (int n = 0; n < 2; ++n) _Pragma("unroll") for (int k = 0; k < 2; ++k) \
;         acc[ai][bj][m][n] = __builtin_amdgcn_mfma_f32_16x16x32_bf16(Bt[n][k], At[m][k], acc[ai][bj][m][n], 0, 0, 0); __builtin_amdgcn_s_setprio(0); } while (0)
; #define PG8_WAIT_V(n) asm volatile("s_waitcnt vmcnt(" #n ")" ::: "memory")
; #define PG8_WAIT_L(n) asm volatile("s_waitcnt lgkmcnt(" #n ")" ::: "memory")
; #define PG8_BAR __builtin_amdgcn_s_barrier()
; #define PG8_SCHED __builtin_amdgcn_sched_barrier(0)
; template <class Epi>
; DI void gemm_phase(LAS unsigned char* lds, const int wid, const Gemm g, const Order& S, const Epi& E) {
;     ...
;             PG8_WAIT_V(8); PG8_WAIT_L(0); PG8_BAR; PG8_MMA(1, 0, At, B0); PG8_MMA(1, 1, At, B1); PG8_BAR; PG8_SCHED;
;             PG8_LDB(B0, 1, 0); PG8_LDB(B1, 1, 1); PG8_SCHED; PG8_LDA(At, 1, 0); PG8_STAGE(PG8_SA(0, 1), a2 + hstepA, voffA);
;             PG8_WAIT_V(8); PG8_WAIT_L(0); PG8_BAR; PG8_MMA(0, 0, At, B0); PG8_MMA(0, 1, At, B1); PG8_BAR; PG8_SCHED;
	s_setprio 1
	s_waitcnt lgkmcnt(0)
	v_mfma_f32_16x16x32_bf16 v[60:63], v[148:151], v[180:183], 0
	v_mfma_f32_16x16x32_bf16 v[56:59], v[156:159], v[180:183], 0
	v_mfma_f32_16x16x32_bf16 v[52:55], v[148:151], v[188:191], 0
	v_mfma_f32_16x16x32_bf16 v[48:51], v[156:159], v[188:191], 0
	v_mfma_f32_16x16x32_bf16 v[36:39], v[148:151], v[196:199], 0
	v_mfma_f32_16x16x32_bf16 v[32:35], v[156:159], v[196:199], 0
	v_mfma_f32_16x16x32_bf16 v[20:23], v[148:151], v[204:207], 0
	v_mfma_f32_16x16x32_bf16 v[16:19], v[156:159], v[204:207], 0
	v_mfma_f32_16x16x32_bf16 v[60:63], v[152:155], v[184:187], v[60:63]
	v_mfma_f32_16x16x32_bf16 v[56:59], v[160:163], v[184:187], v[56:59]
	v_mfma_f32_16x16x32_bf16 v[52:55], v[152:155], v[192:195], v[52:55]
	v_mfma_f32_16x16x32_bf16 v[48:51], v[160:163], v[192:195], v[48:51]
	v_mfma_f32_16x16x32_bf16 v[36:39], v[152:155], v[200:203], v[36:39]
	v_mfma_f32_16x16x32_bf16 v[32:35], v[160:163], v[200:203], v[32:35]
	v_mfma_f32_16x16x32_bf16 v[20:23], v[152:155], v[208:211], v[20:23]
	v_mfma_f32_16x16x32_bf16 v[16:19], v[160:163], v[208:211], v[16:19]
	s_setprio 0
	s_setprio 1
	v_mfma_f32_16x16x32_bf16 v[44:47], v[164:167], v[180:183], 0
	v_mfma_f32_16x16x32_bf16 v[40:43], v[172:175], v[180:183], 0
	v_mfma_f32_16x16x32_bf16 v[28:31], v[164:167], v[188:191], 0
	v_mfma_f32_16x16x32_bf16 v[24:27], v[172:175], v[188:191], 0
	v_mfma_f32_16x16x32_bf16 v[12:15], v[164:167], v[196:199], 0
	v_mfma_f32_16x16x32_bf16 v[8:11], v[172:175], v[196:199], 0
	v_mfma_f32_16x16x32_bf16 v[4:7], v[164:167], v[204:207], 0
	v_mfma_f32_16x16x32_bf16 v[0:3], v[172:175], v[204:207], 0
	v_mfma_f32_16x16x32_bf16 v[44:47], v[168:171], v[184:187], v[44:47]
	v_mfma_f32_16x16x32_bf16 v[40:43], v[176:179], v[184:187], v[40:43]
	v_mfma_f32_16x16x32_bf16 v[28:31], v[168:171], v[192:195], v[28:31]
	v_mfma_f32_16x16x32_bf16 v[24:27], v[176:179], v[192:195], v[24:27]
	v_mfma_f32_16x16x32_bf16 v[12:15], v[168:171], v[200:203], v[12:15]
	v_mfma_f32_16x16x32_bf16 v[8:11], v[176:179], v[200:203], v[8:11]
	v_mfma_f32_16x16x32_bf16 v[4:7], v[168:171], v[208:211], v[4:7]
	v_mfma_f32_16x16x32_bf16 v[0:3], v[176:179], v[208:211], v[0:3]
	s_setprio 0
	s_barrier
	s_add_i32 s63, 0, 0x18000
	s_add_i32 s64, 0, 0x1c000
	v_add_u32_e32 v160, s63, v144
	v_add_u32_e32 v176, s64, v144
	ds_read_b128 v[148:151], v160
	ds_read_b128 v[152:155], v160 offset:1024
	ds_read_b128 v[156:159], v160 offset:2048
	ds_read_b128 v[160:163], v160 offset:3072
	ds_read_b128 v[164:167], v176
	ds_read_b128 v[168:171], v176 offset:1024
	ds_read_b128 v[172:175], v176 offset:2048
	ds_read_b128 v[176:179], v176 offset:3072
	s_add_u32 s44, s48, 0x30000
	s_addc_u32 s45, s49, 0
	s_mov_b32 m0, s26
	v_lshl_add_u64 v[220:221], s[44:45], 0, v[134:135]
	ds_read_b128 v[180:183], v147 offset:32768
	ds_read_b128 v[184:187], v147 offset:33792
	ds_read_b128 v[188:191], v147 offset:34816
	ds_read_b128 v[192:195], v147 offset:35840
	ds_read_b128 v[196:199], v147 offset:36864
	ds_read_b128 v[200:203], v147 offset:37888
	ds_read_b128 v[204:207], v147 offset:38912
	ds_read_b128 v[208:211], v147 offset:39936
	global_load_lds_dwordx4 v[220:221], off
	v_lshl_add_u64 v[220:221], s[44:45], 0, v[130:131]
	s_mov_b32 m0, s27
	s_nop 0
	global_load_lds_dwordx4 v[220:221], off
	s_waitcnt vmcnt(8)
	s_waitcnt lgkmcnt(0)
	s_barrier
	s_setprio 1
	s_waitcnt lgkmcnt(0)
	v_mfma_f32_16x16x32_bf16 v[124:127], v[148:151], v[180:183], v[124:127]
	v_mfma_f32_16x16x32_bf16 v[120:123], v[156:159], v[180:183], v[120:123]
	v_mfma_f32_16x16x32_bf16 v[116:119], v[148:151], v[188:191], v[116:119]
	v_mfma_f32_16x16x32_bf16 v[112:115], v[156:159], v[188:191], v[112:115]
	v_mfma_f32_16x16x32_bf16 v[100:103], v[148:151], v[196:199], v[100:103]
	v_mfma_f32_16x16x32_bf16 v[96:99], v[156:159], v[196:199], v[96:99]
	v_mfma_f32_16x16x32_bf16 v[84:87], v[148:151], v[204:207], v[84:87]
	v_mfma_f32_16x16x32_bf16 v[80:83], v[156:159], v[204:207], v[80:83]
	v_mfma_f32_16x16x32_bf16 v[124:127], v[152:155], v[184:187], v[124:127]
	v_mfma_f32_16x16x32_bf16 v[120:123], v[160:163], v[184:187], v[120:123]
	v_mfma_f32_16x16x32_bf16 v[116:119], v[152:155], v[192:195], v[116:119]
	v_mfma_f32_16x16x32_bf16 v[112:115], v[160:163], v[192:195], v[112:115]
	v_mfma_f32_16x16x32_bf16 v[100:103], v[152:155], v[200:203], v[100:103]
	v_mfma_f32_16x16x32_bf16 v[96:99], v[160:163], v[200:203], v[96:99]
	v_mfma_f32_16x16x32_bf16 v[84:87], v[152:155], v[208:211], v[84:87]
	v_mfma_f32_16x16x32_bf16 v[80:83], v[160:163], v[208:211], v[80:83]
	s_setprio 0
	s_setprio 1
	v_mfma_f32_16x16x32_bf16 v[108:111], v[164:167], v[180:183], v[108:111]
	v_mfma_f32_16x16x32_bf16 v[104:107], v[172:175], v[180:183], v[104:107]
	v_mfma_f32_16x16x32_bf16 v[92:95], v[164:167], v[188:191], v[92:95]
	v_mfma_f32_16x16x32_bf16 v[88:91], v[172:175], v[188:191], v[88:91]
	v_mfma_f32_16x16x32_bf16 v[76:79], v[164:167], v[196:199], v[76:79]
	v_mfma_f32_16x16x32_bf16 v[72:75], v[172:175], v[196:199], v[72:75]
	v_mfma_f32_16x16x32_bf16 v[68:71], v[164:167], v[204:207], v[68:71]
	v_mfma_f32_16x16x32_bf16 v[64:67], v[172:175], v[204:207], v[64:67]
	v_mfma_f32_16x16x32_bf16 v[108:111], v[168:171], v[184:187], v[108:111]
	v_mfma_f32_16x16x32_bf16 v[104:107], v[176:179], v[184:187], v[104:107]
	v_mfma_f32_16x16x32_bf16 v[92:95], v[168:171], v[192:195], v[92:95]
	v_mfma_f32_16x16x32_bf16 v[88:91], v[176:179], v[192:195], v[88:91]
	v_mfma_f32_16x16x32_bf16 v[76:79], v[168:171], v[200:203], v[76:79]
	v_mfma_f32_16x16x32_bf16 v[72:75], v[176:179], v[200:203], v[72:75]
	v_mfma_f32_16x16x32_bf16 v[68:71], v[168:171], v[208:211], v[68:71]
	v_mfma_f32_16x16x32_bf16 v[64:67], v[176:179], v[208:211], v[64:67]
	s_setprio 0
	s_barrier
; #define PG8_STAGE(bufoff, gbase, voff) do { _Pragma("unroll") for (int _i = 0; _i < 2; ++_i) \
;         __builtin_amdgcn_global_load_lds((const unsigned*)((const char*)(gbase) + (voff)[_i]), (LAS unsigned*)(lds + (bufoff) + ldsw + _i * 8192), 16, 0, 0); } while (0)
; #define PG8_LDA(dst, b, h) do { _Pragma("unroll") for (int m = 0; m < 4; ++m) _Pragma("unroll") for (int k = 0; k < 2; ++k) dst[m][k] = *(const LAS bf16x8*)(lds + PG8_SA(b, h) + aoff + m * 2048 + k * 1024); } while (0)
; #define PG8_MMA(ai, bj, At, Bt) do { __builtin_amdgcn_s_setprio(1); _Pragma("unroll") for (int m = 0; m < 4; ++m) _Pragma("unroll") for (int n = 0; n < 2; ++n) _Pragma("unroll") for (int k = 0; k < 2; ++k) \
;         acc[ai][bj][m][n] = __builtin_amdgcn_mfma_f32_16x16x32_bf16(Bt[n][k], At[m][k], acc[ai][bj][m][n], 0, 0, 0); __builtin_amdgcn_s_setprio(0); } while (0)
; #define PG8_WAIT_V(n) asm volatile("s_waitcnt vmcnt(" #n ")" ::: "memory")
; #define PG8_WAIT_L(n) asm volatile("s_waitcnt lgkmcnt(" #n ")" ::: "memory")
; #define PG8_BAR __builtin_amdgcn_s_barrier()
; #define PG8_SCHED __builtin_amdgcn_sched_barrier(0)
; template <class Epi>
; DI void gemm_phase(LAS unsigned char* lds, const int wid, const Gemm g, const Order& S, const Epi& E) {
;     ...
;         for (int t = 0; t < nt; t += 2) {
;     ...
;             PG8_LDA(At, 1, 1); PG8_STAGE(PG8_SB(1, 0), b3, voffB); PG8_STAGE(PG8_SB(1, 1), b3 + hstepB, voffB); PG8_STAGE(PG8_SA(1, 0), a3, voffA);
;             PG8_WAIT_V(8); PG8_WAIT_L(0); PG8_BAR; PG8_MMA(1, 0, At, B0); PG8_MMA(1, 1, At, B1); PG8_BAR; PG8_SCHED;
	s_add_i32 s44, s63, s94
	v_lshl_add_u64 v[212:213], v[212:213], 0, s[30:31]
	s_mov_b32 m0, s44
	ds_read_b128 v[180:183], v147 offset:49152
	ds_read_b128 v[184:187], v147 offset:50176
	ds_read_b128 v[188:191], v147 offset:51200
	ds_read_b128 v[192:195], v147 offset:52224
	ds_read_b128 v[196:199], v147 offset:53248
	ds_read_b128 v[200:203], v147 offset:54272
	ds_read_b128 v[204:207], v147 offset:55296
	ds_read_b128 v[208:211], v147 offset:56320
	global_load_lds_dwordx4 v[212:213], off
	s_add_i32 m0, s44, 0x2000
	s_add_u32 s44, s46, 0x20080
	v_lshl_add_u64 v[212:213], v[214:215], 0, s[30:31]
	s_addc_u32 s45, s47, 0
	s_add_i32 s46, s64, s94
	global_load_lds_dwordx4 v[212:213], off
	v_lshl_add_u64 v[212:213], s[44:45], 0, v[132:133]
	s_mov_b32 m0, s46
	s_nop 0
	global_load_lds_dwordx4 v[212:213], off
	v_lshl_add_u64 v[212:213], s[44:45], 0, v[128:129]
	s_add_i32 m0, s46, 0x2000
	s_nop 0
	global_load_lds_dwordx4 v[212:213], off
	v_lshl_add_u64 v[212:213], v[216:217], 0, s[30:31]
	s_mov_b32 m0, s52
	s_nop 0
	global_load_lds_dwordx4 v[212:213], off
	v_lshl_add_u64 v[212:213], v[218:219], 0, s[30:31]
	s_mov_b32 m0, s53
	s_nop 0
	global_load_lds_dwordx4 v[212:213], off
	s_waitcnt vmcnt(8)
	s_waitcnt lgkmcnt(0)
	s_barrier
	s_setprio 1
	s_waitcnt lgkmcnt(0)
	v_mfma_f32_16x16x32_bf16 v[60:63], v[148:151], v[180:183], v[60:63]
	v_mfma_f32_16x16x32_bf16 v[56:59], v[156:159], v[180:183], v[56:59]
	v_mfma_f32_16x16x32_bf16 v[52:55], v[148:151], v[188:191], v[52:55]
	v_mfma_f32_16x16x32_bf16 v[48:51], v[156:159], v[188:191], v[48:51]
	v_mfma_f32_16x16x32_bf16 v[36:39], v[148:151], v[196:199], v[36:39]
	v_mfma_f32_16x16x32_bf16 v[32:35], v[156:159], v[196:199], v[32:35]
	v_mfma_f32_16x16x32_bf16 v[20:23], v[148:151], v[204:207], v[20:23]
	v_mfma_f32_16x16x32_bf16 v[16:19], v[156:159], v[204:207], v[16:19]
	v_mfma_f32_16x16x32_bf16 v[60:63], v[152:155], v[184:187], v[60:63]
	v_mfma_f32_16x16x32_bf16 v[56:59], v[160:163], v[184:187], v[56:59]
	v_mfma_f32_16x16x32_bf16 v[52:55], v[152:155], v[192:195], v[52:55]
	v_mfma_f32_16x16x32_bf16 v[48:51], v[160:163], v[192:195], v[48:51]
	v_mfma_f32_16x16x32_bf16 v[36:39], v[152:155], v[200:203], v[36:39]
	v_mfma_f32_16x16x32_bf16 v[32:35], v[160:163], v[200:203], v[32:35]
	v_mfma_f32_16x16x32_bf16 v[20:23], v[152:155], v[208:211], v[20:23]
	v_mfma_f32_16x16x32_bf16 v[16:19], v[160:163], v[208:211], v[16:19]
	s_setprio 0
	s_setprio 1
	v_mfma_f32_16x16x32_bf16 v[44:47], v[164:167], v[180:183], v[44:47]
	v_mfma_f32_16x16x32_bf16 v[40:43], v[172:175], v[180:183], v[40:43]
	v_mfma_f32_16x16x32_bf16 v[28:31], v[164:167], v[188:191], v[28:31]
	v_mfma_f32_16x16x32_bf16 v[24:27], v[172:175], v[188:191], v[24:27]
	v_mfma_f32_16x16x32_bf16 v[12:15], v[164:167], v[196:199], v[12:15]
	v_mfma_f32_16x16x32_bf16 v[8:11], v[172:175], v[196:199], v[8:11]
	v_mfma_f32_16x16x32_bf16 v[4:7], v[164:167], v[204:207], v[4:7]
	v_mfma_f32_16x16x32_bf16 v[0:3], v[172:175], v[204:207], v[0:3]
	v_mfma_f32_16x16x32_bf16 v[44:47], v[168:171], v[184:187], v[44:47]
	v_mfma_f32_16x16x32_bf16 v[40:43], v[176:179], v[184:187], v[40:43]
	v_mfma_f32_16x16x32_bf16 v[28:31], v[168:171], v[192:195], v[28:31]
	v_mfma_f32_16x16x32_bf16 v[24:27], v[176:179], v[192:195], v[24:27]
	v_mfma_f32_16x16x32_bf16 v[12:15], v[168:171], v[200:203], v[12:15]
	v_mfma_f32_16x16x32_bf16 v[8:11], v[176:179], v[200:203], v[8:11]
	v_mfma_f32_16x16x32_bf16 v[4:7], v[168:171], v[208:211], v[4:7]
	v_mfma_f32_16x16x32_bf16 v[0:3], v[176:179], v[208:211], v[0:3]
	s_setprio 0
	s_barrier
	s_add_i32 s62, s62, 2
	s_add_u32 s39, s39, 0x100
	s_addc_u32 s61, s61, 0
	s_cmp_gt_u32 s62, 5
	s_mov_b64 s[44:45], s[12:13]
	s_cbranch_scc0 .LBB0_790
	s_branch .Lpeel_exit_3

; #define PG8_BAR __builtin_amdgcn_s_barrier()
; template <class Epi>
; DI void gemm_phase(LAS unsigned char* lds, const int wid, const Gemm g, const Order& S, const Epi& E) {
;     ...
;         if (wr == 0) PG8_BAR;
.Lpeel_exit_3:
	s_and_b64 vcc, exec, s[34:35]
	s_cbranch_vccz .LBB0_793
	s_barrier

; #define PG8_STAGE(bufoff, gbase, voff) do { _Pragma("unroll") for (int _i = 0; _i < 2; ++_i) \
;         __builtin_amdgcn_global_load_lds((const unsigned*)((const char*)(gbase) + (voff)[_i]), (LAS unsigned*)(lds + (bufoff) + ldsw + _i * 8192), 16, 0, 0); } while (0)
; #define PG8_LDA(dst, b, h) do { _Pragma("unroll") for (int m = 0; m < 4; ++m) _Pragma("unroll") for (int k = 0; k < 2; ++k) dst[m][k] = *(const LAS bf16x8*)(lds + PG8_SA(b, h) + aoff + m * 2048 + k * 1024); } while (0)
; #define PG8_LDB(dst, b, h) do { _Pragma("unroll") for (int n = 0; n < 2; ++n) _Pragma("unroll") for (int k = 0; k < 2; ++k) dst[n][k] = *(const LAS bf16x8*)(lds + PG8_SB(b, h) + boff + n * 2048 + k * 1024); } while (0)
; #define PG8_MMA(ai, bj, At, Bt) do { __builtin_amdgcn_s_setprio(1); _Pragma("unroll") for (int m = 0; m < 4; ++m) _Pragma("unroll") for (int n = 0; n < 2; ++n) _Pragma("unroll") for (int k = 0; k < 2; ++k) \
;         acc[ai][bj][m][n] = __builtin_amdgcn_mfma_f32_16x16x32_bf16(Bt[n][k], At[m][k], acc[ai][bj][m][n], 0, 0, 0); __builtin_amdgcn_s_setprio(0); } while (0)
; #define PG8_WAIT_V(n) asm volatile("s_waitcnt vmcnt(" #n ")" ::: "memory")
; #define PG8_WAIT_L(n) asm volatile("s_waitcnt lgkmcnt(" #n ")" ::: "memory")
; #define PG8_BAR __builtin_amdgcn_s_barrier()
; template <class Epi>
; DI void gemm_phase(LAS unsigned char* lds, const int wid, const Gemm g, const Order& S, const Epi& E) {
;     ...
;             const bool last = (t == nt - 2);
;             const char* a1 = cA + (size_t)(t + 1) * kstep;
;             const char* a2 = last ? nA : cA + (size_t)(t + 2) * kstep; const char* b2 = last ? nB : cB + (size_t)(t + 2) * kstep;
;             const char* a3 = a2 + kstep; const char* b3 = b2 + kstep;
;             PG8_LDB(B0, 0, 0); PG8_LDB(B1, 0, 1); PG8_SCHED; PG8_LDA(At, 0, 0); PG8_STAGE(PG8_SA(1, 1), a1 + hstepA, voffA);
;             PG8_WAIT_V(8); PG8_WAIT_L(0); PG8_BAR; PG8_MMA(0, 0, At, B0); PG8_MMA(0, 1, At, B1); PG8_BAR; PG8_SCHED;
;             PG8_LDA(At, 0, 1); PG8_STAGE(PG8_SB(0, 0), b2, voffB); PG8_STAGE(PG8_SB(0, 1), b2 + hstepB, voffB); PG8_STAGE(PG8_SA(0, 0), a2, voffA);
;     ...
;         for (int a = 0; a < 2; ++a)
; #pragma unroll
;             for (int b = 0; b < 2; ++b)
; #pragma unroll
;                 for (int m = 0; m < 4; ++m)
; #pragma unroll
;                     for (int n = 0; n < 2; ++n) acc[a][b][m][n] = (f32x4){0.f, 0.f, 0.f, 0.f};
.LBB0_988:
	s_add_u32 s54, s36, 0x100
	v_mov_b32_e32 v0, 0
	s_addc_u32 s55, s37, 0
	s_mov_b32 s56, -2
	ds_read_b128 v[152:155], v149
	ds_read_b128 v[156:159], v149 offset:1024
	ds_read_b128 v[160:163], v149 offset:2048
	ds_read_b128 v[164:167], v149 offset:3072
	ds_read_b128 v[168:171], v150
	ds_read_b128 v[172:175], v150 offset:1024
	ds_read_b128 v[176:179], v150 offset:2048
	ds_read_b128 v[180:183], v150 offset:3072
	s_add_u32 s36, s34, 0x100
	s_addc_u32 s37, s35, 0
	s_cmp_eq_u32 s56, 8
	s_cselect_b32 s41, s11, s37
	s_cselect_b32 s40, s10, s36
	s_cselect_b32 s39, s31, s55
	s_cselect_b32 s38, s30, s54
	v_lshl_add_u64 v[146:147], s[34:35], 0, v[138:139]
	s_add_i32 m0, s25, 0xc000
	ds_read_b128 v[184:187], v151
	ds_read_b128 v[188:191], v151 offset:1024
	ds_read_b128 v[192:195], v151 offset:2048
	ds_read_b128 v[196:199], v151 offset:3072
	ds_read_b128 v[200:203], v151 offset:4096
	ds_read_b128 v[204:207], v151 offset:5120
	ds_read_b128 v[208:211], v151 offset:6144
	ds_read_b128 v[212:215], v151 offset:7168
	global_load_lds_dwordx4 v[146:147], off
	v_lshl_add_u64 v[146:147], s[34:35], 0, v[140:141]
	s_add_i32 m0, s25, 0xe000
	s_nop 0
	global_load_lds_dwordx4 v[146:147], off
	s_waitcnt vmcnt(8)
	s_waitcnt lgkmcnt(0)
	s_barrier
	s_setprio 1
	s_waitcnt lgkmcnt(0)
	v_mfma_f32_16x16x32_bf16 v[124:127], v[152:155], v[184:187], 0
	v_mfma_f32_16x16x32_bf16 v[120:123], v[160:163], v[184:187], 0
	v_mfma_f32_16x16x32_bf16 v[108:111], v[152:155], v[192:195], 0
	v_mfma_f32_16x16x32_bf16 v[104:107], v[160:163], v[192:195], 0
	v_mfma_f32_16x16x32_bf16 v[92:95], v[152:155], v[200:203], 0
	v_mfma_f32_16x16x32_bf16 v[88:91], v[160:163], v[200:203], 0
	v_mfma_f32_16x16x32_bf16 v[76:79], v[152:155], v[208:211], 0
	v_mfma_f32_16x16x32_bf16 v[72:75], v[160:163], v[208:211], 0
	v_mfma_f32_16x16x32_bf16 v[124:127], v[156:159], v[188:191], v[124:127]
	v_mfma_f32_16x16x32_bf16 v[120:123], v[164:167], v[188:191], v[120:123]
	v_mfma_f32_16x16x32_bf16 v[108:111], v[156:159], v[196:199], v[108:111]
	v_mfma_f32_16x16x32_bf16 v[104:107], v[164:167], v[196:199], v[104:107]
	v_mfma_f32_16x16x32_bf16 v[92:95], v[156:159], v[204:207], v[92:95]
	v_mfma_f32_16x16x32_bf16 v[88:91], v[164:167], v[204:207], v[88:91]
	v_mfma_f32_16x16x32_bf16 v[76:79], v[156:159], v[212:215], v[76:79]
	v_mfma_f32_16x16x32_bf16 v[72:75], v[164:167], v[212:215], v[72:75]
	s_setprio 0
	s_setprio 1
	v_mfma_f32_16x16x32_bf16 v[116:119], v[168:171], v[184:187], 0
	v_mfma_f32_16x16x32_bf16 v[112:115], v[176:179], v[184:187], 0
	v_mfma_f32_16x16x32_bf16 v[100:103], v[168:171], v[192:195], 0
	v_mfma_f32_16x16x32_bf16 v[96:99], v[176:179], v[192:195], 0
	v_mfma_f32_16x16x32_bf16 v[84:87], v[168:171], v[200:203], 0
	v_mfma_f32_16x16x32_bf16 v[80:83], v[176:179], v[200:203], 0
	v_mfma_f32_16x16x32_bf16 v[68:71], v[168:171], v[208:211], 0
	v_mfma_f32_16x16x32_bf16 v[64:67], v[176:179], v[208:211], 0
	v_mfma_f32_16x16x32_bf16 v[116:119], v[172:175], v[188:191], v[116:119]
	v_mfma_f32_16x16x32_bf16 v[112:115], v[180:183], v[188:191], v[112:115]
	v_mfma_f32_16x16x32_bf16 v[100:103], v[172:175], v[196:199], v[100:103]
	v_mfma_f32_16x16x32_bf16 v[96:99], v[180:183], v[196:199], v[96:99]
	v_mfma_f32_16x16x32_bf16 v[84:87], v[172:175], v[204:207], v[84:87]
	v_mfma_f32_16x16x32_bf16 v[80:83], v[180:183], v[204:207], v[80:83]
	v_mfma_f32_16x16x32_bf16 v[68:71], v[172:175], v[212:215], v[68:71]
	v_mfma_f32_16x16x32_bf16 v[64:67], v[180:183], v[212:215], v[64:67]
	s_setprio 0
	s_barrier
	s_add_i32 s34, s48, s94
	v_lshl_add_u64 v[146:147], s[38:39], 0, v[130:131]
	s_mov_b32 m0, s34
	ds_read_b128 v[184:187], v151 offset:16384
	ds_read_b128 v[188:191], v151 offset:17408
	ds_read_b128 v[192:195], v151 offset:18432
	ds_read_b128 v[196:199], v151 offset:19456
	ds_read_b128 v[200:203], v151 offset:20480
	ds_read_b128 v[204:207], v151 offset:21504
	ds_read_b128 v[208:211], v151 offset:22528
	ds_read_b128 v[212:215], v151 offset:23552
	global_load_lds_dwordx4 v[146:147], off
	s_add_i32 m0, s34, 0x2000
	s_add_u32 s34, s38, 0x30000
	v_lshl_add_u64 v[216:217], s[38:39], 0, v[134:135]
	s_addc_u32 s35, s39, 0
	s_add_i32 s57, s49, s94
	global_load_lds_dwordx4 v[216:217], off
	v_lshl_add_u64 v[218:219], s[34:35], 0, v[130:131]
	s_mov_b32 m0, s57
	v_lshl_add_u64 v[220:221], s[40:41], 0, v[132:133]
	global_load_lds_dwordx4 v[218:219], off
	v_lshl_add_u64 v[218:219], s[34:35], 0, v[134:135]
	s_add_i32 m0, s57, 0x2000
	s_nop 0
	global_load_lds_dwordx4 v[218:219], off
	v_lshl_add_u64 v[218:219], s[40:41], 0, v[128:129]
	s_mov_b32 m0, s25
	s_nop 0
	global_load_lds_dwordx4 v[218:219], off
	s_mov_b32 m0, s42
	s_nop 0
	global_load_lds_dwordx4 v[220:221], off
	s_waitcnt vmcnt(8)
	s_waitcnt lgkmcnt(0)
	s_barrier
; #define PG8_STAGE(bufoff, gbase, voff) do { _Pragma("unroll") for (int _i = 0; _i < 2; ++_i) \
;         __builtin_amdgcn_global_load_lds((const unsigned*)((const char*)(gbase) + (voff)[_i]), (LAS unsigned*)(lds + (bufoff) + ldsw + _i * 8192), 16, 0, 0); } while (0)
; #define PG8_LDA(dst, b, h) do { _Pragma("unroll") for (int m = 0; m < 4; ++m) _Pragma("unroll") for (int k = 0; k < 2; ++k) dst[m][k] = *(const LAS bf16x8*)(lds + PG8_SA(b, h) + aoff + m * 2048 + k * 1024); } while (0)
; #define PG8_LDB(dst, b, h) do { _Pragma("unroll") for (int n = 0; n < 2; ++n) _Pragma("unroll") for (int k = 0; k < 2; ++k) dst[n][k] = *(const LAS bf16x8*)(lds + PG8_SB(b, h) + boff + n * 2048 + k * 1024); } while (0)
; #define PG8_MMA(ai, bj, At, Bt) do { __builtin_amdgcn_s_setprio(1); _Pragma("unroll") for (int m = 0; m < 4; ++m) _Pragma("unroll") for (int n = 0; n < 2; ++n) _Pragma("unroll") for (int k = 0; k < 2; ++k) \
;         acc[ai][bj][m][n] = __builtin_amdgcn_mfma_f32_16x16x32_bf16(Bt[n][k], At[m][k], acc[ai][bj][m][n], 0, 0, 0); __builtin_amdgcn_s_setprio(0); } while (0)
; #define PG8_WAIT_V(n) asm volatile("s_waitcnt vmcnt(" #n ")" ::: "memory")
; #define PG8_WAIT_L(n) asm volatile("s_waitcnt lgkmcnt(" #n ")" ::: "memory")
; #define PG8_BAR __builtin_amdgcn_s_barrier()
; #define PG8_SCHED __builtin_amdgcn_sched_barrier(0)
; template <class Epi>
; DI void gemm_phase(LAS unsigned char* lds, const int wid, const Gemm g, const Order& S, const Epi& E) {
;     ...
;             PG8_WAIT_V(8); PG8_WAIT_L(0); PG8_BAR; PG8_MMA(1, 0, At, B0); PG8_MMA(1, 1, At, B1); PG8_BAR; PG8_SCHED;
;             PG8_LDB(B0, 1, 0); PG8_LDB(B1, 1, 1); PG8_SCHED; PG8_LDA(At, 1, 0); PG8_STAGE(PG8_SA(0, 1), a2 + hstepA, voffA);
;             PG8_WAIT_V(8); PG8_WAIT_L(0); PG8_BAR; PG8_MMA(0, 0, At, B0); PG8_MMA(0, 1, At, B1); PG8_BAR; PG8_SCHED;
	s_setprio 1
	s_waitcnt lgkmcnt(0)
	v_mfma_f32_16x16x32_bf16 v[60:63], v[152:155], v[184:187], 0
	v_mfma_f32_16x16x32_bf16 v[56:59], v[160:163], v[184:187], 0
	v_mfma_f32_16x16x32_bf16 v[44:47], v[152:155], v[192:195], 0
	v_mfma_f32_16x16x32_bf16 v[40:43], v[160:163], v[192:195], 0
	v_mfma_f32_16x16x32_bf16 v[28:31], v[152:155], v[200:203], 0
	v_mfma_f32_16x16x32_bf16 v[24:27], v[160:163], v[200:203], 0
	v_mfma_f32_16x16x32_bf16 v[12:15], v[152:155], v[208:211], 0
	v_mfma_f32_16x16x32_bf16 v[8:11], v[160:163], v[208:211], 0
	v_mfma_f32_16x16x32_bf16 v[60:63], v[156:159], v[188:191], v[60:63]
	v_mfma_f32_16x16x32_bf16 v[56:59], v[164:167], v[188:191], v[56:59]
	v_mfma_f32_16x16x32_bf16 v[44:47], v[156:159], v[196:199], v[44:47]
	v_mfma_f32_16x16x32_bf16 v[40:43], v[164:167], v[196:199], v[40:43]
	v_mfma_f32_16x16x32_bf16 v[28:31], v[156:159], v[204:207], v[28:31]
	v_mfma_f32_16x16x32_bf16 v[24:27], v[164:167], v[204:207], v[24:27]
	v_mfma_f32_16x16x32_bf16 v[12:15], v[156:159], v[212:215], v[12:15]
	v_mfma_f32_16x16x32_bf16 v[8:11], v[164:167], v[212:215], v[8:11]
	s_setprio 0
	s_setprio 1
	v_mfma_f32_16x16x32_bf16 v[52:55], v[168:171], v[184:187], 0
	v_mfma_f32_16x16x32_bf16 v[48:51], v[176:179], v[184:187], 0
	v_mfma_f32_16x16x32_bf16 v[36:39], v[168:171], v[192:195], 0
	v_mfma_f32_16x16x32_bf16 v[32:35], v[176:179], v[192:195], 0
	v_mfma_f32_16x16x32_bf16 v[20:23], v[168:171], v[200:203], 0
	v_mfma_f32_16x16x32_bf16 v[16:19], v[176:179], v[200:203], 0
	v_mfma_f32_16x16x32_bf16 v[4:7], v[168:171], v[208:211], 0
	v_mfma_f32_16x16x32_bf16 v[0:3], v[176:179], v[208:211], 0
	v_mfma_f32_16x16x32_bf16 v[52:55], v[172:175], v[188:191], v[52:55]
	v_mfma_f32_16x16x32_bf16 v[48:51], v[180:183], v[188:191], v[48:51]
	v_mfma_f32_16x16x32_bf16 v[36:39], v[172:175], v[196:199], v[36:39]
	v_mfma_f32_16x16x32_bf16 v[32:35], v[180:183], v[196:199], v[32:35]
	v_mfma_f32_16x16x32_bf16 v[20:23], v[172:175], v[204:207], v[20:23]
	v_mfma_f32_16x16x32_bf16 v[16:19], v[180:183], v[204:207], v[16:19]
	v_mfma_f32_16x16x32_bf16 v[4:7], v[172:175], v[212:215], v[4:7]
	v_mfma_f32_16x16x32_bf16 v[0:3], v[180:183], v[212:215], v[0:3]
	s_setprio 0
	s_barrier
	s_add_i32 s57, 0, 0x18000
	v_add_u32_e32 v136, s57, v148
	s_add_i32 s58, 0, 0x1c000
	ds_read_b128 v[152:155], v136
	ds_read_b128 v[156:159], v136 offset:1024
	ds_read_b128 v[160:163], v136 offset:2048
	ds_read_b128 v[164:167], v136 offset:3072
	v_add_u32_e32 v136, s58, v148
	ds_read_b128 v[168:171], v136
	ds_read_b128 v[172:175], v136 offset:1024
	ds_read_b128 v[176:179], v136 offset:2048
	ds_read_b128 v[180:183], v136 offset:3072
	s_add_u32 s34, s40, 0x30000
	s_addc_u32 s35, s41, 0
	s_mov_b32 m0, s43
	v_lshl_add_u64 v[222:223], s[34:35], 0, v[128:129]
	ds_read_b128 v[184:187], v151 offset:32768
	ds_read_b128 v[188:191], v151 offset:33792
	ds_read_b128 v[192:195], v151 offset:34816
	ds_read_b128 v[196:199], v151 offset:35840
	ds_read_b128 v[200:203], v151 offset:36864
	ds_read_b128 v[204:207], v151 offset:37888
	ds_read_b128 v[208:211], v151 offset:38912
	ds_read_b128 v[212:215], v151 offset:39936
	global_load_lds_dwordx4 v[222:223], off
	v_lshl_add_u64 v[222:223], s[34:35], 0, v[132:133]
	s_mov_b32 m0, s44
	s_nop 0
	global_load_lds_dwordx4 v[222:223], off
	s_waitcnt vmcnt(8)
	s_waitcnt lgkmcnt(0)
	s_barrier
	s_setprio 1
	s_waitcnt lgkmcnt(0)
	v_mfma_f32_16x16x32_bf16 v[124:127], v[152:155], v[184:187], v[124:127]
	v_mfma_f32_16x16x32_bf16 v[120:123], v[160:163], v[184:187], v[120:123]
	v_mfma_f32_16x16x32_bf16 v[108:111], v[152:155], v[192:195], v[108:111]
	v_mfma_f32_16x16x32_bf16 v[104:107], v[160:163], v[192:195], v[104:107]
	v_mfma_f32_16x16x32_bf16 v[92:95], v[152:155], v[200:203], v[92:95]
	v_mfma_f32_16x16x32_bf16 v[88:91], v[160:163], v[200:203], v[88:91]
	v_mfma_f32_16x16x32_bf16 v[76:79], v[152:155], v[208:211], v[76:79]
	v_mfma_f32_16x16x32_bf16 v[72:75], v[160:163], v[208:211], v[72:75]
	v_mfma_f32_16x16x32_bf16 v[124:127], v[156:159], v[188:191], v[124:127]
	v_mfma_f32_16x16x32_bf16 v[120:123], v[164:167], v[188:191], v[120:123]
	v_mfma_f32_16x16x32_bf16 v[108:111], v[156:159], v[196:199], v[108:111]
	v_mfma_f32_16x16x32_bf16 v[104:107], v[164:167], v[196:199], v[104:107]
	v_mfma_f32_16x16x32_bf16 v[92:95], v[156:159], v[204:207], v[92:95]
	v_mfma_f32_16x16x32_bf16 v[88:91], v[164:167], v[204:207], v[88:91]
	v_mfma_f32_16x16x32_bf16 v[76:79], v[156:159], v[212:215], v[76:79]
	v_mfma_f32_16x16x32_bf16 v[72:75], v[164:167], v[212:215], v[72:75]
	s_setprio 0
	s_setprio 1
	v_mfma_f32_16x16x32_bf16 v[116:119], v[168:171], v[184:187], v[116:119]
	v_mfma_f32_16x16x32_bf16 v[112:115], v[176:179], v[184:187], v[112:115]
	v_mfma_f32_16x16x32_bf16 v[100:103], v[168:171], v[192:195], v[100:103]
	v_mfma_f32_16x16x32_bf16 v[96:99], v[176:179], v[192:195], v[96:99]
	v_mfma_f32_16x16x32_bf16 v[84:87], v[168:171], v[200:203], v[84:87]
	v_mfma_f32_16x16x32_bf16 v[80:83], v[176:179], v[200:203], v[80:83]
	v_mfma_f32_16x16x32_bf16 v[68:71], v[168:171], v[208:211], v[68:71]
	v_mfma_f32_16x16x32_bf16 v[64:67], v[176:179], v[208:211], v[64:67]
	v_mfma_f32_16x16x32_bf16 v[116:119], v[172:175], v[188:191], v[116:119]
	v_mfma_f32_16x16x32_bf16 v[112:115], v[180:183], v[188:191], v[112:115]
	v_mfma_f32_16x16x32_bf16 v[100:103], v[172:175], v[196:199], v[100:103]
	v_mfma_f32_16x16x32_bf16 v[96:99], v[180:183], v[196:199], v[96:99]
	v_mfma_f32_16x16x32_bf16 v[84:87], v[172:175], v[204:207], v[84:87]
	v_mfma_f32_16x16x32_bf16 v[80:83], v[180:183], v[204:207], v[80:83]
	v_mfma_f32_16x16x32_bf16 v[68:71], v[172:175], v[212:215], v[68:71]
	v_mfma_f32_16x16x32_bf16 v[64:67], v[180:183], v[212:215], v[64:67]
	s_setprio 0
	s_barrier
; #define PG8_STAGE(bufoff, gbase, voff) do { _Pragma("unroll") for (int _i = 0; _i < 2; ++_i) \
;         __builtin_amdgcn_global_load_lds((const unsigned*)((const char*)(gbase) + (voff)[_i]), (LAS unsigned*)(lds + (bufoff) + ldsw + _i * 8192), 16, 0, 0); } while (0)
; #define PG8_LDA(dst, b, h) do { _Pragma("unroll") for (int m = 0; m < 4; ++m) _Pragma("unroll") for (int k = 0; k < 2; ++k) dst[m][k] = *(const LAS bf16x8*)(lds + PG8_SA(b, h) + aoff + m * 2048 + k * 1024); } while (0)
; #define PG8_MMA(ai, bj, At, Bt) do { __builtin_amdgcn_s_setprio(1); _Pragma("unroll") for (int m = 0; m < 4; ++m) _Pragma("unroll") for (int n = 0; n < 2; ++n) _Pragma("unroll") for (int k = 0; k < 2; ++k) \
;         acc[ai][bj][m][n] = __builtin_amdgcn_mfma_f32_16x16x32_bf16(Bt[n][k], At[m][k], acc[ai][bj][m][n], 0, 0, 0); __builtin_amdgcn_s_setprio(0); } while (0)
; #define PG8_WAIT_V(n) asm volatile("s_waitcnt vmcnt(" #n ")" ::: "memory")
; #define PG8_WAIT_L(n) asm volatile("s_waitcnt lgkmcnt(" #n ")" ::: "memory")
; #define PG8_BAR __builtin_amdgcn_s_barrier()
; #define PG8_SCHED __builtin_amdgcn_sched_barrier(0)
; template <class Epi>
; DI void gemm_phase(LAS unsigned char* lds, const int wid, const Gemm g, const Order& S, const Epi& E) {
;     ...
;         for (int t = 0; t < nt; t += 2) {
;     ...
;             PG8_LDA(At, 1, 1); PG8_STAGE(PG8_SB(1, 0), b3, voffB); PG8_STAGE(PG8_SB(1, 1), b3 + hstepB, voffB); PG8_STAGE(PG8_SA(1, 0), a3, voffA);
;             PG8_WAIT_V(8); PG8_WAIT_L(0); PG8_BAR; PG8_MMA(1, 0, At, B0); PG8_MMA(1, 1, At, B1); PG8_BAR; PG8_SCHED;
	s_add_i32 s34, s57, s94
	v_lshl_add_u64 v[146:147], v[146:147], 0, s[16:17]
	s_mov_b32 m0, s34
	ds_read_b128 v[184:187], v151 offset:49152
	ds_read_b128 v[188:191], v151 offset:50176
	ds_read_b128 v[192:195], v151 offset:51200
	ds_read_b128 v[196:199], v151 offset:52224
	ds_read_b128 v[200:203], v151 offset:53248
	ds_read_b128 v[204:207], v151 offset:54272
	ds_read_b128 v[208:211], v151 offset:55296
	ds_read_b128 v[212:215], v151 offset:56320
	global_load_lds_dwordx4 v[146:147], off
	s_add_i32 m0, s34, 0x2000
	s_add_u32 s34, s38, 0x30080
	v_lshl_add_u64 v[146:147], v[216:217], 0, s[16:17]
	s_addc_u32 s35, s39, 0
	s_add_i32 s38, s58, s94
	global_load_lds_dwordx4 v[146:147], off
	v_lshl_add_u64 v[146:147], s[34:35], 0, v[130:131]
	s_mov_b32 m0, s38
	s_nop 0
	global_load_lds_dwordx4 v[146:147], off
	v_lshl_add_u64 v[146:147], s[34:35], 0, v[134:135]
	s_add_i32 m0, s38, 0x2000
	s_nop 0
	global_load_lds_dwordx4 v[146:147], off
	v_lshl_add_u64 v[146:147], v[218:219], 0, s[16:17]
	s_mov_b32 m0, s46
	s_nop 0
	global_load_lds_dwordx4 v[146:147], off
	v_lshl_add_u64 v[146:147], v[220:221], 0, s[16:17]
	s_mov_b32 m0, s47
	s_nop 0
	global_load_lds_dwordx4 v[146:147], off
	s_waitcnt vmcnt(8)
	s_waitcnt lgkmcnt(0)
	s_barrier
	s_setprio 1
	s_waitcnt lgkmcnt(0)
	v_mfma_f32_16x16x32_bf16 v[60:63], v[152:155], v[184:187], v[60:63]
	v_mfma_f32_16x16x32_bf16 v[56:59], v[160:163], v[184:187], v[56:59]
	v_mfma_f32_16x16x32_bf16 v[44:47], v[152:155], v[192:195], v[44:47]
	v_mfma_f32_16x16x32_bf16 v[40:43], v[160:163], v[192:195], v[40:43]
	v_mfma_f32_16x16x32_bf16 v[28:31], v[152:155], v[200:203], v[28:31]
	v_mfma_f32_16x16x32_bf16 v[24:27], v[160:163], v[200:203], v[24:27]
	v_mfma_f32_16x16x32_bf16 v[12:15], v[152:155], v[208:211], v[12:15]
	v_mfma_f32_16x16x32_bf16 v[8:11], v[160:163], v[208:211], v[8:11]
	v_mfma_f32_16x16x32_bf16 v[60:63], v[156:159], v[188:191], v[60:63]
	v_mfma_f32_16x16x32_bf16 v[56:59], v[164:167], v[188:191], v[56:59]
	v_mfma_f32_16x16x32_bf16 v[44:47], v[156:159], v[196:199], v[44:47]
	v_mfma_f32_16x16x32_bf16 v[40:43], v[164:167], v[196:199], v[40:43]
	v_mfma_f32_16x16x32_bf16 v[28:31], v[156:159], v[204:207], v[28:31]
	v_mfma_f32_16x16x32_bf16 v[24:27], v[164:167], v[204:207], v[24:27]
	v_mfma_f32_16x16x32_bf16 v[12:15], v[156:159], v[212:215], v[12:15]
	v_mfma_f32_16x16x32_bf16 v[8:11], v[164:167], v[212:215], v[8:11]
	s_setprio 0
	s_setprio 1
	v_mfma_f32_16x16x32_bf16 v[52:55], v[168:171], v[184:187], v[52:55]
	v_mfma_f32_16x16x32_bf16 v[48:51], v[176:179], v[184:187], v[48:51]
	v_mfma_f32_16x16x32_bf16 v[36:39], v[168:171], v[192:195], v[36:39]
	v_mfma_f32_16x16x32_bf16 v[32:35], v[176:179], v[192:195], v[32:35]
	v_mfma_f32_16x16x32_bf16 v[20:23], v[168:171], v[200:203], v[20:23]
	v_mfma_f32_16x16x32_bf16 v[16:19], v[176:179], v[200:203], v[16:19]
	v_mfma_f32_16x16x32_bf16 v[4:7], v[168:171], v[208:211], v[4:7]
	v_mfma_f32_16x16x32_bf16 v[0:3], v[176:179], v[208:211], v[0:3]
	v_mfma_f32_16x16x32_bf16 v[52:55], v[172:175], v[188:191], v[52:55]
	v_mfma_f32_16x16x32_bf16 v[48:51], v[180:183], v[188:191], v[48:51]
	v_mfma_f32_16x16x32_bf16 v[36:39], v[172:175], v[196:199], v[36:39]
	v_mfma_f32_16x16x32_bf16 v[32:35], v[180:183], v[196:199], v[32:35]
	v_mfma_f32_16x16x32_bf16 v[20:23], v[172:175], v[204:207], v[20:23]
	v_mfma_f32_16x16x32_bf16 v[16:19], v[180:183], v[204:207], v[16:19]
	v_mfma_f32_16x16x32_bf16 v[4:7], v[172:175], v[212:215], v[4:7]
	v_mfma_f32_16x16x32_bf16 v[0:3], v[180:183], v[212:215], v[0:3]
	s_setprio 0
	s_barrier
	s_add_i32 s56, s56, 2
	s_add_u32 s54, s54, 0x100
	s_addc_u32 s55, s55, 0
	s_cmp_gt_u32 s56, 9
	s_mov_b64 s[34:35], s[36:37]
	s_cbranch_scc0 .LBB0_989
	s_branch .Lpeel_exit_4

; #define PG8_BAR __builtin_amdgcn_s_barrier()
; template <class Epi>
; DI void gemm_phase(LAS unsigned char* lds, const int wid, const Gemm g, const Order& S, const Epi& E) {
;     ...
;         if (wr == 0) PG8_BAR;
.Lpeel_exit_4:
	s_and_b64 vcc, exec, s[26:27]
	s_cbranch_vccz .LBB0_992
	s_barrier

; #define PG8_STAGE(bufoff, gbase, voff) do { _Pragma("unroll") for (int _i = 0; _i < 2; ++_i) \
;         __builtin_amdgcn_global_load_lds((const unsigned*)((const char*)(gbase) + (voff)[_i]), (LAS unsigned*)(lds + (bufoff) + ldsw + _i * 8192), 16, 0, 0); } while (0)
; #define PG8_LDA(dst, b, h) do { _Pragma("unroll") for (int m = 0; m < 4; ++m) _Pragma("unroll") for (int k = 0; k < 2; ++k) dst[m][k] = *(const LAS bf16x8*)(lds + PG8_SA(b, h) + aoff + m * 2048 + k * 1024); } while (0)
; #define PG8_LDB(dst, b, h) do { _Pragma("unroll") for (int n = 0; n < 2; ++n) _Pragma("unroll") for (int k = 0; k < 2; ++k) dst[n][k] = *(const LAS bf16x8*)(lds + PG8_SB(b, h) + boff + n * 2048 + k * 1024); } while (0)
; #define PG8_MMA(ai, bj, At, Bt) do { __builtin_amdgcn_s_setprio(1); _Pragma("unroll") for (int m = 0; m < 4; ++m) _Pragma("unroll") for (int n = 0; n < 2; ++n) _Pragma("unroll") for (int k = 0; k < 2; ++k) \
;         acc[ai][bj][m][n] = __builtin_amdgcn_mfma_f32_16x16x32_bf16(Bt[n][k], At[m][k], acc[ai][bj][m][n], 0, 0, 0); __builtin_amdgcn_s_setprio(0); } while (0)
; #define PG8_WAIT_V(n) asm volatile("s_waitcnt vmcnt(" #n ")" ::: "memory")
; #define PG8_WAIT_L(n) asm volatile("s_waitcnt lgkmcnt(" #n ")" ::: "memory")
; template <class Epi>
; DI void gemm_phase(LAS unsigned char* lds, const int wid, const Gemm g, const Order& S, const Epi& E) {
;     ...
;         const char* nA = has_next ? (const char*)(g.A + (size_t)nxt.g * g.gsA + (size_t)nxt.pm * BM * g.lda) : cA;
;         const char* nB = has_next ? (const char*)(g.Bt + (size_t)nxt.g * g.gsB + (size_t)nxt.pn * BM * g.ldb) : cB;
;         for (int t = 0; t < nt; t += 2) {
;             const bool last = (t == nt - 2);
;             const char* a1 = cA + (size_t)(t + 1) * kstep;
;             const char* a2 = last ? nA : cA + (size_t)(t + 2) * kstep; const char* b2 = last ? nB : cB + (size_t)(t + 2) * kstep;
;             const char* a3 = a2 + kstep; const char* b3 = b2 + kstep;
;             PG8_LDB(B0, 0, 0); PG8_LDB(B1, 0, 1); PG8_SCHED; PG8_LDA(At, 0, 0); PG8_STAGE(PG8_SA(1, 1), a1 + hstepA, voffA);
;             PG8_WAIT_V(8); PG8_WAIT_L(0); PG8_BAR; PG8_MMA(0, 0, At, B0); PG8_MMA(0, 1, At, B1); PG8_BAR; PG8_SCHED;
;             PG8_LDA(At, 0, 1); PG8_STAGE(PG8_SB(0, 0), b2, voffB); PG8_STAGE(PG8_SB(0, 1), b2 + hstepB, voffB); PG8_STAGE(PG8_SA(0, 0), a2, voffA);
.LBB0_1012:
	s_ashr_i32 s29, s28, 31
	s_lshl_b64 s[34:35], s[28:29], 18
	s_add_u32 s34, s6, s34
	s_addc_u32 s35, s7, s35
	s_and_b64 s[36:37], s[8:9], exec
	s_cselect_b32 s29, s35, s41
	s_cselect_b32 s54, s34, s40
	s_ashr_i32 s31, s30, 31
	s_lshl_b64 s[36:37], s[30:31], 18
	s_add_u32 s36, s21, s36
	s_addc_u32 s37, s24, s37
	s_and_b64 s[44:45], s[8:9], exec
	s_cselect_b32 s31, s37, s43
	s_cselect_b32 s55, s36, s42
	s_add_u32 s40, s40, 0x20080
	s_addc_u32 s41, s41, 0
	s_add_u32 s56, s42, 0x100
	v_mov_b32_e32 v0, 0
	s_addc_u32 s57, s43, 0
	s_mov_b32 s58, -2
	s_waitcnt vmcnt(0)
	ds_read_b128 v[144:147], v153
	ds_read_b128 v[148:151], v153 offset:1024
	ds_read_b128 v[156:159], v153 offset:2048
	ds_read_b128 v[160:163], v153 offset:3072
	ds_read_b128 v[164:167], v154
	ds_read_b128 v[168:171], v154 offset:1024
	ds_read_b128 v[172:175], v154 offset:2048
	ds_read_b128 v[176:179], v154 offset:3072
	s_add_u32 s42, s40, 0xfffe0080
	s_addc_u32 s43, s41, -1
	s_cmp_eq_u32 s58, 4
	s_cselect_b32 s45, s29, s43
	s_cselect_b32 s44, s54, s42
	s_cselect_b32 s43, s31, s57
	s_cselect_b32 s42, s55, s56
	v_lshl_add_u64 v[212:213], s[40:41], 0, v[136:137]
	s_add_i32 m0, s25, 0xc000
	ds_read_b128 v[180:183], v155
	ds_read_b128 v[184:187], v155 offset:1024
	ds_read_b128 v[188:191], v155 offset:2048
	ds_read_b128 v[192:195], v155 offset:3072
	ds_read_b128 v[196:199], v155 offset:4096
	ds_read_b128 v[200:203], v155 offset:5120
	ds_read_b128 v[204:207], v155 offset:6144
	ds_read_b128 v[208:211], v155 offset:7168
	global_load_lds_dwordx4 v[212:213], off
	v_lshl_add_u64 v[212:213], s[40:41], 0, v[138:139]
	s_add_i32 m0, s25, 0xe000
	s_nop 0
	global_load_lds_dwordx4 v[212:213], off
	s_waitcnt vmcnt(8)
	s_waitcnt lgkmcnt(0)
	s_barrier
	s_setprio 1
	s_waitcnt lgkmcnt(0)
	v_mfma_f32_16x16x32_bf16 v[124:127], v[144:147], v[180:183], 0
	v_mfma_f32_16x16x32_bf16 v[120:123], v[156:159], v[180:183], 0
	v_mfma_f32_16x16x32_bf16 v[116:119], v[144:147], v[188:191], 0
	v_mfma_f32_16x16x32_bf16 v[112:115], v[156:159], v[188:191], 0
	v_mfma_f32_16x16x32_bf16 v[96:99], v[144:147], v[196:199], 0
	v_mfma_f32_16x16x32_bf16 v[88:91], v[156:159], v[196:199], 0
	v_mfma_f32_16x16x32_bf16 v[80:83], v[144:147], v[204:207], 0
	v_mfma_f32_16x16x32_bf16 v[72:75], v[156:159], v[204:207], 0
	v_mfma_f32_16x16x32_bf16 v[124:127], v[148:151], v[184:187], v[124:127]
	v_mfma_f32_16x16x32_bf16 v[120:123], v[160:163], v[184:187], v[120:123]
	v_mfma_f32_16x16x32_bf16 v[116:119], v[148:151], v[192:195], v[116:119]
	v_mfma_f32_16x16x32_bf16 v[112:115], v[160:163], v[192:195], v[112:115]
	v_mfma_f32_16x16x32_bf16 v[96:99], v[148:151], v[200:203], v[96:99]
	v_mfma_f32_16x16x32_bf16 v[88:91], v[160:163], v[200:203], v[88:91]
	v_mfma_f32_16x16x32_bf16 v[80:83], v[148:151], v[208:211], v[80:83]
	v_mfma_f32_16x16x32_bf16 v[72:75], v[160:163], v[208:211], v[72:75]
	s_setprio 0
	s_setprio 1
	v_mfma_f32_16x16x32_bf16 v[108:111], v[164:167], v[180:183], 0
	v_mfma_f32_16x16x32_bf16 v[104:107], v[172:175], v[180:183], 0
	v_mfma_f32_16x16x32_bf16 v[100:103], v[164:167], v[188:191], 0
	v_mfma_f32_16x16x32_bf16 v[92:95], v[172:175], v[188:191], 0
	v_mfma_f32_16x16x32_bf16 v[84:87], v[164:167], v[196:199], 0
	v_mfma_f32_16x16x32_bf16 v[76:79], v[172:175], v[196:199], 0
	v_mfma_f32_16x16x32_bf16 v[68:71], v[164:167], v[204:207], 0
	v_mfma_f32_16x16x32_bf16 v[64:67], v[172:175], v[204:207], 0
	v_mfma_f32_16x16x32_bf16 v[108:111], v[168:171], v[184:187], v[108:111]
	v_mfma_f32_16x16x32_bf16 v[104:107], v[176:179], v[184:187], v[104:107]
	v_mfma_f32_16x16x32_bf16 v[100:103], v[168:171], v[192:195], v[100:103]
	v_mfma_f32_16x16x32_bf16 v[92:95], v[176:179], v[192:195], v[92:95]
	v_mfma_f32_16x16x32_bf16 v[84:87], v[168:171], v[200:203], v[84:87]
	v_mfma_f32_16x16x32_bf16 v[76:79], v[176:179], v[200:203], v[76:79]
	v_mfma_f32_16x16x32_bf16 v[68:71], v[168:171], v[208:211], v[68:71]
	v_mfma_f32_16x16x32_bf16 v[64:67], v[176:179], v[208:211], v[64:67]
	s_setprio 0
	s_barrier
	s_add_i32 s59, s51, s94
	v_lshl_add_u64 v[212:213], s[42:43], 0, v[130:131]
	s_mov_b32 m0, s59
	ds_read_b128 v[180:183], v155 offset:16384
	ds_read_b128 v[184:187], v155 offset:17408
	ds_read_b128 v[188:191], v155 offset:18432
	ds_read_b128 v[192:195], v155 offset:19456
	ds_read_b128 v[196:199], v155 offset:20480
	ds_read_b128 v[200:203], v155 offset:21504
	ds_read_b128 v[204:207], v155 offset:22528
	ds_read_b128 v[208:211], v155 offset:23552
	global_load_lds_dwordx4 v[212:213], off
	s_add_i32 m0, s59, 0x2000
	s_add_u32 s60, s42, 0x20000
	v_lshl_add_u64 v[214:215], s[42:43], 0, v[134:135]
	s_addc_u32 s61, s43, 0
	s_add_i32 s59, s52, s94
	global_load_lds_dwordx4 v[214:215], off
	v_lshl_add_u64 v[216:217], s[60:61], 0, v[130:131]
	s_mov_b32 m0, s59
	v_lshl_add_u64 v[218:219], s[44:45], 0, v[132:133]
	global_load_lds_dwordx4 v[216:217], off
	v_lshl_add_u64 v[216:217], s[60:61], 0, v[134:135]
	s_add_i32 m0, s59, 0x2000
	s_nop 0
	global_load_lds_dwordx4 v[216:217], off
	v_lshl_add_u64 v[216:217], s[44:45], 0, v[128:129]
	s_mov_b32 m0, s25
	s_nop 0
	global_load_lds_dwordx4 v[216:217], off
	s_mov_b32 m0, s39
	s_nop 0
	global_load_lds_dwordx4 v[218:219], off
	s_waitcnt vmcnt(8)
	s_waitcnt lgkmcnt(0)
	s_barrier
; #define PG8_STAGE(bufoff, gbase, voff) do { _Pragma("unroll") for (int _i = 0; _i < 2; ++_i) \
;         __builtin_amdgcn_global_load_lds((const unsigned*)((const char*)(gbase) + (voff)[_i]), (LAS unsigned*)(lds + (bufoff) + ldsw + _i * 8192), 16, 0, 0); } while (0)
; #define PG8_LDA(dst, b, h) do { _Pragma("unroll") for (int m = 0; m < 4; ++m) _Pragma("unroll") for (int k = 0; k < 2; ++k) dst[m][k] = *(const LAS bf16x8*)(lds + PG8_SA(b, h) + aoff + m * 2048 + k * 1024); } while (0)
; #define PG8_LDB(dst, b, h) do { _Pragma("unroll") for (int n = 0; n < 2; ++n) _Pragma("unroll") for (int k = 0; k < 2; ++k) dst[n][k] = *(const LAS bf16x8*)(lds + PG8_SB(b, h) + boff + n * 2048 + k * 1024); } while (0)
; #define PG8_MMA(ai, bj, At, Bt) do { __builtin_amdgcn_s_setprio(1); _Pragma("unroll") for (int m = 0; m < 4; ++m) _Pragma("unroll") for (int n = 0; n < 2; ++n) _Pragma("unroll") for (int k = 0; k < 2; ++k) \
;         acc[ai][bj][m][n] = __builtin_amdgcn_mfma_f32_16x16x32_bf16(Bt[n][k], At[m][k], acc[ai][bj][m][n], 0, 0, 0); __builtin_amdgcn_s_setprio(0); } while (0)
; #define PG8_WAIT_V(n) asm volatile("s_waitcnt vmcnt(" #n ")" ::: "memory")
; #define PG8_WAIT_L(n) asm volatile("s_waitcnt lgkmcnt(" #n ")" ::: "memory")
; #define PG8_BAR __builtin_amdgcn_s_barrier()
; #define PG8_SCHED __builtin_amdgcn_sched_barrier(0)
; template <class Epi>
; DI void gemm_phase(LAS unsigned char* lds, const int wid, const Gemm g, const Order& S, const Epi& E) {
;     ...
;             PG8_WAIT_V(8); PG8_WAIT_L(0); PG8_BAR; PG8_MMA(1, 0, At, B0); PG8_MMA(1, 1, At, B1); PG8_BAR; PG8_SCHED;
;             PG8_LDB(B0, 1, 0); PG8_LDB(B1, 1, 1); PG8_SCHED; PG8_LDA(At, 1, 0); PG8_STAGE(PG8_SA(0, 1), a2 + hstepA, voffA);
;             PG8_WAIT_V(8); PG8_WAIT_L(0); PG8_BAR; PG8_MMA(0, 0, At, B0); PG8_MMA(0, 1, At, B1); PG8_BAR; PG8_SCHED;
	s_setprio 1
	s_waitcnt lgkmcnt(0)
	v_mfma_f32_16x16x32_bf16 v[60:63], v[144:147], v[180:183], 0
	v_mfma_f32_16x16x32_bf16 v[56:59], v[156:159], v[180:183], 0
	v_mfma_f32_16x16x32_bf16 v[48:51], v[144:147], v[188:191], 0
	v_mfma_f32_16x16x32_bf16 v[40:43], v[156:159], v[188:191], 0
	v_mfma_f32_16x16x32_bf16 v[32:35], v[144:147], v[196:199], 0
	v_mfma_f32_16x16x32_bf16 v[24:27], v[156:159], v[196:199], 0
	v_mfma_f32_16x16x32_bf16 v[16:19], v[144:147], v[204:207], 0
	v_mfma_f32_16x16x32_bf16 v[8:11], v[156:159], v[204:207], 0
	v_mfma_f32_16x16x32_bf16 v[60:63], v[148:151], v[184:187], v[60:63]
	v_mfma_f32_16x16x32_bf16 v[56:59], v[160:163], v[184:187], v[56:59]
	v_mfma_f32_16x16x32_bf16 v[48:51], v[148:151], v[192:195], v[48:51]
	v_mfma_f32_16x16x32_bf16 v[40:43], v[160:163], v[192:195], v[40:43]
	v_mfma_f32_16x16x32_bf16 v[32:35], v[148:151], v[200:203], v[32:35]
	v_mfma_f32_16x16x32_bf16 v[24:27], v[160:163], v[200:203], v[24:27]
	v_mfma_f32_16x16x32_bf16 v[16:19], v[148:151], v[208:211], v[16:19]
	v_mfma_f32_16x16x32_bf16 v[8:11], v[160:163], v[208:211], v[8:11]
	s_setprio 0
	s_setprio 1
	v_mfma_f32_16x16x32_bf16 v[52:55], v[164:167], v[180:183], 0
	v_mfma_f32_16x16x32_bf16 v[44:47], v[172:175], v[180:183], 0
	v_mfma_f32_16x16x32_bf16 v[36:39], v[164:167], v[188:191], 0
	v_mfma_f32_16x16x32_bf16 v[28:31], v[172:175], v[188:191], 0
	v_mfma_f32_16x16x32_bf16 v[20:23], v[164:167], v[196:199], 0
	v_mfma_f32_16x16x32_bf16 v[12:15], v[172:175], v[196:199], 0
	v_mfma_f32_16x16x32_bf16 v[4:7], v[164:167], v[204:207], 0
	v_mfma_f32_16x16x32_bf16 v[0:3], v[172:175], v[204:207], 0
	v_mfma_f32_16x16x32_bf16 v[52:55], v[168:171], v[184:187], v[52:55]
	v_mfma_f32_16x16x32_bf16 v[44:47], v[176:179], v[184:187], v[44:47]
	v_mfma_f32_16x16x32_bf16 v[36:39], v[168:171], v[192:195], v[36:39]
	v_mfma_f32_16x16x32_bf16 v[28:31], v[176:179], v[192:195], v[28:31]
	v_mfma_f32_16x16x32_bf16 v[20:23], v[168:171], v[200:203], v[20:23]
	v_mfma_f32_16x16x32_bf16 v[12:15], v[176:179], v[200:203], v[12:15]
	v_mfma_f32_16x16x32_bf16 v[4:7], v[168:171], v[208:211], v[4:7]
	v_mfma_f32_16x16x32_bf16 v[0:3], v[176:179], v[208:211], v[0:3]
	s_setprio 0
	s_barrier
	s_add_i32 s59, 0, 0x18000
	s_add_i32 s60, 0, 0x1c000
	v_add_u32_e32 v160, s59, v152
	v_add_u32_e32 v176, s60, v152
	ds_read_b128 v[144:147], v160
	ds_read_b128 v[148:151], v160 offset:1024
	ds_read_b128 v[156:159], v160 offset:2048
	ds_read_b128 v[160:163], v160 offset:3072
	ds_read_b128 v[164:167], v176
	ds_read_b128 v[168:171], v176 offset:1024
	ds_read_b128 v[172:175], v176 offset:2048
	ds_read_b128 v[176:179], v176 offset:3072
	s_add_u32 s44, s44, 0x20000
	s_addc_u32 s45, s45, 0
	s_mov_b32 m0, s46
	v_lshl_add_u64 v[220:221], s[44:45], 0, v[128:129]
	ds_read_b128 v[180:183], v155 offset:32768
	ds_read_b128 v[184:187], v155 offset:33792
	ds_read_b128 v[188:191], v155 offset:34816
	ds_read_b128 v[192:195], v155 offset:35840
	ds_read_b128 v[196:199], v155 offset:36864
	ds_read_b128 v[200:203], v155 offset:37888
	ds_read_b128 v[204:207], v155 offset:38912
	ds_read_b128 v[208:211], v155 offset:39936
	global_load_lds_dwordx4 v[220:221], off
	v_lshl_add_u64 v[220:221], s[44:45], 0, v[132:133]
	s_mov_b32 m0, s47
	s_nop 0
	global_load_lds_dwordx4 v[220:221], off
	s_waitcnt vmcnt(8)
	s_waitcnt lgkmcnt(0)
	s_barrier
	s_setprio 1
	s_waitcnt lgkmcnt(0)
	v_mfma_f32_16x16x32_bf16 v[124:127], v[144:147], v[180:183], v[124:127]
	v_mfma_f32_16x16x32_bf16 v[120:123], v[156:159], v[180:183], v[120:123]
	v_mfma_f32_16x16x32_bf16 v[116:119], v[144:147], v[188:191], v[116:119]
	v_mfma_f32_16x16x32_bf16 v[112:115], v[156:159], v[188:191], v[112:115]
	v_mfma_f32_16x16x32_bf16 v[96:99], v[144:147], v[196:199], v[96:99]
	v_mfma_f32_16x16x32_bf16 v[88:91], v[156:159], v[196:199], v[88:91]
	v_mfma_f32_16x16x32_bf16 v[80:83], v[144:147], v[204:207], v[80:83]
	v_mfma_f32_16x16x32_bf16 v[72:75], v[156:159], v[204:207], v[72:75]
	v_mfma_f32_16x16x32_bf16 v[124:127], v[148:151], v[184:187], v[124:127]
	v_mfma_f32_16x16x32_bf16 v[120:123], v[160:163], v[184:187], v[120:123]
	v_mfma_f32_16x16x32_bf16 v[116:119], v[148:151], v[192:195], v[116:119]
	v_mfma_f32_16x16x32_bf16 v[112:115], v[160:163], v[192:195], v[112:115]
	v_mfma_f32_16x16x32_bf16 v[96:99], v[148:151], v[200:203], v[96:99]
	v_mfma_f32_16x16x32_bf16 v[88:91], v[160:163], v[200:203], v[88:91]
	v_mfma_f32_16x16x32_bf16 v[80:83], v[148:151], v[208:211], v[80:83]
	v_mfma_f32_16x16x32_bf16 v[72:75], v[160:163], v[208:211], v[72:75]
	s_setprio 0
	s_setprio 1
	v_mfma_f32_16x16x32_bf16 v[108:111], v[164:167], v[180:183], v[108:111]
	v_mfma_f32_16x16x32_bf16 v[104:107], v[172:175], v[180:183], v[104:107]
	v_mfma_f32_16x16x32_bf16 v[100:103], v[164:167], v[188:191], v[100:103]
	v_mfma_f32_16x16x32_bf16 v[92:95], v[172:175], v[188:191], v[92:95]
	v_mfma_f32_16x16x32_bf16 v[84:87], v[164:167], v[196:199], v[84:87]
	v_mfma_f32_16x16x32_bf16 v[76:79], v[172:175], v[196:199], v[76:79]
	v_mfma_f32_16x16x32_bf16 v[68:71], v[164:167], v[204:207], v[68:71]
	v_mfma_f32_16x16x32_bf16 v[64:67], v[172:175], v[204:207], v[64:67]
	v_mfma_f32_16x16x32_bf16 v[108:111], v[168:171], v[184:187], v[108:111]
	v_mfma_f32_16x16x32_bf16 v[104:107], v[176:179], v[184:187], v[104:107]
	v_mfma_f32_16x16x32_bf16 v[100:103], v[168:171], v[192:195], v[100:103]
	v_mfma_f32_16x16x32_bf16 v[92:95], v[176:179], v[192:195], v[92:95]
	v_mfma_f32_16x16x32_bf16 v[84:87], v[168:171], v[200:203], v[84:87]
	v_mfma_f32_16x16x32_bf16 v[76:79], v[176:179], v[200:203], v[76:79]
	v_mfma_f32_16x16x32_bf16 v[68:71], v[168:171], v[208:211], v[68:71]
	v_mfma_f32_16x16x32_bf16 v[64:67], v[176:179], v[208:211], v[64:67]
	s_setprio 0
	s_barrier
; #define PG8_STAGE(bufoff, gbase, voff) do { _Pragma("unroll") for (int _i = 0; _i < 2; ++_i) \
;         __builtin_amdgcn_global_load_lds((const unsigned*)((const char*)(gbase) + (voff)[_i]), (LAS unsigned*)(lds + (bufoff) + ldsw + _i * 8192), 16, 0, 0); } while (0)
; #define PG8_LDA(dst, b, h) do { _Pragma("unroll") for (int m = 0; m < 4; ++m) _Pragma("unroll") for (int k = 0; k < 2; ++k) dst[m][k] = *(const LAS bf16x8*)(lds + PG8_SA(b, h) + aoff + m * 2048 + k * 1024); } while (0)
; #define PG8_MMA(ai, bj, At, Bt) do { __builtin_amdgcn_s_setprio(1); _Pragma("unroll") for (int m = 0; m < 4; ++m) _Pragma("unroll") for (int n = 0; n < 2; ++n) _Pragma("unroll") for (int k = 0; k < 2; ++k) \
;         acc[ai][bj][m][n] = __builtin_amdgcn_mfma_f32_16x16x32_bf16(Bt[n][k], At[m][k], acc[ai][bj][m][n], 0, 0, 0); __builtin_amdgcn_s_setprio(0); } while (0)
; #define PG8_WAIT_V(n) asm volatile("s_waitcnt vmcnt(" #n ")" ::: "memory")
; #define PG8_WAIT_L(n) asm volatile("s_waitcnt lgkmcnt(" #n ")" ::: "memory")
; #define PG8_BAR __builtin_amdgcn_s_barrier()
; #define PG8_SCHED __builtin_amdgcn_sched_barrier(0)
; template <class Epi>
; DI void gemm_phase(LAS unsigned char* lds, const int wid, const Gemm g, const Order& S, const Epi& E) {
;     ...
;         for (int t = 0; t < nt; t += 2) {
;     ...
;             PG8_LDA(At, 1, 1); PG8_STAGE(PG8_SB(1, 0), b3, voffB); PG8_STAGE(PG8_SB(1, 1), b3 + hstepB, voffB); PG8_STAGE(PG8_SA(1, 0), a3, voffA);
;             PG8_WAIT_V(8); PG8_WAIT_L(0); PG8_BAR; PG8_MMA(1, 0, At, B0); PG8_MMA(1, 1, At, B1); PG8_BAR; PG8_SCHED;
	s_add_i32 s44, s59, s94
	v_lshl_add_u64 v[212:213], v[212:213], 0, s[16:17]
	s_mov_b32 m0, s44
	ds_read_b128 v[180:183], v155 offset:49152
	ds_read_b128 v[184:187], v155 offset:50176
	ds_read_b128 v[188:191], v155 offset:51200
	ds_read_b128 v[192:195], v155 offset:52224
	ds_read_b128 v[196:199], v155 offset:53248
	ds_read_b128 v[200:203], v155 offset:54272
	ds_read_b128 v[204:207], v155 offset:55296
	ds_read_b128 v[208:211], v155 offset:56320
	global_load_lds_dwordx4 v[212:213], off
	s_add_i32 m0, s44, 0x2000
	s_add_u32 s42, s42, 0x20080
	v_lshl_add_u64 v[212:213], v[214:215], 0, s[16:17]
	s_addc_u32 s43, s43, 0
	s_add_i32 s44, s60, s94
	global_load_lds_dwordx4 v[212:213], off
	v_lshl_add_u64 v[212:213], s[42:43], 0, v[130:131]
	s_mov_b32 m0, s44
	s_nop 0
	global_load_lds_dwordx4 v[212:213], off
	v_lshl_add_u64 v[212:213], s[42:43], 0, v[134:135]
	s_add_i32 m0, s44, 0x2000
	s_nop 0
	global_load_lds_dwordx4 v[212:213], off
	v_lshl_add_u64 v[212:213], v[216:217], 0, s[16:17]
	s_mov_b32 m0, s49
	s_nop 0
	global_load_lds_dwordx4 v[212:213], off
	v_lshl_add_u64 v[212:213], v[218:219], 0, s[16:17]
	s_mov_b32 m0, s50
	s_nop 0
	global_load_lds_dwordx4 v[212:213], off
	s_waitcnt vmcnt(8)
	s_waitcnt lgkmcnt(0)
	s_barrier
	s_setprio 1
	s_waitcnt lgkmcnt(0)
	v_mfma_f32_16x16x32_bf16 v[60:63], v[144:147], v[180:183], v[60:63]
	v_mfma_f32_16x16x32_bf16 v[56:59], v[156:159], v[180:183], v[56:59]
	v_mfma_f32_16x16x32_bf16 v[48:51], v[144:147], v[188:191], v[48:51]
	v_mfma_f32_16x16x32_bf16 v[40:43], v[156:159], v[188:191], v[40:43]
	v_mfma_f32_16x16x32_bf16 v[32:35], v[144:147], v[196:199], v[32:35]
	v_mfma_f32_16x16x32_bf16 v[24:27], v[156:159], v[196:199], v[24:27]
	v_mfma_f32_16x16x32_bf16 v[16:19], v[144:147], v[204:207], v[16:19]
	v_mfma_f32_16x16x32_bf16 v[8:11], v[156:159], v[204:207], v[8:11]
	v_mfma_f32_16x16x32_bf16 v[60:63], v[148:151], v[184:187], v[60:63]
	v_mfma_f32_16x16x32_bf16 v[56:59], v[160:163], v[184:187], v[56:59]
	v_mfma_f32_16x16x32_bf16 v[48:51], v[148:151], v[192:195], v[48:51]
	v_mfma_f32_16x16x32_bf16 v[40:43], v[160:163], v[192:195], v[40:43]
	v_mfma_f32_16x16x32_bf16 v[32:35], v[148:151], v[200:203], v[32:35]
	v_mfma_f32_16x16x32_bf16 v[24:27], v[160:163], v[200:203], v[24:27]
	v_mfma_f32_16x16x32_bf16 v[16:19], v[148:151], v[208:211], v[16:19]
	v_mfma_f32_16x16x32_bf16 v[8:11], v[160:163], v[208:211], v[8:11]
	s_setprio 0
	s_setprio 1
	v_mfma_f32_16x16x32_bf16 v[52:55], v[164:167], v[180:183], v[52:55]
	v_mfma_f32_16x16x32_bf16 v[44:47], v[172:175], v[180:183], v[44:47]
	v_mfma_f32_16x16x32_bf16 v[36:39], v[164:167], v[188:191], v[36:39]
	v_mfma_f32_16x16x32_bf16 v[28:31], v[172:175], v[188:191], v[28:31]
	v_mfma_f32_16x16x32_bf16 v[20:23], v[164:167], v[196:199], v[20:23]
	v_mfma_f32_16x16x32_bf16 v[12:15], v[172:175], v[196:199], v[12:15]
	v_mfma_f32_16x16x32_bf16 v[4:7], v[164:167], v[204:207], v[4:7]
	v_mfma_f32_16x16x32_bf16 v[0:3], v[172:175], v[204:207], v[0:3]
	v_mfma_f32_16x16x32_bf16 v[52:55], v[168:171], v[184:187], v[52:55]
	v_mfma_f32_16x16x32_bf16 v[44:47], v[176:179], v[184:187], v[44:47]
	v_mfma_f32_16x16x32_bf16 v[36:39], v[168:171], v[192:195], v[36:39]
	v_mfma_f32_16x16x32_bf16 v[28:31], v[176:179], v[192:195], v[28:31]
	v_mfma_f32_16x16x32_bf16 v[20:23], v[168:171], v[200:203], v[20:23]
	v_mfma_f32_16x16x32_bf16 v[12:15], v[176:179], v[200:203], v[12:15]
	v_mfma_f32_16x16x32_bf16 v[4:7], v[168:171], v[208:211], v[4:7]
	v_mfma_f32_16x16x32_bf16 v[0:3], v[176:179], v[208:211], v[0:3]
	s_setprio 0
	s_barrier
	s_add_i32 s58, s58, 2
	s_add_u32 s40, s40, 0x100
	s_addc_u32 s41, s41, 0
	s_add_u32 s56, s56, 0x100
	s_addc_u32 s57, s57, 0
	s_cmp_gt_u32 s58, 5
	s_cbranch_scc0 .LBB0_1013
	s_branch .Lpeel_exit_5

; #define PG8_STAGE(bufoff, gbase, voff) do { _Pragma("unroll") for (int _i = 0; _i < 2; ++_i) \
;         __builtin_amdgcn_global_load_lds((const unsigned*)((const char*)(gbase) + (voff)[_i]), (LAS unsigned*)(lds + (bufoff) + ldsw + _i * 8192), 16, 0, 0); } while (0)
; #define PG8_LDA(dst, b, h) do { _Pragma("unroll") for (int m = 0; m < 4; ++m) _Pragma("unroll") for (int k = 0; k < 2; ++k) dst[m][k] = *(const LAS bf16x8*)(lds + PG8_SA(b, h) + aoff + m * 2048 + k * 1024); } while (0)
; #define PG8_LDB(dst, b, h) do { _Pragma("unroll") for (int n = 0; n < 2; ++n) _Pragma("unroll") for (int k = 0; k < 2; ++k) dst[n][k] = *(const LAS bf16x8*)(lds + PG8_SB(b, h) + boff + n * 2048 + k * 1024); } while (0)
; #define PG8_MMA(ai, bj, At, Bt) do { __builtin_amdgcn_s_setprio(1); _Pragma("unroll") for (int m = 0; m < 4; ++m) _Pragma("unroll") for (int n = 0; n < 2; ++n) _Pragma("unroll") for (int k = 0; k < 2; ++k) \
;         acc[ai][bj][m][n] = __builtin_amdgcn_mfma_f32_16x16x32_bf16(Bt[n][k], At[m][k], acc[ai][bj][m][n], 0, 0, 0); __builtin_amdgcn_s_setprio(0); } while (0)
; #define PG8_WAIT_V(n) asm volatile("s_waitcnt vmcnt(" #n ")" ::: "memory")
; #define PG8_WAIT_L(n) asm volatile("s_waitcnt lgkmcnt(" #n ")" ::: "memory")
; template <class Epi>
; DI void gemm_phase(LAS unsigned char* lds, const int wid, const Gemm g, const Order& S, const Epi& E) {
;     ...
;         const char* nA = has_next ? (const char*)(g.A + (size_t)nxt.g * g.gsA + (size_t)nxt.pm * BM * g.lda) : cA;
;         const char* nB = has_next ? (const char*)(g.Bt + (size_t)nxt.g * g.gsB + (size_t)nxt.pn * BM * g.ldb) : cB;
;         for (int t = 0; t < nt; t += 2) {
;             const bool last = (t == nt - 2);
;             const char* a1 = cA + (size_t)(t + 1) * kstep;
;             const char* a2 = last ? nA : cA + (size_t)(t + 2) * kstep; const char* b2 = last ? nB : cB + (size_t)(t + 2) * kstep;
;             const char* a3 = a2 + kstep; const char* b3 = b2 + kstep;
;             PG8_LDB(B0, 0, 0); PG8_LDB(B1, 0, 1); PG8_SCHED; PG8_LDA(At, 0, 0); PG8_STAGE(PG8_SA(1, 1), a1 + hstepA, voffA);
;             PG8_WAIT_V(8); PG8_WAIT_L(0); PG8_BAR; PG8_MMA(0, 0, At, B0); PG8_MMA(0, 1, At, B1); PG8_BAR; PG8_SCHED;
;             PG8_LDA(At, 0, 1); PG8_STAGE(PG8_SB(0, 0), b2, voffB); PG8_STAGE(PG8_SB(0, 1), b2 + hstepB, voffB); PG8_STAGE(PG8_SA(0, 0), a2, voffA);
.LBB0_1090:
	s_ashr_i32 s29, s28, 31
	s_lshl_b64 s[34:35], s[28:29], 18
	s_add_u32 s34, s6, s34
	s_addc_u32 s35, s7, s35
	s_and_b64 s[36:37], s[8:9], exec
	s_cselect_b32 s29, s35, s41
	s_cselect_b32 s54, s34, s40
	s_ashr_i32 s31, s30, 31
	s_lshl_b64 s[36:37], s[30:31], 18
	s_add_u32 s36, s21, s36
	s_addc_u32 s37, s24, s37
	s_and_b64 s[44:45], s[8:9], exec
	s_cselect_b32 s31, s37, s43
	s_cselect_b32 s55, s36, s42
	s_add_u32 s40, s40, 0x20080
	s_addc_u32 s41, s41, 0
	s_add_u32 s56, s42, 0x100
	v_mov_b32_e32 v0, 0
	s_addc_u32 s57, s43, 0
	s_mov_b32 s58, -2
	ds_read_b128 v[128:131], v165
	ds_read_b128 v[132:135], v165 offset:1024
	ds_read_b128 v[136:139], v165 offset:2048
	ds_read_b128 v[140:143], v165 offset:3072
	ds_read_b128 v[160:163], v166
	ds_read_b128 v[168:171], v166 offset:1024
	ds_read_b128 v[172:175], v166 offset:2048
	ds_read_b128 v[176:179], v166 offset:3072
	s_add_u32 s42, s40, 0xfffe0080
	s_addc_u32 s43, s41, -1
	s_cmp_eq_u32 s58, 4
	s_cselect_b32 s45, s29, s43
	s_cselect_b32 s44, s54, s42
	s_cselect_b32 s43, s31, s57
	s_cselect_b32 s42, s55, s56
	v_lshl_add_u64 v[212:213], s[40:41], 0, v[152:153]
	s_add_i32 m0, s25, 0xc000
	ds_read_b128 v[180:183], v167
	ds_read_b128 v[184:187], v167 offset:1024
	ds_read_b128 v[188:191], v167 offset:2048
	ds_read_b128 v[192:195], v167 offset:3072
	ds_read_b128 v[196:199], v167 offset:4096
	ds_read_b128 v[200:203], v167 offset:5120
	ds_read_b128 v[204:207], v167 offset:6144
	ds_read_b128 v[208:211], v167 offset:7168
	global_load_lds_dwordx4 v[212:213], off
	v_lshl_add_u64 v[212:213], s[40:41], 0, v[154:155]
	s_add_i32 m0, s25, 0xe000
	s_nop 0
	global_load_lds_dwordx4 v[212:213], off
	s_waitcnt vmcnt(8)
	s_waitcnt lgkmcnt(0)
	s_barrier
	s_setprio 1
	s_waitcnt lgkmcnt(0)
	v_mfma_f32_16x16x32_bf16 v[124:127], v[128:131], v[180:183], 0
	v_mfma_f32_16x16x32_bf16 v[120:123], v[136:139], v[180:183], 0
	v_mfma_f32_16x16x32_bf16 v[116:119], v[128:131], v[188:191], 0
	v_mfma_f32_16x16x32_bf16 v[104:107], v[136:139], v[188:191], 0
	v_mfma_f32_16x16x32_bf16 v[92:95], v[128:131], v[196:199], 0
	v_mfma_f32_16x16x32_bf16 v[88:91], v[136:139], v[196:199], 0
	v_mfma_f32_16x16x32_bf16 v[76:79], v[128:131], v[204:207], 0
	v_mfma_f32_16x16x32_bf16 v[72:75], v[136:139], v[204:207], 0
	v_mfma_f32_16x16x32_bf16 v[124:127], v[132:135], v[184:187], v[124:127]
	v_mfma_f32_16x16x32_bf16 v[120:123], v[140:143], v[184:187], v[120:123]
	v_mfma_f32_16x16x32_bf16 v[116:119], v[132:135], v[192:195], v[116:119]
	v_mfma_f32_16x16x32_bf16 v[104:107], v[140:143], v[192:195], v[104:107]
	v_mfma_f32_16x16x32_bf16 v[92:95], v[132:135], v[200:203], v[92:95]
	v_mfma_f32_16x16x32_bf16 v[88:91], v[140:143], v[200:203], v[88:91]
	v_mfma_f32_16x16x32_bf16 v[76:79], v[132:135], v[208:211], v[76:79]
	v_mfma_f32_16x16x32_bf16 v[72:75], v[140:143], v[208:211], v[72:75]
	s_setprio 0
	s_setprio 1
	v_mfma_f32_16x16x32_bf16 v[112:115], v[160:163], v[180:183], 0
	v_mfma_f32_16x16x32_bf16 v[108:111], v[172:175], v[180:183], 0
	v_mfma_f32_16x16x32_bf16 v[100:103], v[160:163], v[188:191], 0
	v_mfma_f32_16x16x32_bf16 v[96:99], v[172:175], v[188:191], 0
	v_mfma_f32_16x16x32_bf16 v[84:87], v[160:163], v[196:199], 0
	v_mfma_f32_16x16x32_bf16 v[80:83], v[172:175], v[196:199], 0
	v_mfma_f32_16x16x32_bf16 v[68:71], v[160:163], v[204:207], 0
	v_mfma_f32_16x16x32_bf16 v[64:67], v[172:175], v[204:207], 0
	v_mfma_f32_16x16x32_bf16 v[112:115], v[168:171], v[184:187], v[112:115]
	v_mfma_f32_16x16x32_bf16 v[108:111], v[176:179], v[184:187], v[108:111]
	v_mfma_f32_16x16x32_bf16 v[100:103], v[168:171], v[192:195], v[100:103]
	v_mfma_f32_16x16x32_bf16 v[96:99], v[176:179], v[192:195], v[96:99]
	v_mfma_f32_16x16x32_bf16 v[84:87], v[168:171], v[200:203], v[84:87]
	v_mfma_f32_16x16x32_bf16 v[80:83], v[176:179], v[200:203], v[80:83]
	v_mfma_f32_16x16x32_bf16 v[68:71], v[168:171], v[208:211], v[68:71]
	v_mfma_f32_16x16x32_bf16 v[64:67], v[176:179], v[208:211], v[64:67]
	s_setprio 0
	s_barrier
	s_add_i32 s59, s51, s94
	v_lshl_add_u64 v[212:213], s[42:43], 0, v[146:147]
	s_mov_b32 m0, s59
	ds_read_b128 v[180:183], v167 offset:16384
	ds_read_b128 v[184:187], v167 offset:17408
	ds_read_b128 v[188:191], v167 offset:18432
	ds_read_b128 v[192:195], v167 offset:19456
	ds_read_b128 v[196:199], v167 offset:20480
	ds_read_b128 v[200:203], v167 offset:21504
	ds_read_b128 v[204:207], v167 offset:22528
	ds_read_b128 v[208:211], v167 offset:23552
	global_load_lds_dwordx4 v[212:213], off
	s_add_i32 m0, s59, 0x2000
	s_add_u32 s60, s42, 0x20000
	v_lshl_add_u64 v[214:215], s[42:43], 0, v[150:151]
	s_addc_u32 s61, s43, 0
	s_add_i32 s59, s52, s94
	global_load_lds_dwordx4 v[214:215], off
	v_lshl_add_u64 v[216:217], s[60:61], 0, v[146:147]
	s_mov_b32 m0, s59
	v_lshl_add_u64 v[218:219], s[44:45], 0, v[148:149]
	global_load_lds_dwordx4 v[216:217], off
	v_lshl_add_u64 v[216:217], s[60:61], 0, v[150:151]
	s_add_i32 m0, s59, 0x2000
	s_nop 0
	global_load_lds_dwordx4 v[216:217], off
	v_lshl_add_u64 v[216:217], s[44:45], 0, v[144:145]
	s_mov_b32 m0, s25
	s_nop 0
	global_load_lds_dwordx4 v[216:217], off
	s_mov_b32 m0, s39
	s_nop 0
	global_load_lds_dwordx4 v[218:219], off
	s_waitcnt vmcnt(8)
	s_waitcnt lgkmcnt(0)
	s_barrier
; #define PG8_STAGE(bufoff, gbase, voff) do { _Pragma("unroll") for (int _i = 0; _i < 2; ++_i) \
;         __builtin_amdgcn_global_load_lds((const unsigned*)((const char*)(gbase) + (voff)[_i]), (LAS unsigned*)(lds + (bufoff) + ldsw + _i * 8192), 16, 0, 0); } while (0)
; #define PG8_LDA(dst, b, h) do { _Pragma("unroll") for (int m = 0; m < 4; ++m) _Pragma("unroll") for (int k = 0; k < 2; ++k) dst[m][k] = *(const LAS bf16x8*)(lds + PG8_SA(b, h) + aoff + m * 2048 + k * 1024); } while (0)
; #define PG8_LDB(dst, b, h) do { _Pragma("unroll") for (int n = 0; n < 2; ++n) _Pragma("unroll") for (int k = 0; k < 2; ++k) dst[n][k] = *(const LAS bf16x8*)(lds + PG8_SB(b, h) + boff + n * 2048 + k * 1024); } while (0)
; #define PG8_MMA(ai, bj, At, Bt) do { __builtin_amdgcn_s_setprio(1); _Pragma("unroll") for (int m = 0; m < 4; ++m) _Pragma("unroll") for (int n = 0; n < 2; ++n) _Pragma("unroll") for (int k = 0; k < 2; ++k) \
;         acc[ai][bj][m][n] = __builtin_amdgcn_mfma_f32_16x16x32_bf16(Bt[n][k], At[m][k], acc[ai][bj][m][n], 0, 0, 0); __builtin_amdgcn_s_setprio(0); } while (0)
; #define PG8_WAIT_V(n) asm volatile("s_waitcnt vmcnt(" #n ")" ::: "memory")
; #define PG8_WAIT_L(n) asm volatile("s_waitcnt lgkmcnt(" #n ")" ::: "memory")
; #define PG8_BAR __builtin_amdgcn_s_barrier()
; #define PG8_SCHED __builtin_amdgcn_sched_barrier(0)
; template <class Epi>
; DI void gemm_phase(LAS unsigned char* lds, const int wid, const Gemm g, const Order& S, const Epi& E) {
;     ...
;             PG8_WAIT_V(8); PG8_WAIT_L(0); PG8_BAR; PG8_MMA(1, 0, At, B0); PG8_MMA(1, 1, At, B1); PG8_BAR; PG8_SCHED;
;             PG8_LDB(B0, 1, 0); PG8_LDB(B1, 1, 1); PG8_SCHED; PG8_LDA(At, 1, 0); PG8_STAGE(PG8_SA(0, 1), a2 + hstepA, voffA);
;             PG8_WAIT_V(8); PG8_WAIT_L(0); PG8_BAR; PG8_MMA(0, 0, At, B0); PG8_MMA(0, 1, At, B1); PG8_BAR; PG8_SCHED;
	s_setprio 1
	s_waitcnt lgkmcnt(0)
	v_mfma_f32_16x16x32_bf16 v[60:63], v[128:131], v[180:183], 0
	v_mfma_f32_16x16x32_bf16 v[56:59], v[136:139], v[180:183], 0
	v_mfma_f32_16x16x32_bf16 v[44:47], v[128:131], v[188:191], 0
	v_mfma_f32_16x16x32_bf16 v[40:43], v[136:139], v[188:191], 0
	v_mfma_f32_16x16x32_bf16 v[28:31], v[128:131], v[196:199], 0
	v_mfma_f32_16x16x32_bf16 v[24:27], v[136:139], v[196:199], 0
	v_mfma_f32_16x16x32_bf16 v[12:15], v[128:131], v[204:207], 0
	v_mfma_f32_16x16x32_bf16 v[8:11], v[136:139], v[204:207], 0
	v_mfma_f32_16x16x32_bf16 v[60:63], v[132:135], v[184:187], v[60:63]
	v_mfma_f32_16x16x32_bf16 v[56:59], v[140:143], v[184:187], v[56:59]
	v_mfma_f32_16x16x32_bf16 v[44:47], v[132:135], v[192:195], v[44:47]
	v_mfma_f32_16x16x32_bf16 v[40:43], v[140:143], v[192:195], v[40:43]
	v_mfma_f32_16x16x32_bf16 v[28:31], v[132:135], v[200:203], v[28:31]
	v_mfma_f32_16x16x32_bf16 v[24:27], v[140:143], v[200:203], v[24:27]
	v_mfma_f32_16x16x32_bf16 v[12:15], v[132:135], v[208:211], v[12:15]
	v_mfma_f32_16x16x32_bf16 v[8:11], v[140:143], v[208:211], v[8:11]
	s_setprio 0
	s_setprio 1
	v_mfma_f32_16x16x32_bf16 v[52:55], v[160:163], v[180:183], 0
	v_mfma_f32_16x16x32_bf16 v[48:51], v[172:175], v[180:183], 0
	v_mfma_f32_16x16x32_bf16 v[36:39], v[160:163], v[188:191], 0
	v_mfma_f32_16x16x32_bf16 v[32:35], v[172:175], v[188:191], 0
	v_mfma_f32_16x16x32_bf16 v[20:23], v[160:163], v[196:199], 0
	v_mfma_f32_16x16x32_bf16 v[16:19], v[172:175], v[196:199], 0
	v_mfma_f32_16x16x32_bf16 v[4:7], v[160:163], v[204:207], 0
	v_mfma_f32_16x16x32_bf16 v[0:3], v[172:175], v[204:207], 0
	v_mfma_f32_16x16x32_bf16 v[52:55], v[168:171], v[184:187], v[52:55]
	v_mfma_f32_16x16x32_bf16 v[48:51], v[176:179], v[184:187], v[48:51]
	v_mfma_f32_16x16x32_bf16 v[36:39], v[168:171], v[192:195], v[36:39]
	v_mfma_f32_16x16x32_bf16 v[32:35], v[176:179], v[192:195], v[32:35]
	v_mfma_f32_16x16x32_bf16 v[20:23], v[168:171], v[200:203], v[20:23]
	v_mfma_f32_16x16x32_bf16 v[16:19], v[176:179], v[200:203], v[16:19]
	v_mfma_f32_16x16x32_bf16 v[4:7], v[168:171], v[208:211], v[4:7]
	v_mfma_f32_16x16x32_bf16 v[0:3], v[176:179], v[208:211], v[0:3]
	s_setprio 0
	s_barrier
	s_add_i32 s59, 0, 0x18000
	s_add_i32 s60, 0, 0x1c000
	v_add_u32_e32 v140, s59, v164
	v_add_u32_e32 v176, s60, v164
	ds_read_b128 v[128:131], v140
	ds_read_b128 v[132:135], v140 offset:1024
	ds_read_b128 v[136:139], v140 offset:2048
	ds_read_b128 v[140:143], v140 offset:3072
	ds_read_b128 v[160:163], v176
	ds_read_b128 v[168:171], v176 offset:1024
	ds_read_b128 v[172:175], v176 offset:2048
	ds_read_b128 v[176:179], v176 offset:3072
	s_add_u32 s44, s44, 0x20000
	s_addc_u32 s45, s45, 0
	s_mov_b32 m0, s46
	v_lshl_add_u64 v[220:221], s[44:45], 0, v[144:145]
	ds_read_b128 v[180:183], v167 offset:32768
	ds_read_b128 v[184:187], v167 offset:33792
	ds_read_b128 v[188:191], v167 offset:34816
	ds_read_b128 v[192:195], v167 offset:35840
	ds_read_b128 v[196:199], v167 offset:36864
	ds_read_b128 v[200:203], v167 offset:37888
	ds_read_b128 v[204:207], v167 offset:38912
	ds_read_b128 v[208:211], v167 offset:39936
	global_load_lds_dwordx4 v[220:221], off
	v_lshl_add_u64 v[220:221], s[44:45], 0, v[148:149]
	s_mov_b32 m0, s47
	s_nop 0
	global_load_lds_dwordx4 v[220:221], off
	s_waitcnt vmcnt(8)
	s_waitcnt lgkmcnt(0)
	s_barrier
	s_setprio 1
	s_waitcnt lgkmcnt(0)
	v_mfma_f32_16x16x32_bf16 v[124:127], v[128:131], v[180:183], v[124:127]
	v_mfma_f32_16x16x32_bf16 v[120:123], v[136:139], v[180:183], v[120:123]
	v_mfma_f32_16x16x32_bf16 v[116:119], v[128:131], v[188:191], v[116:119]
	v_mfma_f32_16x16x32_bf16 v[104:107], v[136:139], v[188:191], v[104:107]
	v_mfma_f32_16x16x32_bf16 v[92:95], v[128:131], v[196:199], v[92:95]
	v_mfma_f32_16x16x32_bf16 v[88:91], v[136:139], v[196:199], v[88:91]
	v_mfma_f32_16x16x32_bf16 v[76:79], v[128:131], v[204:207], v[76:79]
	v_mfma_f32_16x16x32_bf16 v[72:75], v[136:139], v[204:207], v[72:75]
	v_mfma_f32_16x16x32_bf16 v[124:127], v[132:135], v[184:187], v[124:127]
	v_mfma_f32_16x16x32_bf16 v[120:123], v[140:143], v[184:187], v[120:123]
	v_mfma_f32_16x16x32_bf16 v[116:119], v[132:135], v[192:195], v[116:119]
	v_mfma_f32_16x16x32_bf16 v[104:107], v[140:143], v[192:195], v[104:107]
	v_mfma_f32_16x16x32_bf16 v[92:95], v[132:135], v[200:203], v[92:95]
	v_mfma_f32_16x16x32_bf16 v[88:91], v[140:143], v[200:203], v[88:91]
	v_mfma_f32_16x16x32_bf16 v[76:79], v[132:135], v[208:211], v[76:79]
	v_mfma_f32_16x16x32_bf16 v[72:75], v[140:143], v[208:211], v[72:75]
	s_setprio 0
	s_setprio 1
	v_mfma_f32_16x16x32_bf16 v[112:115], v[160:163], v[180:183], v[112:115]
	v_mfma_f32_16x16x32_bf16 v[108:111], v[172:175], v[180:183], v[108:111]
	v_mfma_f32_16x16x32_bf16 v[100:103], v[160:163], v[188:191], v[100:103]
	v_mfma_f32_16x16x32_bf16 v[96:99], v[172:175], v[188:191], v[96:99]
	v_mfma_f32_16x16x32_bf16 v[84:87], v[160:163], v[196:199], v[84:87]
	v_mfma_f32_16x16x32_bf16 v[80:83], v[172:175], v[196:199], v[80:83]
	v_mfma_f32_16x16x32_bf16 v[68:71], v[160:163], v[204:207], v[68:71]
	v_mfma_f32_16x16x32_bf16 v[64:67], v[172:175], v[204:207], v[64:67]
	v_mfma_f32_16x16x32_bf16 v[112:115], v[168:171], v[184:187], v[112:115]
	v_mfma_f32_16x16x32_bf16 v[108:111], v[176:179], v[184:187], v[108:111]
	v_mfma_f32_16x16x32_bf16 v[100:103], v[168:171], v[192:195], v[100:103]
	v_mfma_f32_16x16x32_bf16 v[96:99], v[176:179], v[192:195], v[96:99]
	v_mfma_f32_16x16x32_bf16 v[84:87], v[168:171], v[200:203], v[84:87]
	v_mfma_f32_16x16x32_bf16 v[80:83], v[176:179], v[200:203], v[80:83]
	v_mfma_f32_16x16x32_bf16 v[68:71], v[168:171], v[208:211], v[68:71]
	v_mfma_f32_16x16x32_bf16 v[64:67], v[176:179], v[208:211], v[64:67]
	s_setprio 0
	s_barrier
; #define PG8_STAGE(bufoff, gbase, voff) do { _Pragma("unroll") for (int _i = 0; _i < 2; ++_i) \
;         __builtin_amdgcn_global_load_lds((const unsigned*)((const char*)(gbase) + (voff)[_i]), (LAS unsigned*)(lds + (bufoff) + ldsw + _i * 8192), 16, 0, 0); } while (0)
; #define PG8_LDA(dst, b, h) do { _Pragma("unroll") for (int m = 0; m < 4; ++m) _Pragma("unroll") for (int k = 0; k < 2; ++k) dst[m][k] = *(const LAS bf16x8*)(lds + PG8_SA(b, h) + aoff + m * 2048 + k * 1024); } while (0)
; #define PG8_MMA(ai, bj, At, Bt) do { __builtin_amdgcn_s_setprio(1); _Pragma("unroll") for (int m = 0; m < 4; ++m) _Pragma("unroll") for (int n = 0; n < 2; ++n) _Pragma("unroll") for (int k = 0; k < 2; ++k) \
;         acc[ai][bj][m][n] = __builtin_amdgcn_mfma_f32_16x16x32_bf16(Bt[n][k], At[m][k], acc[ai][bj][m][n], 0, 0, 0); __builtin_amdgcn_s_setprio(0); } while (0)
; #define PG8_WAIT_V(n) asm volatile("s_waitcnt vmcnt(" #n ")" ::: "memory")
; #define PG8_WAIT_L(n) asm volatile("s_waitcnt lgkmcnt(" #n ")" ::: "memory")
; #define PG8_BAR __builtin_amdgcn_s_barrier()
; #define PG8_SCHED __builtin_amdgcn_sched_barrier(0)
; template <class Epi>
; DI void gemm_phase(LAS unsigned char* lds, const int wid, const Gemm g, const Order& S, const Epi& E) {
;     ...
;         for (int t = 0; t < nt; t += 2) {
;     ...
;             PG8_LDA(At, 1, 1); PG8_STAGE(PG8_SB(1, 0), b3, voffB); PG8_STAGE(PG8_SB(1, 1), b3 + hstepB, voffB); PG8_STAGE(PG8_SA(1, 0), a3, voffA);
;             PG8_WAIT_V(8); PG8_WAIT_L(0); PG8_BAR; PG8_MMA(1, 0, At, B0); PG8_MMA(1, 1, At, B1); PG8_BAR; PG8_SCHED;
	s_add_i32 s44, s59, s94
	v_lshl_add_u64 v[212:213], v[212:213], 0, s[16:17]
	s_mov_b32 m0, s44
	ds_read_b128 v[180:183], v167 offset:49152
	ds_read_b128 v[184:187], v167 offset:50176
	ds_read_b128 v[188:191], v167 offset:51200
	ds_read_b128 v[192:195], v167 offset:52224
	ds_read_b128 v[196:199], v167 offset:53248
	ds_read_b128 v[200:203], v167 offset:54272
	ds_read_b128 v[204:207], v167 offset:55296
	ds_read_b128 v[208:211], v167 offset:56320
	global_load_lds_dwordx4 v[212:213], off
	s_add_i32 m0, s44, 0x2000
	s_add_u32 s42, s42, 0x20080
	v_lshl_add_u64 v[212:213], v[214:215], 0, s[16:17]
	s_addc_u32 s43, s43, 0
	s_add_i32 s44, s60, s94
	global_load_lds_dwordx4 v[212:213], off
	v_lshl_add_u64 v[212:213], s[42:43], 0, v[146:147]
	s_mov_b32 m0, s44
	s_nop 0
	global_load_lds_dwordx4 v[212:213], off
	v_lshl_add_u64 v[212:213], s[42:43], 0, v[150:151]
	s_add_i32 m0, s44, 0x2000
	s_nop 0
	global_load_lds_dwordx4 v[212:213], off
	v_lshl_add_u64 v[212:213], v[216:217], 0, s[16:17]
	s_mov_b32 m0, s49
	s_nop 0
	global_load_lds_dwordx4 v[212:213], off
	v_lshl_add_u64 v[212:213], v[218:219], 0, s[16:17]
	s_mov_b32 m0, s50
	s_nop 0
	global_load_lds_dwordx4 v[212:213], off
	s_waitcnt vmcnt(8)
	s_waitcnt lgkmcnt(0)
	s_barrier
	s_setprio 1
	s_waitcnt lgkmcnt(0)
	v_mfma_f32_16x16x32_bf16 v[60:63], v[128:131], v[180:183], v[60:63]
	v_mfma_f32_16x16x32_bf16 v[56:59], v[136:139], v[180:183], v[56:59]
	v_mfma_f32_16x16x32_bf16 v[44:47], v[128:131], v[188:191], v[44:47]
	v_mfma_f32_16x16x32_bf16 v[40:43], v[136:139], v[188:191], v[40:43]
	v_mfma_f32_16x16x32_bf16 v[28:31], v[128:131], v[196:199], v[28:31]
	v_mfma_f32_16x16x32_bf16 v[24:27], v[136:139], v[196:199], v[24:27]
	v_mfma_f32_16x16x32_bf16 v[12:15], v[128:131], v[204:207], v[12:15]
	v_mfma_f32_16x16x32_bf16 v[8:11], v[136:139], v[204:207], v[8:11]
	v_mfma_f32_16x16x32_bf16 v[60:63], v[132:135], v[184:187], v[60:63]
	v_mfma_f32_16x16x32_bf16 v[56:59], v[140:143], v[184:187], v[56:59]
	v_mfma_f32_16x16x32_bf16 v[44:47], v[132:135], v[192:195], v[44:47]
	v_mfma_f32_16x16x32_bf16 v[40:43], v[140:143], v[192:195], v[40:43]
	v_mfma_f32_16x16x32_bf16 v[28:31], v[132:135], v[200:203], v[28:31]
	v_mfma_f32_16x16x32_bf16 v[24:27], v[140:143], v[200:203], v[24:27]
	v_mfma_f32_16x16x32_bf16 v[12:15], v[132:135], v[208:211], v[12:15]
	v_mfma_f32_16x16x32_bf16 v[8:11], v[140:143], v[208:211], v[8:11]
	s_setprio 0
	s_setprio 1
	v_mfma_f32_16x16x32_bf16 v[52:55], v[160:163], v[180:183], v[52:55]
	v_mfma_f32_16x16x32_bf16 v[48:51], v[172:175], v[180:183], v[48:51]
	v_mfma_f32_16x16x32_bf16 v[36:39], v[160:163], v[188:191], v[36:39]
	v_mfma_f32_16x16x32_bf16 v[32:35], v[172:175], v[188:191], v[32:35]
	v_mfma_f32_16x16x32_bf16 v[20:23], v[160:163], v[196:199], v[20:23]
	v_mfma_f32_16x16x32_bf16 v[16:19], v[172:175], v[196:199], v[16:19]
	v_mfma_f32_16x16x32_bf16 v[4:7], v[160:163], v[204:207], v[4:7]
	v_mfma_f32_16x16x32_bf16 v[0:3], v[172:175], v[204:207], v[0:3]
	v_mfma_f32_16x16x32_bf16 v[52:55], v[168:171], v[184:187], v[52:55]
	v_mfma_f32_16x16x32_bf16 v[48:51], v[176:179], v[184:187], v[48:51]
	v_mfma_f32_16x16x32_bf16 v[36:39], v[168:171], v[192:195], v[36:39]
	v_mfma_f32_16x16x32_bf16 v[32:35], v[176:179], v[192:195], v[32:35]
	v_mfma_f32_16x16x32_bf16 v[20:23], v[168:171], v[200:203], v[20:23]
	v_mfma_f32_16x16x32_bf16 v[16:19], v[176:179], v[200:203], v[16:19]
	v_mfma_f32_16x16x32_bf16 v[4:7], v[168:171], v[208:211], v[4:7]
	v_mfma_f32_16x16x32_bf16 v[0:3], v[176:179], v[208:211], v[0:3]
	s_setprio 0
	s_barrier
	s_add_i32 s58, s58, 2
	s_add_u32 s40, s40, 0x100
	s_addc_u32 s41, s41, 0
	s_add_u32 s56, s56, 0x100
	s_addc_u32 s57, s57, 0
	s_cmp_gt_u32 s58, 5
	s_cbranch_scc0 .LBB0_1091
	s_branch .Lpeel_exit_6

; #define PG8_STAGE(bufoff, gbase, voff) do { _Pragma("unroll") for (int _i = 0; _i < 2; ++_i) \
;         __builtin_amdgcn_global_load_lds((const unsigned*)((const char*)(gbase) + (voff)[_i]), (LAS unsigned*)(lds + (bufoff) + ldsw + _i * 8192), 16, 0, 0); } while (0)
; #define PG8_LDA(dst, b, h) do { _Pragma("unroll") for (int m = 0; m < 4; ++m) _Pragma("unroll") for (int k = 0; k < 2; ++k) dst[m][k] = *(const LAS bf16x8*)(lds + PG8_SA(b, h) + aoff + m * 2048 + k * 1024); } while (0)
; #define PG8_LDB(dst, b, h) do { _Pragma("unroll") for (int n = 0; n < 2; ++n) _Pragma("unroll") for (int k = 0; k < 2; ++k) dst[n][k] = *(const LAS bf16x8*)(lds + PG8_SB(b, h) + boff + n * 2048 + k * 1024); } while (0)
; #define PG8_MMA(ai, bj, At, Bt) do { __builtin_amdgcn_s_setprio(1); _Pragma("unroll") for (int m = 0; m < 4; ++m) _Pragma("unroll") for (int n = 0; n < 2; ++n) _Pragma("unroll") for (int k = 0; k < 2; ++k) \
;         acc[ai][bj][m][n] = __builtin_amdgcn_mfma_f32_16x16x32_bf16(Bt[n][k], At[m][k], acc[ai][bj][m][n], 0, 0, 0); __builtin_amdgcn_s_setprio(0); } while (0)
; #define PG8_WAIT_V(n) asm volatile("s_waitcnt vmcnt(" #n ")" ::: "memory")
; #define PG8_WAIT_L(n) asm volatile("s_waitcnt lgkmcnt(" #n ")" ::: "memory")
; template <class Epi>
; DI void gemm_phase(LAS unsigned char* lds, const int wid, const Gemm g, const Order& S, const Epi& E) {
;     ...
;         const char* nA = has_next ? (const char*)(g.A + (size_t)nxt.g * g.gsA + (size_t)nxt.pm * BM * g.lda) : cA;
;         const char* nB = has_next ? (const char*)(g.Bt + (size_t)nxt.g * g.gsB + (size_t)nxt.pn * BM * g.ldb) : cB;
;         for (int t = 0; t < nt; t += 2) {
;             const bool last = (t == nt - 2);
;             const char* a1 = cA + (size_t)(t + 1) * kstep;
;             const char* a2 = last ? nA : cA + (size_t)(t + 2) * kstep; const char* b2 = last ? nB : cB + (size_t)(t + 2) * kstep;
;             const char* a3 = a2 + kstep; const char* b3 = b2 + kstep;
;             PG8_LDB(B0, 0, 0); PG8_LDB(B1, 0, 1); PG8_SCHED; PG8_LDA(At, 0, 0); PG8_STAGE(PG8_SA(1, 1), a1 + hstepA, voffA);
;             PG8_WAIT_V(8); PG8_WAIT_L(0); PG8_BAR; PG8_MMA(0, 0, At, B0); PG8_MMA(0, 1, At, B1); PG8_BAR; PG8_SCHED;
;             PG8_LDA(At, 0, 1); PG8_STAGE(PG8_SB(0, 0), b2, voffB); PG8_STAGE(PG8_SB(0, 1), b2 + hstepB, voffB); PG8_STAGE(PG8_SA(0, 0), a2, voffA);
.LBB0_1169:
	s_ashr_i32 s31, s30, 31
	s_lshl_b64 s[36:37], s[30:31], 18
	s_add_u32 s36, s6, s36
	s_addc_u32 s37, s7, s37
	s_and_b64 s[38:39], s[8:9], exec
	s_cselect_b32 s31, s37, s43
	s_cselect_b32 s56, s36, s42
	s_ashr_i32 s35, s34, 31
	s_lshl_b64 s[38:39], s[34:35], 18
	s_add_u32 s38, s21, s38
	s_addc_u32 s39, s24, s39
	s_and_b64 s[46:47], s[8:9], exec
	s_cselect_b32 s35, s39, s45
	s_cselect_b32 s57, s38, s44
	s_add_u32 s42, s42, 0x20080
	s_addc_u32 s43, s43, 0
	s_add_u32 s58, s44, 0x100
	v_mov_b32_e32 v0, 0
	s_addc_u32 s59, s45, 0
	s_mov_b32 s60, -2
	ds_read_b128 v[128:131], v183
	ds_read_b128 v[132:135], v183 offset:1024
	ds_read_b128 v[136:139], v183 offset:2048
	ds_read_b128 v[140:143], v183 offset:3072
	ds_read_b128 v[144:147], v184
	ds_read_b128 v[148:151], v184 offset:1024
	ds_read_b128 v[152:155], v184 offset:2048
	ds_read_b128 v[172:175], v184 offset:3072
	s_add_u32 s44, s42, 0xfffe0080
	s_addc_u32 s45, s43, -1
	s_cmp_eq_u32 s60, 4
	s_cselect_b32 s47, s31, s45
	s_cselect_b32 s46, s56, s44
	s_cselect_b32 s45, s35, s59
	s_cselect_b32 s44, s57, s58
	v_lshl_add_u64 v[180:181], s[42:43], 0, v[164:165]
	s_add_i32 m0, s25, 0xc000
	ds_read_b128 v[176:179], v185
	ds_read_b128 v[186:189], v185 offset:1024
	ds_read_b128 v[190:193], v185 offset:2048
	ds_read_b128 v[194:197], v185 offset:3072
	ds_read_b128 v[198:201], v185 offset:4096
	ds_read_b128 v[202:205], v185 offset:5120
	ds_read_b128 v[206:209], v185 offset:6144
	ds_read_b128 v[210:213], v185 offset:7168
	global_load_lds_dwordx4 v[180:181], off
	v_lshl_add_u64 v[180:181], s[42:43], 0, v[166:167]
	s_add_i32 m0, s25, 0xe000
	s_nop 0
	global_load_lds_dwordx4 v[180:181], off
	s_waitcnt vmcnt(8)
	s_waitcnt lgkmcnt(0)
	s_barrier
	s_setprio 1
	s_waitcnt lgkmcnt(0)
	v_mfma_f32_16x16x32_bf16 v[124:127], v[128:131], v[176:179], 0
	v_mfma_f32_16x16x32_bf16 v[120:123], v[136:139], v[176:179], 0
	v_mfma_f32_16x16x32_bf16 v[108:111], v[128:131], v[190:193], 0
	v_mfma_f32_16x16x32_bf16 v[104:107], v[136:139], v[190:193], 0
	v_mfma_f32_16x16x32_bf16 v[92:95], v[128:131], v[198:201], 0
	v_mfma_f32_16x16x32_bf16 v[88:91], v[136:139], v[198:201], 0
	v_mfma_f32_16x16x32_bf16 v[76:79], v[128:131], v[206:209], 0
	v_mfma_f32_16x16x32_bf16 v[72:75], v[136:139], v[206:209], 0
	v_mfma_f32_16x16x32_bf16 v[124:127], v[132:135], v[186:189], v[124:127]
	v_mfma_f32_16x16x32_bf16 v[120:123], v[140:143], v[186:189], v[120:123]
	v_mfma_f32_16x16x32_bf16 v[108:111], v[132:135], v[194:197], v[108:111]
	v_mfma_f32_16x16x32_bf16 v[104:107], v[140:143], v[194:197], v[104:107]
	v_mfma_f32_16x16x32_bf16 v[92:95], v[132:135], v[202:205], v[92:95]
	v_mfma_f32_16x16x32_bf16 v[88:91], v[140:143], v[202:205], v[88:91]
	v_mfma_f32_16x16x32_bf16 v[76:79], v[132:135], v[210:213], v[76:79]
	v_mfma_f32_16x16x32_bf16 v[72:75], v[140:143], v[210:213], v[72:75]
	s_setprio 0
	s_setprio 1
	v_mfma_f32_16x16x32_bf16 v[116:119], v[144:147], v[176:179], 0
	v_mfma_f32_16x16x32_bf16 v[112:115], v[152:155], v[176:179], 0
	v_mfma_f32_16x16x32_bf16 v[100:103], v[144:147], v[190:193], 0
	v_mfma_f32_16x16x32_bf16 v[96:99], v[152:155], v[190:193], 0
	v_mfma_f32_16x16x32_bf16 v[84:87], v[144:147], v[198:201], 0
	v_mfma_f32_16x16x32_bf16 v[80:83], v[152:155], v[198:201], 0
	v_mfma_f32_16x16x32_bf16 v[68:71], v[144:147], v[206:209], 0
	v_mfma_f32_16x16x32_bf16 v[64:67], v[152:155], v[206:209], 0
	v_mfma_f32_16x16x32_bf16 v[116:119], v[148:151], v[186:189], v[116:119]
	v_mfma_f32_16x16x32_bf16 v[112:115], v[172:175], v[186:189], v[112:115]
	v_mfma_f32_16x16x32_bf16 v[100:103], v[148:151], v[194:197], v[100:103]
	v_mfma_f32_16x16x32_bf16 v[96:99], v[172:175], v[194:197], v[96:99]
	v_mfma_f32_16x16x32_bf16 v[84:87], v[148:151], v[202:205], v[84:87]
	v_mfma_f32_16x16x32_bf16 v[80:83], v[172:175], v[202:205], v[80:83]
	v_mfma_f32_16x16x32_bf16 v[68:71], v[148:151], v[210:213], v[68:71]
	v_mfma_f32_16x16x32_bf16 v[64:67], v[172:175], v[210:213], v[64:67]
	s_setprio 0
	s_barrier
	s_add_i32 s61, s53, s94
	v_lshl_add_u64 v[180:181], s[44:45], 0, v[158:159]
	s_mov_b32 m0, s61
	ds_read_b128 v[176:179], v185 offset:16384
	ds_read_b128 v[186:189], v185 offset:17408
	ds_read_b128 v[190:193], v185 offset:18432
	ds_read_b128 v[194:197], v185 offset:19456
	ds_read_b128 v[198:201], v185 offset:20480
	ds_read_b128 v[202:205], v185 offset:21504
	ds_read_b128 v[206:209], v185 offset:22528
	ds_read_b128 v[210:213], v185 offset:23552
	global_load_lds_dwordx4 v[180:181], off
	s_add_i32 m0, s61, 0x2000
	s_add_u32 s62, s44, 0x20000
	v_lshl_add_u64 v[214:215], s[44:45], 0, v[162:163]
	s_addc_u32 s63, s45, 0
	s_add_i32 s61, s54, s94
	global_load_lds_dwordx4 v[214:215], off
	v_lshl_add_u64 v[216:217], s[62:63], 0, v[158:159]
	s_mov_b32 m0, s61
	v_lshl_add_u64 v[218:219], s[46:47], 0, v[160:161]
	global_load_lds_dwordx4 v[216:217], off
	v_lshl_add_u64 v[216:217], s[62:63], 0, v[162:163]
	s_add_i32 m0, s61, 0x2000
	s_nop 0
	global_load_lds_dwordx4 v[216:217], off
	v_lshl_add_u64 v[216:217], s[46:47], 0, v[156:157]
	s_mov_b32 m0, s25
	s_nop 0
	global_load_lds_dwordx4 v[216:217], off
	s_mov_b32 m0, s41
	s_nop 0
	global_load_lds_dwordx4 v[218:219], off
	s_waitcnt vmcnt(8)
	s_waitcnt lgkmcnt(0)
	s_barrier
; #define PG8_STAGE(bufoff, gbase, voff) do { _Pragma("unroll") for (int _i = 0; _i < 2; ++_i) \
;         __builtin_amdgcn_global_load_lds((const unsigned*)((const char*)(gbase) + (voff)[_i]), (LAS unsigned*)(lds + (bufoff) + ldsw + _i * 8192), 16, 0, 0); } while (0)
; #define PG8_LDA(dst, b, h) do { _Pragma("unroll") for (int m = 0; m < 4; ++m) _Pragma("unroll") for (int k = 0; k < 2; ++k) dst[m][k] = *(const LAS bf16x8*)(lds + PG8_SA(b, h) + aoff + m * 2048 + k * 1024); } while (0)
; #define PG8_LDB(dst, b, h) do { _Pragma("unroll") for (int n = 0; n < 2; ++n) _Pragma("unroll") for (int k = 0; k < 2; ++k) dst[n][k] = *(const LAS bf16x8*)(lds + PG8_SB(b, h) + boff + n * 2048 + k * 1024); } while (0)
; #define PG8_MMA(ai, bj, At, Bt) do { __builtin_amdgcn_s_setprio(1); _Pragma("unroll") for (int m = 0; m < 4; ++m) _Pragma("unroll") for (int n = 0; n < 2; ++n) _Pragma("unroll") for (int k = 0; k < 2; ++k) \
;         acc[ai][bj][m][n] = __builtin_amdgcn_mfma_f32_16x16x32_bf16(Bt[n][k], At[m][k], acc[ai][bj][m][n], 0, 0, 0); __builtin_amdgcn_s_setprio(0); } while (0)
; #define PG8_WAIT_V(n) asm volatile("s_waitcnt vmcnt(" #n ")" ::: "memory")
; #define PG8_WAIT_L(n) asm volatile("s_waitcnt lgkmcnt(" #n ")" ::: "memory")
; #define PG8_BAR __builtin_amdgcn_s_barrier()
; #define PG8_SCHED __builtin_amdgcn_sched_barrier(0)
; template <class Epi>
; DI void gemm_phase(LAS unsigned char* lds, const int wid, const Gemm g, const Order& S, const Epi& E) {
;     ...
;             PG8_WAIT_V(8); PG8_WAIT_L(0); PG8_BAR; PG8_MMA(1, 0, At, B0); PG8_MMA(1, 1, At, B1); PG8_BAR; PG8_SCHED;
;             PG8_LDB(B0, 1, 0); PG8_LDB(B1, 1, 1); PG8_SCHED; PG8_LDA(At, 1, 0); PG8_STAGE(PG8_SA(0, 1), a2 + hstepA, voffA);
;             PG8_WAIT_V(8); PG8_WAIT_L(0); PG8_BAR; PG8_MMA(0, 0, At, B0); PG8_MMA(0, 1, At, B1); PG8_BAR; PG8_SCHED;
	s_setprio 1
	s_waitcnt lgkmcnt(0)
	v_mfma_f32_16x16x32_bf16 v[60:63], v[128:131], v[176:179], 0
	v_mfma_f32_16x16x32_bf16 v[56:59], v[136:139], v[176:179], 0
	v_mfma_f32_16x16x32_bf16 v[44:47], v[128:131], v[190:193], 0
	v_mfma_f32_16x16x32_bf16 v[40:43], v[136:139], v[190:193], 0
	v_mfma_f32_16x16x32_bf16 v[28:31], v[128:131], v[198:201], 0
	v_mfma_f32_16x16x32_bf16 v[24:27], v[136:139], v[198:201], 0
	v_mfma_f32_16x16x32_bf16 v[12:15], v[128:131], v[206:209], 0
	v_mfma_f32_16x16x32_bf16 v[8:11], v[136:139], v[206:209], 0
	v_mfma_f32_16x16x32_bf16 v[60:63], v[132:135], v[186:189], v[60:63]
	v_mfma_f32_16x16x32_bf16 v[56:59], v[140:143], v[186:189], v[56:59]
	v_mfma_f32_16x16x32_bf16 v[44:47], v[132:135], v[194:197], v[44:47]
	v_mfma_f32_16x16x32_bf16 v[40:43], v[140:143], v[194:197], v[40:43]
	v_mfma_f32_16x16x32_bf16 v[28:31], v[132:135], v[202:205], v[28:31]
	v_mfma_f32_16x16x32_bf16 v[24:27], v[140:143], v[202:205], v[24:27]
	v_mfma_f32_16x16x32_bf16 v[12:15], v[132:135], v[210:213], v[12:15]
	v_mfma_f32_16x16x32_bf16 v[8:11], v[140:143], v[210:213], v[8:11]
	s_setprio 0
	s_setprio 1
	v_mfma_f32_16x16x32_bf16 v[52:55], v[144:147], v[176:179], 0
	v_mfma_f32_16x16x32_bf16 v[48:51], v[152:155], v[176:179], 0
	v_mfma_f32_16x16x32_bf16 v[36:39], v[144:147], v[190:193], 0
	v_mfma_f32_16x16x32_bf16 v[32:35], v[152:155], v[190:193], 0
	v_mfma_f32_16x16x32_bf16 v[20:23], v[144:147], v[198:201], 0
	v_mfma_f32_16x16x32_bf16 v[16:19], v[152:155], v[198:201], 0
	v_mfma_f32_16x16x32_bf16 v[4:7], v[144:147], v[206:209], 0
	v_mfma_f32_16x16x32_bf16 v[0:3], v[152:155], v[206:209], 0
	v_mfma_f32_16x16x32_bf16 v[52:55], v[148:151], v[186:189], v[52:55]
	v_mfma_f32_16x16x32_bf16 v[48:51], v[172:175], v[186:189], v[48:51]
	v_mfma_f32_16x16x32_bf16 v[36:39], v[148:151], v[194:197], v[36:39]
	v_mfma_f32_16x16x32_bf16 v[32:35], v[172:175], v[194:197], v[32:35]
	v_mfma_f32_16x16x32_bf16 v[20:23], v[148:151], v[202:205], v[20:23]
	v_mfma_f32_16x16x32_bf16 v[16:19], v[172:175], v[202:205], v[16:19]
	v_mfma_f32_16x16x32_bf16 v[4:7], v[148:151], v[210:213], v[4:7]
	v_mfma_f32_16x16x32_bf16 v[0:3], v[172:175], v[210:213], v[0:3]
	s_setprio 0
	s_barrier
	s_add_i32 s61, 0, 0x18000
	s_add_i32 s62, 0, 0x1c000
	v_add_u32_e32 v140, s61, v182
	v_add_u32_e32 v172, s62, v182
	ds_read_b128 v[128:131], v140
	ds_read_b128 v[132:135], v140 offset:1024
	ds_read_b128 v[136:139], v140 offset:2048
	ds_read_b128 v[140:143], v140 offset:3072
	ds_read_b128 v[144:147], v172
	ds_read_b128 v[148:151], v172 offset:1024
	ds_read_b128 v[152:155], v172 offset:2048
	ds_read_b128 v[172:175], v172 offset:3072
	s_add_u32 s46, s46, 0x20000
	s_addc_u32 s47, s47, 0
	s_mov_b32 m0, s48
	v_lshl_add_u64 v[220:221], s[46:47], 0, v[156:157]
	ds_read_b128 v[176:179], v185 offset:32768
	ds_read_b128 v[186:189], v185 offset:33792
	ds_read_b128 v[190:193], v185 offset:34816
	ds_read_b128 v[194:197], v185 offset:35840
	ds_read_b128 v[198:201], v185 offset:36864
	ds_read_b128 v[202:205], v185 offset:37888
	ds_read_b128 v[206:209], v185 offset:38912
	ds_read_b128 v[210:213], v185 offset:39936
	global_load_lds_dwordx4 v[220:221], off
	v_lshl_add_u64 v[220:221], s[46:47], 0, v[160:161]
	s_mov_b32 m0, s49
	s_nop 0
	global_load_lds_dwordx4 v[220:221], off
	s_waitcnt vmcnt(8)
	s_waitcnt lgkmcnt(0)
	s_barrier
	s_setprio 1
	s_waitcnt lgkmcnt(0)
	v_mfma_f32_16x16x32_bf16 v[124:127], v[128:131], v[176:179], v[124:127]
	v_mfma_f32_16x16x32_bf16 v[120:123], v[136:139], v[176:179], v[120:123]
	v_mfma_f32_16x16x32_bf16 v[108:111], v[128:131], v[190:193], v[108:111]
	v_mfma_f32_16x16x32_bf16 v[104:107], v[136:139], v[190:193], v[104:107]
	v_mfma_f32_16x16x32_bf16 v[92:95], v[128:131], v[198:201], v[92:95]
	v_mfma_f32_16x16x32_bf16 v[88:91], v[136:139], v[198:201], v[88:91]
	v_mfma_f32_16x16x32_bf16 v[76:79], v[128:131], v[206:209], v[76:79]
	v_mfma_f32_16x16x32_bf16 v[72:75], v[136:139], v[206:209], v[72:75]
	v_mfma_f32_16x16x32_bf16 v[124:127], v[132:135], v[186:189], v[124:127]
	v_mfma_f32_16x16x32_bf16 v[120:123], v[140:143], v[186:189], v[120:123]
	v_mfma_f32_16x16x32_bf16 v[108:111], v[132:135], v[194:197], v[108:111]
	v_mfma_f32_16x16x32_bf16 v[104:107], v[140:143], v[194:197], v[104:107]
	v_mfma_f32_16x16x32_bf16 v[92:95], v[132:135], v[202:205], v[92:95]
	v_mfma_f32_16x16x32_bf16 v[88:91], v[140:143], v[202:205], v[88:91]
	v_mfma_f32_16x16x32_bf16 v[76:79], v[132:135], v[210:213], v[76:79]
	v_mfma_f32_16x16x32_bf16 v[72:75], v[140:143], v[210:213], v[72:75]
	s_setprio 0
	s_setprio 1
	v_mfma_f32_16x16x32_bf16 v[116:119], v[144:147], v[176:179], v[116:119]
	v_mfma_f32_16x16x32_bf16 v[112:115], v[152:155], v[176:179], v[112:115]
	v_mfma_f32_16x16x32_bf16 v[100:103], v[144:147], v[190:193], v[100:103]
	v_mfma_f32_16x16x32_bf16 v[96:99], v[152:155], v[190:193], v[96:99]
	v_mfma_f32_16x16x32_bf16 v[84:87], v[144:147], v[198:201], v[84:87]
	v_mfma_f32_16x16x32_bf16 v[80:83], v[152:155], v[198:201], v[80:83]
	v_mfma_f32_16x16x32_bf16 v[68:71], v[144:147], v[206:209], v[68:71]
	v_mfma_f32_16x16x32_bf16 v[64:67], v[152:155], v[206:209], v[64:67]
	v_mfma_f32_16x16x32_bf16 v[116:119], v[148:151], v[186:189], v[116:119]
	v_mfma_f32_16x16x32_bf16 v[112:115], v[172:175], v[186:189], v[112:115]
	v_mfma_f32_16x16x32_bf16 v[100:103], v[148:151], v[194:197], v[100:103]
	v_mfma_f32_16x16x32_bf16 v[96:99], v[172:175], v[194:197], v[96:99]
	v_mfma_f32_16x16x32_bf16 v[84:87], v[148:151], v[202:205], v[84:87]
	v_mfma_f32_16x16x32_bf16 v[80:83], v[172:175], v[202:205], v[80:83]
	v_mfma_f32_16x16x32_bf16 v[68:71], v[148:151], v[210:213], v[68:71]
	v_mfma_f32_16x16x32_bf16 v[64:67], v[172:175], v[210:213], v[64:67]
	s_setprio 0
	s_barrier
; #define PG8_STAGE(bufoff, gbase, voff) do { _Pragma("unroll") for (int _i = 0; _i < 2; ++_i) \
;         __builtin_amdgcn_global_load_lds((const unsigned*)((const char*)(gbase) + (voff)[_i]), (LAS unsigned*)(lds + (bufoff) + ldsw + _i * 8192), 16, 0, 0); } while (0)
; #define PG8_LDA(dst, b, h) do { _Pragma("unroll") for (int m = 0; m < 4; ++m) _Pragma("unroll") for (int k = 0; k < 2; ++k) dst[m][k] = *(const LAS bf16x8*)(lds + PG8_SA(b, h) + aoff + m * 2048 + k * 1024); } while (0)
; #define PG8_MMA(ai, bj, At, Bt) do { __builtin_amdgcn_s_setprio(1); _Pragma("unroll") for (int m = 0; m < 4; ++m) _Pragma("unroll") for (int n = 0; n < 2; ++n) _Pragma("unroll") for (int k = 0; k < 2; ++k) \
;         acc[ai][bj][m][n] = __builtin_amdgcn_mfma_f32_16x16x32_bf16(Bt[n][k], At[m][k], acc[ai][bj][m][n], 0, 0, 0); __builtin_amdgcn_s_setprio(0); } while (0)
; #define PG8_WAIT_V(n) asm volatile("s_waitcnt vmcnt(" #n ")" ::: "memory")
; #define PG8_WAIT_L(n) asm volatile("s_waitcnt lgkmcnt(" #n ")" ::: "memory")
; #define PG8_BAR __builtin_amdgcn_s_barrier()
; #define PG8_SCHED __builtin_amdgcn_sched_barrier(0)
; template <class Epi>
; DI void gemm_phase(LAS unsigned char* lds, const int wid, const Gemm g, const Order& S, const Epi& E) {
;     ...
;         for (int t = 0; t < nt; t += 2) {
;     ...
;             PG8_LDA(At, 1, 1); PG8_STAGE(PG8_SB(1, 0), b3, voffB); PG8_STAGE(PG8_SB(1, 1), b3 + hstepB, voffB); PG8_STAGE(PG8_SA(1, 0), a3, voffA);
;             PG8_WAIT_V(8); PG8_WAIT_L(0); PG8_BAR; PG8_MMA(1, 0, At, B0); PG8_MMA(1, 1, At, B1); PG8_BAR; PG8_SCHED;
	s_add_i32 s46, s61, s94
	v_lshl_add_u64 v[180:181], v[180:181], 0, s[26:27]
	s_mov_b32 m0, s46
	ds_read_b128 v[176:179], v185 offset:49152
	ds_read_b128 v[186:189], v185 offset:50176
	ds_read_b128 v[190:193], v185 offset:51200
	ds_read_b128 v[194:197], v185 offset:52224
	ds_read_b128 v[198:201], v185 offset:53248
	ds_read_b128 v[202:205], v185 offset:54272
	ds_read_b128 v[206:209], v185 offset:55296
	ds_read_b128 v[210:213], v185 offset:56320
	global_load_lds_dwordx4 v[180:181], off
	s_add_i32 m0, s46, 0x2000
	s_add_u32 s44, s44, 0x20080
	v_lshl_add_u64 v[180:181], v[214:215], 0, s[26:27]
	s_addc_u32 s45, s45, 0
	s_add_i32 s46, s62, s94
	global_load_lds_dwordx4 v[180:181], off
	v_lshl_add_u64 v[180:181], s[44:45], 0, v[158:159]
	s_mov_b32 m0, s46
	s_nop 0
	global_load_lds_dwordx4 v[180:181], off
	v_lshl_add_u64 v[180:181], s[44:45], 0, v[162:163]
	s_add_i32 m0, s46, 0x2000
	s_nop 0
	global_load_lds_dwordx4 v[180:181], off
	v_lshl_add_u64 v[180:181], v[216:217], 0, s[26:27]
	s_mov_b32 m0, s51
	s_nop 0
	global_load_lds_dwordx4 v[180:181], off
	v_lshl_add_u64 v[180:181], v[218:219], 0, s[26:27]
	s_mov_b32 m0, s52
	s_nop 0
	global_load_lds_dwordx4 v[180:181], off
	s_waitcnt vmcnt(8)
	s_waitcnt lgkmcnt(0)
	s_barrier
	s_setprio 1
	s_waitcnt lgkmcnt(0)
	v_mfma_f32_16x16x32_bf16 v[60:63], v[128:131], v[176:179], v[60:63]
	v_mfma_f32_16x16x32_bf16 v[56:59], v[136:139], v[176:179], v[56:59]
	v_mfma_f32_16x16x32_bf16 v[44:47], v[128:131], v[190:193], v[44:47]
	v_mfma_f32_16x16x32_bf16 v[40:43], v[136:139], v[190:193], v[40:43]
	v_mfma_f32_16x16x32_bf16 v[28:31], v[128:131], v[198:201], v[28:31]
	v_mfma_f32_16x16x32_bf16 v[24:27], v[136:139], v[198:201], v[24:27]
	v_mfma_f32_16x16x32_bf16 v[12:15], v[128:131], v[206:209], v[12:15]
	v_mfma_f32_16x16x32_bf16 v[8:11], v[136:139], v[206:209], v[8:11]
	v_mfma_f32_16x16x32_bf16 v[60:63], v[132:135], v[186:189], v[60:63]
	v_mfma_f32_16x16x32_bf16 v[56:59], v[140:143], v[186:189], v[56:59]
	v_mfma_f32_16x16x32_bf16 v[44:47], v[132:135], v[194:197], v[44:47]
	v_mfma_f32_16x16x32_bf16 v[40:43], v[140:143], v[194:197], v[40:43]
	v_mfma_f32_16x16x32_bf16 v[28:31], v[132:135], v[202:205], v[28:31]
	v_mfma_f32_16x16x32_bf16 v[24:27], v[140:143], v[202:205], v[24:27]
	v_mfma_f32_16x16x32_bf16 v[12:15], v[132:135], v[210:213], v[12:15]
	v_mfma_f32_16x16x32_bf16 v[8:11], v[140:143], v[210:213], v[8:11]
	s_setprio 0
	s_setprio 1
	v_mfma_f32_16x16x32_bf16 v[52:55], v[144:147], v[176:179], v[52:55]
	v_mfma_f32_16x16x32_bf16 v[48:51], v[152:155], v[176:179], v[48:51]
	v_mfma_f32_16x16x32_bf16 v[36:39], v[144:147], v[190:193], v[36:39]
	v_mfma_f32_16x16x32_bf16 v[32:35], v[152:155], v[190:193], v[32:35]
	v_mfma_f32_16x16x32_bf16 v[20:23], v[144:147], v[198:201], v[20:23]
	v_mfma_f32_16x16x32_bf16 v[16:19], v[152:155], v[198:201], v[16:19]
	v_mfma_f32_16x16x32_bf16 v[4:7], v[144:147], v[206:209], v[4:7]
	v_mfma_f32_16x16x32_bf16 v[0:3], v[152:155], v[206:209], v[0:3]
	v_mfma_f32_16x16x32_bf16 v[52:55], v[148:151], v[186:189], v[52:55]
	v_mfma_f32_16x16x32_bf16 v[48:51], v[172:175], v[186:189], v[48:51]
	v_mfma_f32_16x16x32_bf16 v[36:39], v[148:151], v[194:197], v[36:39]
	v_mfma_f32_16x16x32_bf16 v[32:35], v[172:175], v[194:197], v[32:35]
	v_mfma_f32_16x16x32_bf16 v[20:23], v[148:151], v[202:205], v[20:23]
	v_mfma_f32_16x16x32_bf16 v[16:19], v[172:175], v[202:205], v[16:19]
	v_mfma_f32_16x16x32_bf16 v[4:7], v[148:151], v[210:213], v[4:7]
	v_mfma_f32_16x16x32_bf16 v[0:3], v[172:175], v[210:213], v[0:3]
	s_setprio 0
	s_barrier
	s_add_i32 s60, s60, 2
	s_add_u32 s42, s42, 0x100
	s_addc_u32 s43, s43, 0
	s_add_u32 s58, s58, 0x100
	s_addc_u32 s59, s59, 0
	s_cmp_gt_u32 s60, 5
	s_cbranch_scc0 .LBB0_1170
	s_branch .Lpeel_exit_7

; #define PG8_STAGE(bufoff, gbase, voff) do { _Pragma("unroll") for (int _i = 0; _i < 2; ++_i) \
;         __builtin_amdgcn_global_load_lds((const unsigned*)((const char*)(gbase) + (voff)[_i]), (LAS unsigned*)(lds + (bufoff) + ldsw + _i * 8192), 16, 0, 0); } while (0)
; #define PG8_LDA(dst, b, h) do { _Pragma("unroll") for (int m = 0; m < 4; ++m) _Pragma("unroll") for (int k = 0; k < 2; ++k) dst[m][k] = *(const LAS bf16x8*)(lds + PG8_SA(b, h) + aoff + m * 2048 + k * 1024); } while (0)
; #define PG8_LDB(dst, b, h) do { _Pragma("unroll") for (int n = 0; n < 2; ++n) _Pragma("unroll") for (int k = 0; k < 2; ++k) dst[n][k] = *(const LAS bf16x8*)(lds + PG8_SB(b, h) + boff + n * 2048 + k * 1024); } while (0)
; #define PG8_MMA(ai, bj, At, Bt) do { __builtin_amdgcn_s_setprio(1); _Pragma("unroll") for (int m = 0; m < 4; ++m) _Pragma("unroll") for (int n = 0; n < 2; ++n) _Pragma("unroll") for (int k = 0; k < 2; ++k) \
;         acc[ai][bj][m][n] = __builtin_amdgcn_mfma_f32_16x16x32_bf16(Bt[n][k], At[m][k], acc[ai][bj][m][n], 0, 0, 0); __builtin_amdgcn_s_setprio(0); } while (0)
; #define PG8_WAIT_V(n) asm volatile("s_waitcnt vmcnt(" #n ")" ::: "memory")
; #define PG8_WAIT_L(n) asm volatile("s_waitcnt lgkmcnt(" #n ")" ::: "memory")
; template <class Epi>
; DI void gemm_phase(LAS unsigned char* lds, const int wid, const Gemm g, const Order& S, const Epi& E) {
;     ...
;         const char* nA = has_next ? (const char*)(g.A + (size_t)nxt.g * g.gsA + (size_t)nxt.pm * BM * g.lda) : cA;
;         const char* nB = has_next ? (const char*)(g.Bt + (size_t)nxt.g * g.gsB + (size_t)nxt.pn * BM * g.ldb) : cB;
;         for (int t = 0; t < nt; t += 2) {
;             const bool last = (t == nt - 2);
;             const char* a1 = cA + (size_t)(t + 1) * kstep;
;             const char* a2 = last ? nA : cA + (size_t)(t + 2) * kstep; const char* b2 = last ? nB : cB + (size_t)(t + 2) * kstep;
;             const char* a3 = a2 + kstep; const char* b3 = b2 + kstep;
;             PG8_LDB(B0, 0, 0); PG8_LDB(B1, 0, 1); PG8_SCHED; PG8_LDA(At, 0, 0); PG8_STAGE(PG8_SA(1, 1), a1 + hstepA, voffA);
;             PG8_WAIT_V(8); PG8_WAIT_L(0); PG8_BAR; PG8_MMA(0, 0, At, B0); PG8_MMA(0, 1, At, B1); PG8_BAR; PG8_SCHED;
;             PG8_LDA(At, 0, 1); PG8_STAGE(PG8_SB(0, 0), b2, voffB); PG8_STAGE(PG8_SB(0, 1), b2 + hstepB, voffB); PG8_STAGE(PG8_SA(0, 0), a2, voffA);
.LBB0_1249:
	s_ashr_i32 s37, s36, 31
	s_lshl_b64 s[40:41], s[36:37], 19
	s_add_u32 s40, s6, s40
	s_addc_u32 s41, s7, s41
	s_and_b64 s[42:43], s[8:9], exec
	s_cselect_b32 s11, s41, s47
	s_cselect_b32 s37, s40, s46
	s_ashr_i32 s39, s38, 31
	s_lshl_b64 s[42:43], s[38:39], 19
	s_add_u32 s42, s21, s42
	s_addc_u32 s43, s24, s43
	s_and_b64 s[50:51], s[8:9], exec
	s_cselect_b32 s39, s43, s49
	s_cselect_b32 s59, s42, s48
	s_add_u32 s46, s46, 0x40080
	s_addc_u32 s47, s47, 0
	s_add_u32 s60, s48, 0x100
	v_mov_b32_e32 v0, 0
	s_addc_u32 s61, s49, 0
	s_mov_b32 s62, -2
	s_waitcnt lgkmcnt(0)
	ds_read_b128 v[128:131], v209
	ds_read_b128 v[132:135], v209 offset:1024
	ds_read_b128 v[136:139], v209 offset:2048
	ds_read_b128 v[140:143], v209 offset:3072
	ds_read_b128 v[144:147], v210
	ds_read_b128 v[148:151], v210 offset:1024
	ds_read_b128 v[152:155], v210 offset:2048
	ds_read_b128 v[156:159], v210 offset:3072
	s_add_u32 s48, s46, 0xfffc0080
	s_addc_u32 s49, s47, -1
	s_cmp_eq_u32 s62, 12
	s_cselect_b32 s51, s11, s49
	s_cselect_b32 s50, s37, s48
	s_cselect_b32 s49, s39, s61
	s_cselect_b32 s48, s59, s60
	v_lshl_add_u64 v[214:215], s[46:47], 0, v[184:185]
	s_add_i32 m0, s25, 0xc000
	ds_read_b128 v[160:163], v211
	ds_read_b128 v[164:167], v211 offset:1024
	ds_read_b128 v[168:171], v211 offset:2048
	ds_read_b128 v[172:175], v211 offset:3072
	ds_read_b128 v[192:195], v211 offset:4096
	ds_read_b128 v[196:199], v211 offset:5120
	ds_read_b128 v[200:203], v211 offset:6144
	ds_read_b128 v[204:207], v211 offset:7168
	global_load_lds_dwordx4 v[214:215], off
	v_lshl_add_u64 v[214:215], s[46:47], 0, v[186:187]
	s_add_i32 m0, s25, 0xe000
	s_nop 0
	global_load_lds_dwordx4 v[214:215], off
	s_waitcnt vmcnt(8)
	s_waitcnt lgkmcnt(0)
	s_barrier
	s_setprio 1
	s_waitcnt lgkmcnt(0)
	v_mfma_f32_16x16x32_bf16 v[124:127], v[128:131], v[160:163], 0
	v_mfma_f32_16x16x32_bf16 v[120:123], v[136:139], v[160:163], 0
	v_mfma_f32_16x16x32_bf16 v[108:111], v[128:131], v[168:171], 0
	v_mfma_f32_16x16x32_bf16 v[104:107], v[136:139], v[168:171], 0
	v_mfma_f32_16x16x32_bf16 v[92:95], v[128:131], v[192:195], 0
	v_mfma_f32_16x16x32_bf16 v[88:91], v[136:139], v[192:195], 0
	v_mfma_f32_16x16x32_bf16 v[76:79], v[128:131], v[200:203], 0
	v_mfma_f32_16x16x32_bf16 v[72:75], v[136:139], v[200:203], 0
	v_mfma_f32_16x16x32_bf16 v[124:127], v[132:135], v[164:167], v[124:127]
	v_mfma_f32_16x16x32_bf16 v[120:123], v[140:143], v[164:167], v[120:123]
	v_mfma_f32_16x16x32_bf16 v[108:111], v[132:135], v[172:175], v[108:111]
	v_mfma_f32_16x16x32_bf16 v[104:107], v[140:143], v[172:175], v[104:107]
	v_mfma_f32_16x16x32_bf16 v[92:95], v[132:135], v[196:199], v[92:95]
	v_mfma_f32_16x16x32_bf16 v[88:91], v[140:143], v[196:199], v[88:91]
	v_mfma_f32_16x16x32_bf16 v[76:79], v[132:135], v[204:207], v[76:79]
	v_mfma_f32_16x16x32_bf16 v[72:75], v[140:143], v[204:207], v[72:75]
	s_setprio 0
	s_setprio 1
	v_mfma_f32_16x16x32_bf16 v[116:119], v[144:147], v[160:163], 0
	v_mfma_f32_16x16x32_bf16 v[112:115], v[152:155], v[160:163], 0
	v_mfma_f32_16x16x32_bf16 v[100:103], v[144:147], v[168:171], 0
	v_mfma_f32_16x16x32_bf16 v[96:99], v[152:155], v[168:171], 0
	v_mfma_f32_16x16x32_bf16 v[84:87], v[144:147], v[192:195], 0
	v_mfma_f32_16x16x32_bf16 v[80:83], v[152:155], v[192:195], 0
	v_mfma_f32_16x16x32_bf16 v[68:71], v[144:147], v[200:203], 0
	v_mfma_f32_16x16x32_bf16 v[64:67], v[152:155], v[200:203], 0
	v_mfma_f32_16x16x32_bf16 v[116:119], v[148:151], v[164:167], v[116:119]
	v_mfma_f32_16x16x32_bf16 v[112:115], v[156:159], v[164:167], v[112:115]
	v_mfma_f32_16x16x32_bf16 v[100:103], v[148:151], v[172:175], v[100:103]
	v_mfma_f32_16x16x32_bf16 v[96:99], v[156:159], v[172:175], v[96:99]
	v_mfma_f32_16x16x32_bf16 v[84:87], v[148:151], v[196:199], v[84:87]
	v_mfma_f32_16x16x32_bf16 v[80:83], v[156:159], v[196:199], v[80:83]
	v_mfma_f32_16x16x32_bf16 v[68:71], v[148:151], v[204:207], v[68:71]
	v_mfma_f32_16x16x32_bf16 v[64:67], v[156:159], v[204:207], v[64:67]
	s_setprio 0
	s_barrier
	s_add_i32 s63, s57, s94
	v_lshl_add_u64 v[214:215], s[48:49], 0, v[178:179]
	s_mov_b32 m0, s63
	ds_read_b128 v[160:163], v211 offset:16384
	ds_read_b128 v[164:167], v211 offset:17408
	ds_read_b128 v[168:171], v211 offset:18432
	ds_read_b128 v[172:175], v211 offset:19456
	ds_read_b128 v[192:195], v211 offset:20480
	ds_read_b128 v[196:199], v211 offset:21504
	ds_read_b128 v[200:203], v211 offset:22528
	ds_read_b128 v[204:207], v211 offset:23552
	global_load_lds_dwordx4 v[214:215], off
	s_add_i32 m0, s63, 0x2000
	s_add_u32 s66, s48, 0x40000
	v_lshl_add_u64 v[216:217], s[48:49], 0, v[182:183]
	s_addc_u32 s67, s49, 0
	s_add_i32 s63, s58, s94
	global_load_lds_dwordx4 v[216:217], off
	v_lshl_add_u64 v[218:219], s[66:67], 0, v[178:179]
	s_mov_b32 m0, s63
	v_lshl_add_u64 v[220:221], s[50:51], 0, v[180:181]
	global_load_lds_dwordx4 v[218:219], off
	v_lshl_add_u64 v[218:219], s[66:67], 0, v[182:183]
	s_add_i32 m0, s63, 0x2000
	s_nop 0
	global_load_lds_dwordx4 v[218:219], off
	v_lshl_add_u64 v[218:219], s[50:51], 0, v[176:177]
	s_mov_b32 m0, s25
	s_nop 0
	global_load_lds_dwordx4 v[218:219], off
	s_mov_b32 m0, s45
	s_nop 0
	global_load_lds_dwordx4 v[220:221], off
	s_waitcnt vmcnt(8)
	s_waitcnt lgkmcnt(0)
	s_barrier
; #define PG8_STAGE(bufoff, gbase, voff) do { _Pragma("unroll") for (int _i = 0; _i < 2; ++_i) \
;         __builtin_amdgcn_global_load_lds((const unsigned*)((const char*)(gbase) + (voff)[_i]), (LAS unsigned*)(lds + (bufoff) + ldsw + _i * 8192), 16, 0, 0); } while (0)
; #define PG8_LDA(dst, b, h) do { _Pragma("unroll") for (int m = 0; m < 4; ++m) _Pragma("unroll") for (int k = 0; k < 2; ++k) dst[m][k] = *(const LAS bf16x8*)(lds + PG8_SA(b, h) + aoff + m * 2048 + k * 1024); } while (0)
; #define PG8_LDB(dst, b, h) do { _Pragma("unroll") for (int n = 0; n < 2; ++n) _Pragma("unroll") for (int k = 0; k < 2; ++k) dst[n][k] = *(const LAS bf16x8*)(lds + PG8_SB(b, h) + boff + n * 2048 + k * 1024); } while (0)
; #define PG8_MMA(ai, bj, At, Bt) do { __builtin_amdgcn_s_setprio(1); _Pragma("unroll") for (int m = 0; m < 4; ++m) _Pragma("unroll") for (int n = 0; n < 2; ++n) _Pragma("unroll") for (int k = 0; k < 2; ++k) \
;         acc[ai][bj][m][n] = __builtin_amdgcn_mfma_f32_16x16x32_bf16(Bt[n][k], At[m][k], acc[ai][bj][m][n], 0, 0, 0); __builtin_amdgcn_s_setprio(0); } while (0)
; #define PG8_WAIT_V(n) asm volatile("s_waitcnt vmcnt(" #n ")" ::: "memory")
; #define PG8_WAIT_L(n) asm volatile("s_waitcnt lgkmcnt(" #n ")" ::: "memory")
; #define PG8_BAR __builtin_amdgcn_s_barrier()
; #define PG8_SCHED __builtin_amdgcn_sched_barrier(0)
; template <class Epi>
; DI void gemm_phase(LAS unsigned char* lds, const int wid, const Gemm g, const Order& S, const Epi& E) {
;     ...
;             PG8_WAIT_V(8); PG8_WAIT_L(0); PG8_BAR; PG8_MMA(1, 0, At, B0); PG8_MMA(1, 1, At, B1); PG8_BAR; PG8_SCHED;
;             PG8_LDB(B0, 1, 0); PG8_LDB(B1, 1, 1); PG8_SCHED; PG8_LDA(At, 1, 0); PG8_STAGE(PG8_SA(0, 1), a2 + hstepA, voffA);
;             PG8_WAIT_V(8); PG8_WAIT_L(0); PG8_BAR; PG8_MMA(0, 0, At, B0); PG8_MMA(0, 1, At, B1); PG8_BAR; PG8_SCHED;
	s_setprio 1
	s_waitcnt lgkmcnt(0)
	v_mfma_f32_16x16x32_bf16 v[60:63], v[128:131], v[160:163], 0
	v_mfma_f32_16x16x32_bf16 v[56:59], v[136:139], v[160:163], 0
	v_mfma_f32_16x16x32_bf16 v[44:47], v[128:131], v[168:171], 0
	v_mfma_f32_16x16x32_bf16 v[40:43], v[136:139], v[168:171], 0
	v_mfma_f32_16x16x32_bf16 v[28:31], v[128:131], v[192:195], 0
	v_mfma_f32_16x16x32_bf16 v[24:27], v[136:139], v[192:195], 0
	v_mfma_f32_16x16x32_bf16 v[12:15], v[128:131], v[200:203], 0
	v_mfma_f32_16x16x32_bf16 v[8:11], v[136:139], v[200:203], 0
	v_mfma_f32_16x16x32_bf16 v[60:63], v[132:135], v[164:167], v[60:63]
	v_mfma_f32_16x16x32_bf16 v[56:59], v[140:143], v[164:167], v[56:59]
	v_mfma_f32_16x16x32_bf16 v[44:47], v[132:135], v[172:175], v[44:47]
	v_mfma_f32_16x16x32_bf16 v[40:43], v[140:143], v[172:175], v[40:43]
	v_mfma_f32_16x16x32_bf16 v[28:31], v[132:135], v[196:199], v[28:31]
	v_mfma_f32_16x16x32_bf16 v[24:27], v[140:143], v[196:199], v[24:27]
	v_mfma_f32_16x16x32_bf16 v[12:15], v[132:135], v[204:207], v[12:15]
	v_mfma_f32_16x16x32_bf16 v[8:11], v[140:143], v[204:207], v[8:11]
	s_setprio 0
	s_setprio 1
	v_mfma_f32_16x16x32_bf16 v[52:55], v[144:147], v[160:163], 0
	v_mfma_f32_16x16x32_bf16 v[48:51], v[152:155], v[160:163], 0
	v_mfma_f32_16x16x32_bf16 v[36:39], v[144:147], v[168:171], 0
	v_mfma_f32_16x16x32_bf16 v[32:35], v[152:155], v[168:171], 0
	v_mfma_f32_16x16x32_bf16 v[20:23], v[144:147], v[192:195], 0
	v_mfma_f32_16x16x32_bf16 v[16:19], v[152:155], v[192:195], 0
	v_mfma_f32_16x16x32_bf16 v[4:7], v[144:147], v[200:203], 0
	v_mfma_f32_16x16x32_bf16 v[0:3], v[152:155], v[200:203], 0
	v_mfma_f32_16x16x32_bf16 v[52:55], v[148:151], v[164:167], v[52:55]
	v_mfma_f32_16x16x32_bf16 v[48:51], v[156:159], v[164:167], v[48:51]
	v_mfma_f32_16x16x32_bf16 v[36:39], v[148:151], v[172:175], v[36:39]
	v_mfma_f32_16x16x32_bf16 v[32:35], v[156:159], v[172:175], v[32:35]
	v_mfma_f32_16x16x32_bf16 v[20:23], v[148:151], v[196:199], v[20:23]
	v_mfma_f32_16x16x32_bf16 v[16:19], v[156:159], v[196:199], v[16:19]
	v_mfma_f32_16x16x32_bf16 v[4:7], v[148:151], v[204:207], v[4:7]
	v_mfma_f32_16x16x32_bf16 v[0:3], v[156:159], v[204:207], v[0:3]
	s_setprio 0
	s_barrier
	s_add_i32 s63, 0, 0x18000
	s_add_i32 s65, 0, 0x1c000
	v_add_u32_e32 v140, s63, v208
	v_add_u32_e32 v156, s65, v208
	ds_read_b128 v[128:131], v140
	ds_read_b128 v[132:135], v140 offset:1024
	ds_read_b128 v[136:139], v140 offset:2048
	ds_read_b128 v[140:143], v140 offset:3072
	ds_read_b128 v[144:147], v156
	ds_read_b128 v[148:151], v156 offset:1024
	ds_read_b128 v[152:155], v156 offset:2048
	ds_read_b128 v[156:159], v156 offset:3072
	s_add_u32 s50, s50, 0x40000
	s_addc_u32 s51, s51, 0
	s_mov_b32 m0, s52
	v_lshl_add_u64 v[222:223], s[50:51], 0, v[176:177]
	ds_read_b128 v[160:163], v211 offset:32768
	ds_read_b128 v[164:167], v211 offset:33792
	ds_read_b128 v[168:171], v211 offset:34816
	ds_read_b128 v[172:175], v211 offset:35840
	ds_read_b128 v[192:195], v211 offset:36864
	ds_read_b128 v[196:199], v211 offset:37888
	ds_read_b128 v[200:203], v211 offset:38912
	ds_read_b128 v[204:207], v211 offset:39936
	global_load_lds_dwordx4 v[222:223], off
	v_lshl_add_u64 v[222:223], s[50:51], 0, v[180:181]
	s_mov_b32 m0, s53
	s_nop 0
	global_load_lds_dwordx4 v[222:223], off
	s_waitcnt vmcnt(8)
	s_waitcnt lgkmcnt(0)
	s_barrier
	s_setprio 1
	s_waitcnt lgkmcnt(0)
	v_mfma_f32_16x16x32_bf16 v[124:127], v[128:131], v[160:163], v[124:127]
	v_mfma_f32_16x16x32_bf16 v[120:123], v[136:139], v[160:163], v[120:123]
	v_mfma_f32_16x16x32_bf16 v[108:111], v[128:131], v[168:171], v[108:111]
	v_mfma_f32_16x16x32_bf16 v[104:107], v[136:139], v[168:171], v[104:107]
	v_mfma_f32_16x16x32_bf16 v[92:95], v[128:131], v[192:195], v[92:95]
	v_mfma_f32_16x16x32_bf16 v[88:91], v[136:139], v[192:195], v[88:91]
	v_mfma_f32_16x16x32_bf16 v[76:79], v[128:131], v[200:203], v[76:79]
	v_mfma_f32_16x16x32_bf16 v[72:75], v[136:139], v[200:203], v[72:75]
	v_mfma_f32_16x16x32_bf16 v[124:127], v[132:135], v[164:167], v[124:127]
	v_mfma_f32_16x16x32_bf16 v[120:123], v[140:143], v[164:167], v[120:123]
	v_mfma_f32_16x16x32_bf16 v[108:111], v[132:135], v[172:175], v[108:111]
	v_mfma_f32_16x16x32_bf16 v[104:107], v[140:143], v[172:175], v[104:107]
	v_mfma_f32_16x16x32_bf16 v[92:95], v[132:135], v[196:199], v[92:95]
	v_mfma_f32_16x16x32_bf16 v[88:91], v[140:143], v[196:199], v[88:91]
	v_mfma_f32_16x16x32_bf16 v[76:79], v[132:135], v[204:207], v[76:79]
	v_mfma_f32_16x16x32_bf16 v[72:75], v[140:143], v[204:207], v[72:75]
	s_setprio 0
	s_setprio 1
	v_mfma_f32_16x16x32_bf16 v[116:119], v[144:147], v[160:163], v[116:119]
	v_mfma_f32_16x16x32_bf16 v[112:115], v[152:155], v[160:163], v[112:115]
	v_mfma_f32_16x16x32_bf16 v[100:103], v[144:147], v[168:171], v[100:103]
	v_mfma_f32_16x16x32_bf16 v[96:99], v[152:155], v[168:171], v[96:99]
	v_mfma_f32_16x16x32_bf16 v[84:87], v[144:147], v[192:195], v[84:87]
	v_mfma_f32_16x16x32_bf16 v[80:83], v[152:155], v[192:195], v[80:83]
	v_mfma_f32_16x16x32_bf16 v[68:71], v[144:147], v[200:203], v[68:71]
	v_mfma_f32_16x16x32_bf16 v[64:67], v[152:155], v[200:203], v[64:67]
	v_mfma_f32_16x16x32_bf16 v[116:119], v[148:151], v[164:167], v[116:119]
	v_mfma_f32_16x16x32_bf16 v[112:115], v[156:159], v[164:167], v[112:115]
	v_mfma_f32_16x16x32_bf16 v[100:103], v[148:151], v[172:175], v[100:103]
	v_mfma_f32_16x16x32_bf16 v[96:99], v[156:159], v[172:175], v[96:99]
	v_mfma_f32_16x16x32_bf16 v[84:87], v[148:151], v[196:199], v[84:87]
	v_mfma_f32_16x16x32_bf16 v[80:83], v[156:159], v[196:199], v[80:83]
	v_mfma_f32_16x16x32_bf16 v[68:71], v[148:151], v[204:207], v[68:71]
	v_mfma_f32_16x16x32_bf16 v[64:67], v[156:159], v[204:207], v[64:67]
	s_setprio 0
	s_barrier
; #define PG8_STAGE(bufoff, gbase, voff) do { _Pragma("unroll") for (int _i = 0; _i < 2; ++_i) \
;         __builtin_amdgcn_global_load_lds((const unsigned*)((const char*)(gbase) + (voff)[_i]), (LAS unsigned*)(lds + (bufoff) + ldsw + _i * 8192), 16, 0, 0); } while (0)
; #define PG8_LDA(dst, b, h) do { _Pragma("unroll") for (int m = 0; m < 4; ++m) _Pragma("unroll") for (int k = 0; k < 2; ++k) dst[m][k] = *(const LAS bf16x8*)(lds + PG8_SA(b, h) + aoff + m * 2048 + k * 1024); } while (0)
; #define PG8_MMA(ai, bj, At, Bt) do { __builtin_amdgcn_s_setprio(1); _Pragma("unroll") for (int m = 0; m < 4; ++m) _Pragma("unroll") for (int n = 0; n < 2; ++n) _Pragma("unroll") for (int k = 0; k < 2; ++k) \
;         acc[ai][bj][m][n] = __builtin_amdgcn_mfma_f32_16x16x32_bf16(Bt[n][k], At[m][k], acc[ai][bj][m][n], 0, 0, 0); __builtin_amdgcn_s_setprio(0); } while (0)
; #define PG8_WAIT_V(n) asm volatile("s_waitcnt vmcnt(" #n ")" ::: "memory")
; #define PG8_WAIT_L(n) asm volatile("s_waitcnt lgkmcnt(" #n ")" ::: "memory")
; #define PG8_BAR __builtin_amdgcn_s_barrier()
; #define PG8_SCHED __builtin_amdgcn_sched_barrier(0)
; template <class Epi>
; DI void gemm_phase(LAS unsigned char* lds, const int wid, const Gemm g, const Order& S, const Epi& E) {
;     ...
;             PG8_LDA(At, 1, 1); PG8_STAGE(PG8_SB(1, 0), b3, voffB); PG8_STAGE(PG8_SB(1, 1), b3 + hstepB, voffB); PG8_STAGE(PG8_SA(1, 0), a3, voffA);
;             PG8_WAIT_V(8); PG8_WAIT_L(0); PG8_BAR; PG8_MMA(1, 0, At, B0); PG8_MMA(1, 1, At, B1); PG8_BAR; PG8_SCHED;
	s_add_i32 s50, s63, s94
	v_lshl_add_u64 v[214:215], v[214:215], 0, s[30:31]
	s_mov_b32 m0, s50
	ds_read_b128 v[160:163], v211 offset:49152
	ds_read_b128 v[164:167], v211 offset:50176
	ds_read_b128 v[168:171], v211 offset:51200
	ds_read_b128 v[172:175], v211 offset:52224
	ds_read_b128 v[192:195], v211 offset:53248
	ds_read_b128 v[196:199], v211 offset:54272
	ds_read_b128 v[200:203], v211 offset:55296
	ds_read_b128 v[204:207], v211 offset:56320
	global_load_lds_dwordx4 v[214:215], off
	s_add_i32 m0, s50, 0x2000
	s_add_u32 s48, s48, 0x40080
	v_lshl_add_u64 v[214:215], v[216:217], 0, s[30:31]
	s_addc_u32 s49, s49, 0
	s_add_i32 s50, s65, s94
	global_load_lds_dwordx4 v[214:215], off
	v_lshl_add_u64 v[214:215], s[48:49], 0, v[178:179]
	s_mov_b32 m0, s50
	s_nop 0
	global_load_lds_dwordx4 v[214:215], off
	v_lshl_add_u64 v[214:215], s[48:49], 0, v[182:183]
	s_add_i32 m0, s50, 0x2000
	s_nop 0
	global_load_lds_dwordx4 v[214:215], off
	v_lshl_add_u64 v[214:215], v[218:219], 0, s[30:31]
	s_mov_b32 m0, s55
	s_nop 0
	global_load_lds_dwordx4 v[214:215], off
	v_lshl_add_u64 v[214:215], v[220:221], 0, s[30:31]
	s_mov_b32 m0, s56
	s_nop 0
	global_load_lds_dwordx4 v[214:215], off
	s_waitcnt vmcnt(8)
	s_waitcnt lgkmcnt(0)
	s_barrier
	s_setprio 1
	s_waitcnt lgkmcnt(0)
	v_mfma_f32_16x16x32_bf16 v[60:63], v[128:131], v[160:163], v[60:63]
	v_mfma_f32_16x16x32_bf16 v[56:59], v[136:139], v[160:163], v[56:59]
	v_mfma_f32_16x16x32_bf16 v[44:47], v[128:131], v[168:171], v[44:47]
	v_mfma_f32_16x16x32_bf16 v[40:43], v[136:139], v[168:171], v[40:43]
	v_mfma_f32_16x16x32_bf16 v[28:31], v[128:131], v[192:195], v[28:31]
	v_mfma_f32_16x16x32_bf16 v[24:27], v[136:139], v[192:195], v[24:27]
	v_mfma_f32_16x16x32_bf16 v[12:15], v[128:131], v[200:203], v[12:15]
	v_mfma_f32_16x16x32_bf16 v[8:11], v[136:139], v[200:203], v[8:11]
	v_mfma_f32_16x16x32_bf16 v[60:63], v[132:135], v[164:167], v[60:63]
	v_mfma_f32_16x16x32_bf16 v[56:59], v[140:143], v[164:167], v[56:59]
	v_mfma_f32_16x16x32_bf16 v[44:47], v[132:135], v[172:175], v[44:47]
	v_mfma_f32_16x16x32_bf16 v[40:43], v[140:143], v[172:175], v[40:43]
	v_mfma_f32_16x16x32_bf16 v[28:31], v[132:135], v[196:199], v[28:31]
	v_mfma_f32_16x16x32_bf16 v[24:27], v[140:143], v[196:199], v[24:27]
	v_mfma_f32_16x16x32_bf16 v[12:15], v[132:135], v[204:207], v[12:15]
	v_mfma_f32_16x16x32_bf16 v[8:11], v[140:143], v[204:207], v[8:11]
	s_setprio 0
	s_setprio 1
	v_mfma_f32_16x16x32_bf16 v[52:55], v[144:147], v[160:163], v[52:55]
	v_mfma_f32_16x16x32_bf16 v[48:51], v[152:155], v[160:163], v[48:51]
	v_mfma_f32_16x16x32_bf16 v[36:39], v[144:147], v[168:171], v[36:39]
	v_mfma_f32_16x16x32_bf16 v[32:35], v[152:155], v[168:171], v[32:35]
	v_mfma_f32_16x16x32_bf16 v[20:23], v[144:147], v[192:195], v[20:23]
	v_mfma_f32_16x16x32_bf16 v[16:19], v[152:155], v[192:195], v[16:19]
	v_mfma_f32_16x16x32_bf16 v[4:7], v[144:147], v[200:203], v[4:7]
	v_mfma_f32_16x16x32_bf16 v[0:3], v[152:155], v[200:203], v[0:3]
	v_mfma_f32_16x16x32_bf16 v[52:55], v[148:151], v[164:167], v[52:55]
	v_mfma_f32_16x16x32_bf16 v[48:51], v[156:159], v[164:167], v[48:51]
	v_mfma_f32_16x16x32_bf16 v[36:39], v[148:151], v[172:175], v[36:39]
	v_mfma_f32_16x16x32_bf16 v[32:35], v[156:159], v[172:175], v[32:35]
	v_mfma_f32_16x16x32_bf16 v[20:23], v[148:151], v[196:199], v[20:23]
	v_mfma_f32_16x16x32_bf16 v[16:19], v[156:159], v[196:199], v[16:19]
	v_mfma_f32_16x16x32_bf16 v[4:7], v[148:151], v[204:207], v[4:7]
	v_mfma_f32_16x16x32_bf16 v[0:3], v[156:159], v[204:207], v[0:3]
	s_setprio 0
	s_barrier
	s_add_i32 s62, s62, 2
	s_add_u32 s46, s46, 0x100
	s_addc_u32 s47, s47, 0
	s_add_u32 s60, s60, 0x100
	s_addc_u32 s61, s61, 0
	s_cmp_gt_u32 s62, 13
	s_cbranch_scc0 .LBB0_1250
	s_branch .Lpeel_exit_8

; #define PG8_STAGE(bufoff, gbase, voff) do { _Pragma("unroll") for (int _i = 0; _i < 2; ++_i) \
;         __builtin_amdgcn_global_load_lds((const unsigned*)((const char*)(gbase) + (voff)[_i]), (LAS unsigned*)(lds + (bufoff) + ldsw + _i * 8192), 16, 0, 0); } while (0)
; #define PG8_LDA(dst, b, h) do { _Pragma("unroll") for (int m = 0; m < 4; ++m) _Pragma("unroll") for (int k = 0; k < 2; ++k) dst[m][k] = *(const LAS bf16x8*)(lds + PG8_SA(b, h) + aoff + m * 2048 + k * 1024); } while (0)
; #define PG8_LDB(dst, b, h) do { _Pragma("unroll") for (int n = 0; n < 2; ++n) _Pragma("unroll") for (int k = 0; k < 2; ++k) dst[n][k] = *(const LAS bf16x8*)(lds + PG8_SB(b, h) + boff + n * 2048 + k * 1024); } while (0)
; #define PG8_MMA(ai, bj, At, Bt) do { __builtin_amdgcn_s_setprio(1); _Pragma("unroll") for (int m = 0; m < 4; ++m) _Pragma("unroll") for (int n = 0; n < 2; ++n) _Pragma("unroll") for (int k = 0; k < 2; ++k) \
;         acc[ai][bj][m][n] = __builtin_amdgcn_mfma_f32_16x16x32_bf16(Bt[n][k], At[m][k], acc[ai][bj][m][n], 0, 0, 0); __builtin_amdgcn_s_setprio(0); } while (0)
; #define PG8_WAIT_V(n) asm volatile("s_waitcnt vmcnt(" #n ")" ::: "memory")
; #define PG8_WAIT_L(n) asm volatile("s_waitcnt lgkmcnt(" #n ")" ::: "memory")
; #define PG8_BAR __builtin_amdgcn_s_barrier()
; template <class Epi>
; DI void gemm_phase(LAS unsigned char* lds, const int wid, const Gemm g, const Order& S, const Epi& E) {
;     ...
;             const bool last = (t == nt - 2);
;             const char* a1 = cA + (size_t)(t + 1) * kstep;
;             const char* a2 = last ? nA : cA + (size_t)(t + 2) * kstep; const char* b2 = last ? nB : cB + (size_t)(t + 2) * kstep;
;             const char* a3 = a2 + kstep; const char* b3 = b2 + kstep;
;             PG8_LDB(B0, 0, 0); PG8_LDB(B1, 0, 1); PG8_SCHED; PG8_LDA(At, 0, 0); PG8_STAGE(PG8_SA(1, 1), a1 + hstepA, voffA);
;             PG8_WAIT_V(8); PG8_WAIT_L(0); PG8_BAR; PG8_MMA(0, 0, At, B0); PG8_MMA(0, 1, At, B1); PG8_BAR; PG8_SCHED;
;             PG8_LDA(At, 0, 1); PG8_STAGE(PG8_SB(0, 0), b2, voffB); PG8_STAGE(PG8_SB(0, 1), b2 + hstepB, voffB); PG8_STAGE(PG8_SA(0, 0), a2, voffA);
;     ...
;         for (int a = 0; a < 2; ++a)
; #pragma unroll
;             for (int b = 0; b < 2; ++b)
; #pragma unroll
;                 for (int m = 0; m < 4; ++m)
; #pragma unroll
;                     for (int n = 0; n < 2; ++n) acc[a][b][m][n] = (f32x4){0.f, 0.f, 0.f, 0.f};
.LBB0_1335:
	s_ashr_i32 s27, s26, 31
	s_lshl_b64 s[30:31], s[26:27], 19
	s_add_u32 s30, s6, s30
	s_addc_u32 s31, s7, s31
	s_and_b64 s[34:35], s[8:9], exec
	s_cselect_b32 s27, s31, s39
	s_cselect_b32 s56, s30, s38
	s_ashr_i32 s29, s28, 31
	s_lshl_b64 s[34:35], s[28:29], 19
	s_add_u32 s34, s21, s34
	s_addc_u32 s35, s44, s35
	s_and_b64 s[42:43], s[8:9], exec
	s_cselect_b32 s29, s35, s41
	s_cselect_b32 s57, s34, s40
	s_add_u32 s38, s38, 0x40080
	s_addc_u32 s39, s39, 0
	s_add_u32 s58, s40, 0x100
	v_mov_b32_e32 v0, 0
	s_addc_u32 s59, s41, 0
	s_mov_b32 s60, -2
	ds_read_b128 v[164:167], v151
	ds_read_b128 v[168:171], v151 offset:1024
	ds_read_b128 v[172:175], v151 offset:2048
	ds_read_b128 v[176:179], v151 offset:3072
	ds_read_b128 v[180:183], v155
	ds_read_b128 v[184:187], v155 offset:1024
	ds_read_b128 v[188:191], v155 offset:2048
	ds_read_b128 v[192:195], v155 offset:3072
	s_add_u32 s40, s38, 0xfffc0080
	s_addc_u32 s41, s39, -1
	s_cmp_eq_u32 s60, 12
	s_cselect_b32 s43, s27, s41
	s_cselect_b32 s42, s56, s40
	s_cselect_b32 s41, s29, s59
	s_cselect_b32 s40, s57, s58
	v_lshl_add_u64 v[144:145], s[38:39], 0, v[136:137]
	s_add_i32 m0, s37, 0xc000
	ds_read_b128 v[196:199], v159
	ds_read_b128 v[200:203], v159 offset:1024
	ds_read_b128 v[204:207], v159 offset:2048
	ds_read_b128 v[208:211], v159 offset:3072
	ds_read_b128 v[212:215], v159 offset:4096
	ds_read_b128 v[216:219], v159 offset:5120
	ds_read_b128 v[220:223], v159 offset:6144
	ds_read_b128 v[224:227], v159 offset:7168
	global_load_lds_dwordx4 v[144:145], off
	v_lshl_add_u64 v[144:145], s[38:39], 0, v[138:139]
	s_add_i32 m0, s37, 0xe000
	s_nop 0
	global_load_lds_dwordx4 v[144:145], off
	s_waitcnt vmcnt(8)
	s_waitcnt lgkmcnt(0)
	s_barrier
	s_setprio 1
	s_waitcnt lgkmcnt(0)
	v_mfma_f32_16x16x32_bf16 v[124:127], v[164:167], v[196:199], 0
	v_mfma_f32_16x16x32_bf16 v[120:123], v[172:175], v[196:199], 0
	v_mfma_f32_16x16x32_bf16 v[108:111], v[164:167], v[204:207], 0
	v_mfma_f32_16x16x32_bf16 v[104:107], v[172:175], v[204:207], 0
	v_mfma_f32_16x16x32_bf16 v[92:95], v[164:167], v[212:215], 0
	v_mfma_f32_16x16x32_bf16 v[88:91], v[172:175], v[212:215], 0
	v_mfma_f32_16x16x32_bf16 v[76:79], v[164:167], v[220:223], 0
	v_mfma_f32_16x16x32_bf16 v[72:75], v[172:175], v[220:223], 0
	v_mfma_f32_16x16x32_bf16 v[124:127], v[168:171], v[200:203], v[124:127]
	v_mfma_f32_16x16x32_bf16 v[120:123], v[176:179], v[200:203], v[120:123]
	v_mfma_f32_16x16x32_bf16 v[108:111], v[168:171], v[208:211], v[108:111]
	v_mfma_f32_16x16x32_bf16 v[104:107], v[176:179], v[208:211], v[104:107]
	v_mfma_f32_16x16x32_bf16 v[92:95], v[168:171], v[216:219], v[92:95]
	v_mfma_f32_16x16x32_bf16 v[88:91], v[176:179], v[216:219], v[88:91]
	v_mfma_f32_16x16x32_bf16 v[76:79], v[168:171], v[224:227], v[76:79]
	v_mfma_f32_16x16x32_bf16 v[72:75], v[176:179], v[224:227], v[72:75]
	s_setprio 0
	s_setprio 1
	v_mfma_f32_16x16x32_bf16 v[116:119], v[180:183], v[196:199], 0
	v_mfma_f32_16x16x32_bf16 v[112:115], v[188:191], v[196:199], 0
	v_mfma_f32_16x16x32_bf16 v[100:103], v[180:183], v[204:207], 0
	v_mfma_f32_16x16x32_bf16 v[96:99], v[188:191], v[204:207], 0
	v_mfma_f32_16x16x32_bf16 v[84:87], v[180:183], v[212:215], 0
	v_mfma_f32_16x16x32_bf16 v[80:83], v[188:191], v[212:215], 0
	v_mfma_f32_16x16x32_bf16 v[68:71], v[180:183], v[220:223], 0
	v_mfma_f32_16x16x32_bf16 v[64:67], v[188:191], v[220:223], 0
	v_mfma_f32_16x16x32_bf16 v[116:119], v[184:187], v[200:203], v[116:119]
	v_mfma_f32_16x16x32_bf16 v[112:115], v[192:195], v[200:203], v[112:115]
	v_mfma_f32_16x16x32_bf16 v[100:103], v[184:187], v[208:211], v[100:103]
	v_mfma_f32_16x16x32_bf16 v[96:99], v[192:195], v[208:211], v[96:99]
	v_mfma_f32_16x16x32_bf16 v[84:87], v[184:187], v[216:219], v[84:87]
	v_mfma_f32_16x16x32_bf16 v[80:83], v[192:195], v[216:219], v[80:83]
	v_mfma_f32_16x16x32_bf16 v[68:71], v[184:187], v[224:227], v[68:71]
	v_mfma_f32_16x16x32_bf16 v[64:67], v[192:195], v[224:227], v[64:67]
	s_setprio 0
	s_barrier
	s_add_i32 s61, s53, s94
	v_lshl_add_u64 v[144:145], s[40:41], 0, v[132:133]
	s_mov_b32 m0, s61
	ds_read_b128 v[196:199], v159 offset:16384
	ds_read_b128 v[200:203], v159 offset:17408
	ds_read_b128 v[204:207], v159 offset:18432
	ds_read_b128 v[208:211], v159 offset:19456
	ds_read_b128 v[212:215], v159 offset:20480
	ds_read_b128 v[216:219], v159 offset:21504
	ds_read_b128 v[220:223], v159 offset:22528
	ds_read_b128 v[224:227], v159 offset:23552
	global_load_lds_dwordx4 v[144:145], off
	s_add_i32 m0, s61, 0x2000
	s_add_u32 s62, s40, 0x40000
	v_lshl_add_u64 v[148:149], s[40:41], 0, v[128:129]
	s_addc_u32 s63, s41, 0
	s_add_i32 s61, s54, s94
	global_load_lds_dwordx4 v[148:149], off
	v_lshl_add_u64 v[152:153], s[62:63], 0, v[132:133]
	s_mov_b32 m0, s61
	v_lshl_add_u64 v[156:157], s[42:43], 0, v[130:131]
	global_load_lds_dwordx4 v[152:153], off
	v_lshl_add_u64 v[152:153], s[62:63], 0, v[128:129]
	s_add_i32 m0, s61, 0x2000
	s_nop 0
	global_load_lds_dwordx4 v[152:153], off
	v_lshl_add_u64 v[152:153], s[42:43], 0, v[134:135]
	s_mov_b32 m0, s37
	s_nop 0
	global_load_lds_dwordx4 v[152:153], off
	s_mov_b32 m0, s46
	s_nop 0
	global_load_lds_dwordx4 v[156:157], off
	s_waitcnt vmcnt(8)
	s_waitcnt lgkmcnt(0)
	s_barrier
; #define PG8_STAGE(bufoff, gbase, voff) do { _Pragma("unroll") for (int _i = 0; _i < 2; ++_i) \
;         __builtin_amdgcn_global_load_lds((const unsigned*)((const char*)(gbase) + (voff)[_i]), (LAS unsigned*)(lds + (bufoff) + ldsw + _i * 8192), 16, 0, 0); } while (0)
; #define PG8_LDA(dst, b, h) do { _Pragma("unroll") for (int m = 0; m < 4; ++m) _Pragma("unroll") for (int k = 0; k < 2; ++k) dst[m][k] = *(const LAS bf16x8*)(lds + PG8_SA(b, h) + aoff + m * 2048 + k * 1024); } while (0)
; #define PG8_LDB(dst, b, h) do { _Pragma("unroll") for (int n = 0; n < 2; ++n) _Pragma("unroll") for (int k = 0; k < 2; ++k) dst[n][k] = *(const LAS bf16x8*)(lds + PG8_SB(b, h) + boff + n * 2048 + k * 1024); } while (0)
; #define PG8_MMA(ai, bj, At, Bt) do { __builtin_amdgcn_s_setprio(1); _Pragma("unroll") for (int m = 0; m < 4; ++m) _Pragma("unroll") for (int n = 0; n < 2; ++n) _Pragma("unroll") for (int k = 0; k < 2; ++k) \
;         acc[ai][bj][m][n] = __builtin_amdgcn_mfma_f32_16x16x32_bf16(Bt[n][k], At[m][k], acc[ai][bj][m][n], 0, 0, 0); __builtin_amdgcn_s_setprio(0); } while (0)
; #define PG8_WAIT_V(n) asm volatile("s_waitcnt vmcnt(" #n ")" ::: "memory")
; #define PG8_WAIT_L(n) asm volatile("s_waitcnt lgkmcnt(" #n ")" ::: "memory")
; #define PG8_BAR __builtin_amdgcn_s_barrier()
; #define PG8_SCHED __builtin_amdgcn_sched_barrier(0)
; template <class Epi>
; DI void gemm_phase(LAS unsigned char* lds, const int wid, const Gemm g, const Order& S, const Epi& E) {
;     ...
;             PG8_WAIT_V(8); PG8_WAIT_L(0); PG8_BAR; PG8_MMA(1, 0, At, B0); PG8_MMA(1, 1, At, B1); PG8_BAR; PG8_SCHED;
;             PG8_LDB(B0, 1, 0); PG8_LDB(B1, 1, 1); PG8_SCHED; PG8_LDA(At, 1, 0); PG8_STAGE(PG8_SA(0, 1), a2 + hstepA, voffA);
;             PG8_WAIT_V(8); PG8_WAIT_L(0); PG8_BAR; PG8_MMA(0, 0, At, B0); PG8_MMA(0, 1, At, B1); PG8_BAR; PG8_SCHED;
	s_setprio 1
	s_waitcnt lgkmcnt(0)
	v_mfma_f32_16x16x32_bf16 v[60:63], v[164:167], v[196:199], 0
	v_mfma_f32_16x16x32_bf16 v[56:59], v[172:175], v[196:199], 0
	v_mfma_f32_16x16x32_bf16 v[44:47], v[164:167], v[204:207], 0
	v_mfma_f32_16x16x32_bf16 v[40:43], v[172:175], v[204:207], 0
	v_mfma_f32_16x16x32_bf16 v[28:31], v[164:167], v[212:215], 0
	v_mfma_f32_16x16x32_bf16 v[24:27], v[172:175], v[212:215], 0
	v_mfma_f32_16x16x32_bf16 v[12:15], v[164:167], v[220:223], 0
	v_mfma_f32_16x16x32_bf16 v[8:11], v[172:175], v[220:223], 0
	v_mfma_f32_16x16x32_bf16 v[60:63], v[168:171], v[200:203], v[60:63]
	v_mfma_f32_16x16x32_bf16 v[56:59], v[176:179], v[200:203], v[56:59]
	v_mfma_f32_16x16x32_bf16 v[44:47], v[168:171], v[208:211], v[44:47]
	v_mfma_f32_16x16x32_bf16 v[40:43], v[176:179], v[208:211], v[40:43]
	v_mfma_f32_16x16x32_bf16 v[28:31], v[168:171], v[216:219], v[28:31]
	v_mfma_f32_16x16x32_bf16 v[24:27], v[176:179], v[216:219], v[24:27]
	v_mfma_f32_16x16x32_bf16 v[12:15], v[168:171], v[224:227], v[12:15]
	v_mfma_f32_16x16x32_bf16 v[8:11], v[176:179], v[224:227], v[8:11]
	s_setprio 0
	s_setprio 1
	v_mfma_f32_16x16x32_bf16 v[52:55], v[180:183], v[196:199], 0
	v_mfma_f32_16x16x32_bf16 v[48:51], v[188:191], v[196:199], 0
	v_mfma_f32_16x16x32_bf16 v[36:39], v[180:183], v[204:207], 0
	v_mfma_f32_16x16x32_bf16 v[32:35], v[188:191], v[204:207], 0
	v_mfma_f32_16x16x32_bf16 v[20:23], v[180:183], v[212:215], 0
	v_mfma_f32_16x16x32_bf16 v[16:19], v[188:191], v[212:215], 0
	v_mfma_f32_16x16x32_bf16 v[4:7], v[180:183], v[220:223], 0
	v_mfma_f32_16x16x32_bf16 v[0:3], v[188:191], v[220:223], 0
	v_mfma_f32_16x16x32_bf16 v[52:55], v[184:187], v[200:203], v[52:55]
	v_mfma_f32_16x16x32_bf16 v[48:51], v[192:195], v[200:203], v[48:51]
	v_mfma_f32_16x16x32_bf16 v[36:39], v[184:187], v[208:211], v[36:39]
	v_mfma_f32_16x16x32_bf16 v[32:35], v[192:195], v[208:211], v[32:35]
	v_mfma_f32_16x16x32_bf16 v[20:23], v[184:187], v[216:219], v[20:23]
	v_mfma_f32_16x16x32_bf16 v[16:19], v[192:195], v[216:219], v[16:19]
	v_mfma_f32_16x16x32_bf16 v[4:7], v[184:187], v[224:227], v[4:7]
	v_mfma_f32_16x16x32_bf16 v[0:3], v[192:195], v[224:227], v[0:3]
	s_setprio 0
	s_barrier
	s_add_i32 s61, 0, 0x18000
	v_add_u32_e32 v146, s61, v147
	s_add_i32 s62, 0, 0x1c000
	ds_read_b128 v[164:167], v146
	ds_read_b128 v[168:171], v146 offset:1024
	ds_read_b128 v[172:175], v146 offset:2048
	ds_read_b128 v[176:179], v146 offset:3072
	v_add_u32_e32 v146, s62, v147
	ds_read_b128 v[180:183], v146
	ds_read_b128 v[184:187], v146 offset:1024
	ds_read_b128 v[188:191], v146 offset:2048
	ds_read_b128 v[192:195], v146 offset:3072
	s_add_u32 s42, s42, 0x40000
	s_addc_u32 s43, s43, 0
	s_mov_b32 m0, s47
	v_lshl_add_u64 v[160:161], s[42:43], 0, v[134:135]
	ds_read_b128 v[196:199], v159 offset:32768
	ds_read_b128 v[200:203], v159 offset:33792
	ds_read_b128 v[204:207], v159 offset:34816
	ds_read_b128 v[208:211], v159 offset:35840
	ds_read_b128 v[212:215], v159 offset:36864
	ds_read_b128 v[216:219], v159 offset:37888
	ds_read_b128 v[220:223], v159 offset:38912
	ds_read_b128 v[224:227], v159 offset:39936
	global_load_lds_dwordx4 v[160:161], off
	v_lshl_add_u64 v[160:161], s[42:43], 0, v[130:131]
	s_mov_b32 m0, s48
	s_nop 0
	global_load_lds_dwordx4 v[160:161], off
	s_waitcnt vmcnt(8)
	s_waitcnt lgkmcnt(0)
	s_barrier
	s_setprio 1
	s_waitcnt lgkmcnt(0)
	v_mfma_f32_16x16x32_bf16 v[124:127], v[164:167], v[196:199], v[124:127]
	v_mfma_f32_16x16x32_bf16 v[120:123], v[172:175], v[196:199], v[120:123]
	v_mfma_f32_16x16x32_bf16 v[108:111], v[164:167], v[204:207], v[108:111]
	v_mfma_f32_16x16x32_bf16 v[104:107], v[172:175], v[204:207], v[104:107]
	v_mfma_f32_16x16x32_bf16 v[92:95], v[164:167], v[212:215], v[92:95]
	v_mfma_f32_16x16x32_bf16 v[88:91], v[172:175], v[212:215], v[88:91]
	v_mfma_f32_16x16x32_bf16 v[76:79], v[164:167], v[220:223], v[76:79]
	v_mfma_f32_16x16x32_bf16 v[72:75], v[172:175], v[220:223], v[72:75]
	v_mfma_f32_16x16x32_bf16 v[124:127], v[168:171], v[200:203], v[124:127]
	v_mfma_f32_16x16x32_bf16 v[120:123], v[176:179], v[200:203], v[120:123]
	v_mfma_f32_16x16x32_bf16 v[108:111], v[168:171], v[208:211], v[108:111]
	v_mfma_f32_16x16x32_bf16 v[104:107], v[176:179], v[208:211], v[104:107]
	v_mfma_f32_16x16x32_bf16 v[92:95], v[168:171], v[216:219], v[92:95]
	v_mfma_f32_16x16x32_bf16 v[88:91], v[176:179], v[216:219], v[88:91]
	v_mfma_f32_16x16x32_bf16 v[76:79], v[168:171], v[224:227], v[76:79]
	v_mfma_f32_16x16x32_bf16 v[72:75], v[176:179], v[224:227], v[72:75]
	s_setprio 0
	s_setprio 1
	v_mfma_f32_16x16x32_bf16 v[116:119], v[180:183], v[196:199], v[116:119]
	v_mfma_f32_16x16x32_bf16 v[112:115], v[188:191], v[196:199], v[112:115]
	v_mfma_f32_16x16x32_bf16 v[100:103], v[180:183], v[204:207], v[100:103]
	v_mfma_f32_16x16x32_bf16 v[96:99], v[188:191], v[204:207], v[96:99]
	v_mfma_f32_16x16x32_bf16 v[84:87], v[180:183], v[212:215], v[84:87]
	v_mfma_f32_16x16x32_bf16 v[80:83], v[188:191], v[212:215], v[80:83]
	v_mfma_f32_16x16x32_bf16 v[68:71], v[180:183], v[220:223], v[68:71]
	v_mfma_f32_16x16x32_bf16 v[64:67], v[188:191], v[220:223], v[64:67]
	v_mfma_f32_16x16x32_bf16 v[116:119], v[184:187], v[200:203], v[116:119]
	v_mfma_f32_16x16x32_bf16 v[112:115], v[192:195], v[200:203], v[112:115]
	v_mfma_f32_16x16x32_bf16 v[100:103], v[184:187], v[208:211], v[100:103]
	v_mfma_f32_16x16x32_bf16 v[96:99], v[192:195], v[208:211], v[96:99]
	v_mfma_f32_16x16x32_bf16 v[84:87], v[184:187], v[216:219], v[84:87]
	v_mfma_f32_16x16x32_bf16 v[80:83], v[192:195], v[216:219], v[80:83]
	v_mfma_f32_16x16x32_bf16 v[68:71], v[184:187], v[224:227], v[68:71]
	v_mfma_f32_16x16x32_bf16 v[64:67], v[192:195], v[224:227], v[64:67]
	s_setprio 0
	s_barrier
; #define PG8_STAGE(bufoff, gbase, voff) do { _Pragma("unroll") for (int _i = 0; _i < 2; ++_i) \
;         __builtin_amdgcn_global_load_lds((const unsigned*)((const char*)(gbase) + (voff)[_i]), (LAS unsigned*)(lds + (bufoff) + ldsw + _i * 8192), 16, 0, 0); } while (0)
; #define PG8_LDA(dst, b, h) do { _Pragma("unroll") for (int m = 0; m < 4; ++m) _Pragma("unroll") for (int k = 0; k < 2; ++k) dst[m][k] = *(const LAS bf16x8*)(lds + PG8_SA(b, h) + aoff + m * 2048 + k * 1024); } while (0)
; #define PG8_MMA(ai, bj, At, Bt) do { __builtin_amdgcn_s_setprio(1); _Pragma("unroll") for (int m = 0; m < 4; ++m) _Pragma("unroll") for (int n = 0; n < 2; ++n) _Pragma("unroll") for (int k = 0; k < 2; ++k) \
;         acc[ai][bj][m][n] = __builtin_amdgcn_mfma_f32_16x16x32_bf16(Bt[n][k], At[m][k], acc[ai][bj][m][n], 0, 0, 0); __builtin_amdgcn_s_setprio(0); } while (0)
; #define PG8_WAIT_V(n) asm volatile("s_waitcnt vmcnt(" #n ")" ::: "memory")
; #define PG8_WAIT_L(n) asm volatile("s_waitcnt lgkmcnt(" #n ")" ::: "memory")
; #define PG8_BAR __builtin_amdgcn_s_barrier()
; #define PG8_SCHED __builtin_amdgcn_sched_barrier(0)
; template <class Epi>
; DI void gemm_phase(LAS unsigned char* lds, const int wid, const Gemm g, const Order& S, const Epi& E) {
;     ...
;             PG8_LDA(At, 1, 1); PG8_STAGE(PG8_SB(1, 0), b3, voffB); PG8_STAGE(PG8_SB(1, 1), b3 + hstepB, voffB); PG8_STAGE(PG8_SA(1, 0), a3, voffA);
;             PG8_WAIT_V(8); PG8_WAIT_L(0); PG8_BAR; PG8_MMA(1, 0, At, B0); PG8_MMA(1, 1, At, B1); PG8_BAR; PG8_SCHED;
	s_add_i32 s42, s61, s94
	v_lshl_add_u64 v[144:145], v[144:145], 0, s[16:17]
	s_mov_b32 m0, s42
	ds_read_b128 v[196:199], v159 offset:49152
	ds_read_b128 v[200:203], v159 offset:50176
	ds_read_b128 v[204:207], v159 offset:51200
	ds_read_b128 v[208:211], v159 offset:52224
	ds_read_b128 v[212:215], v159 offset:53248
	ds_read_b128 v[216:219], v159 offset:54272
	ds_read_b128 v[220:223], v159 offset:55296
	ds_read_b128 v[224:227], v159 offset:56320
	global_load_lds_dwordx4 v[144:145], off
	s_add_i32 m0, s42, 0x2000
	s_add_u32 s40, s40, 0x40080
	v_lshl_add_u64 v[144:145], v[148:149], 0, s[16:17]
	s_addc_u32 s41, s41, 0
	s_add_i32 s42, s62, s94
	global_load_lds_dwordx4 v[144:145], off
	v_lshl_add_u64 v[144:145], s[40:41], 0, v[132:133]
	s_mov_b32 m0, s42
	s_nop 0
	global_load_lds_dwordx4 v[144:145], off
	v_lshl_add_u64 v[144:145], s[40:41], 0, v[128:129]
	s_add_i32 m0, s42, 0x2000
	s_nop 0
	global_load_lds_dwordx4 v[144:145], off
	v_lshl_add_u64 v[144:145], v[152:153], 0, s[16:17]
	s_mov_b32 m0, s51
	s_nop 0
	global_load_lds_dwordx4 v[144:145], off
	v_lshl_add_u64 v[144:145], v[156:157], 0, s[16:17]
	s_mov_b32 m0, s52
	s_nop 0
	global_load_lds_dwordx4 v[144:145], off
	s_waitcnt vmcnt(8)
	s_waitcnt lgkmcnt(0)
	s_barrier
	s_setprio 1
	s_waitcnt lgkmcnt(0)
	v_mfma_f32_16x16x32_bf16 v[60:63], v[164:167], v[196:199], v[60:63]
	v_mfma_f32_16x16x32_bf16 v[56:59], v[172:175], v[196:199], v[56:59]
	v_mfma_f32_16x16x32_bf16 v[44:47], v[164:167], v[204:207], v[44:47]
	v_mfma_f32_16x16x32_bf16 v[40:43], v[172:175], v[204:207], v[40:43]
	v_mfma_f32_16x16x32_bf16 v[28:31], v[164:167], v[212:215], v[28:31]
	v_mfma_f32_16x16x32_bf16 v[24:27], v[172:175], v[212:215], v[24:27]
	v_mfma_f32_16x16x32_bf16 v[12:15], v[164:167], v[220:223], v[12:15]
	v_mfma_f32_16x16x32_bf16 v[8:11], v[172:175], v[220:223], v[8:11]
	v_mfma_f32_16x16x32_bf16 v[60:63], v[168:171], v[200:203], v[60:63]
	v_mfma_f32_16x16x32_bf16 v[56:59], v[176:179], v[200:203], v[56:59]
	v_mfma_f32_16x16x32_bf16 v[44:47], v[168:171], v[208:211], v[44:47]
	v_mfma_f32_16x16x32_bf16 v[40:43], v[176:179], v[208:211], v[40:43]
	v_mfma_f32_16x16x32_bf16 v[28:31], v[168:171], v[216:219], v[28:31]
	v_mfma_f32_16x16x32_bf16 v[24:27], v[176:179], v[216:219], v[24:27]
	v_mfma_f32_16x16x32_bf16 v[12:15], v[168:171], v[224:227], v[12:15]
	v_mfma_f32_16x16x32_bf16 v[8:11], v[176:179], v[224:227], v[8:11]
	s_setprio 0
	s_setprio 1
	v_mfma_f32_16x16x32_bf16 v[52:55], v[180:183], v[196:199], v[52:55]
	v_mfma_f32_16x16x32_bf16 v[48:51], v[188:191], v[196:199], v[48:51]
	v_mfma_f32_16x16x32_bf16 v[36:39], v[180:183], v[204:207], v[36:39]
	v_mfma_f32_16x16x32_bf16 v[32:35], v[188:191], v[204:207], v[32:35]
	v_mfma_f32_16x16x32_bf16 v[20:23], v[180:183], v[212:215], v[20:23]
	v_mfma_f32_16x16x32_bf16 v[16:19], v[188:191], v[212:215], v[16:19]
	v_mfma_f32_16x16x32_bf16 v[4:7], v[180:183], v[220:223], v[4:7]
	v_mfma_f32_16x16x32_bf16 v[0:3], v[188:191], v[220:223], v[0:3]
	v_mfma_f32_16x16x32_bf16 v[52:55], v[184:187], v[200:203], v[52:55]
	v_mfma_f32_16x16x32_bf16 v[48:51], v[192:195], v[200:203], v[48:51]
	v_mfma_f32_16x16x32_bf16 v[36:39], v[184:187], v[208:211], v[36:39]
	v_mfma_f32_16x16x32_bf16 v[32:35], v[192:195], v[208:211], v[32:35]
	v_mfma_f32_16x16x32_bf16 v[20:23], v[184:187], v[216:219], v[20:23]
	v_mfma_f32_16x16x32_bf16 v[16:19], v[192:195], v[216:219], v[16:19]
	v_mfma_f32_16x16x32_bf16 v[4:7], v[184:187], v[224:227], v[4:7]
	v_mfma_f32_16x16x32_bf16 v[0:3], v[192:195], v[224:227], v[0:3]
	s_setprio 0
	s_barrier
	s_add_i32 s60, s60, 2
	s_add_u32 s38, s38, 0x100
	s_addc_u32 s39, s39, 0
	s_add_u32 s58, s58, 0x100
	s_addc_u32 s59, s59, 0
	s_cmp_gt_u32 s60, 13
	s_cbranch_scc0 .LBB0_1336
	s_branch .Lpeel_exit_9

; #define PG8_BAR __builtin_amdgcn_s_barrier()
; template <class Epi>
; DI void gemm_phase(LAS unsigned char* lds, const int wid, const Gemm g, const Order& S, const Epi& E) {
;     ...
;         if (wr == 0) PG8_BAR;
.Lpeel_exit_9:
	s_and_b64 vcc, exec, s[24:25]
	s_cbranch_vccz .LBB0_1339
	s_barrier

; #define PG8_STAGE(bufoff, gbase, voff) do { _Pragma("unroll") for (int _i = 0; _i < 2; ++_i) \
;         __builtin_amdgcn_global_load_lds((const unsigned*)((const char*)(gbase) + (voff)[_i]), (LAS unsigned*)(lds + (bufoff) + ldsw + _i * 8192), 16, 0, 0); } while (0)
; #define PG8_LDA(dst, b, h) do { _Pragma("unroll") for (int m = 0; m < 4; ++m) _Pragma("unroll") for (int k = 0; k < 2; ++k) dst[m][k] = *(const LAS bf16x8*)(lds + PG8_SA(b, h) + aoff + m * 2048 + k * 1024); } while (0)
; #define PG8_LDB(dst, b, h) do { _Pragma("unroll") for (int n = 0; n < 2; ++n) _Pragma("unroll") for (int k = 0; k < 2; ++k) dst[n][k] = *(const LAS bf16x8*)(lds + PG8_SB(b, h) + boff + n * 2048 + k * 1024); } while (0)
; #define PG8_MMA(ai, bj, At, Bt) do { __builtin_amdgcn_s_setprio(1); _Pragma("unroll") for (int m = 0; m < 4; ++m) _Pragma("unroll") for (int n = 0; n < 2; ++n) _Pragma("unroll") for (int k = 0; k < 2; ++k) \
;         acc[ai][bj][m][n] = __builtin_amdgcn_mfma_f32_16x16x32_bf16(Bt[n][k], At[m][k], acc[ai][bj][m][n], 0, 0, 0); __builtin_amdgcn_s_setprio(0); } while (0)
; #define PG8_WAIT_V(n) asm volatile("s_waitcnt vmcnt(" #n ")" ::: "memory")
; #define PG8_WAIT_L(n) asm volatile("s_waitcnt lgkmcnt(" #n ")" ::: "memory")
; #define PG8_BAR __builtin_amdgcn_s_barrier()
; template <class Epi>
; DI void gemm_phase(LAS unsigned char* lds, const int wid, const Gemm g, const Order& S, const Epi& E) {
;     ...
;             const bool last = (t == nt - 2);
;             const char* a1 = cA + (size_t)(t + 1) * kstep;
;             const char* a2 = last ? nA : cA + (size_t)(t + 2) * kstep; const char* b2 = last ? nB : cB + (size_t)(t + 2) * kstep;
;             const char* a3 = a2 + kstep; const char* b3 = b2 + kstep;
;             PG8_LDB(B0, 0, 0); PG8_LDB(B1, 0, 1); PG8_SCHED; PG8_LDA(At, 0, 0); PG8_STAGE(PG8_SA(1, 1), a1 + hstepA, voffA);
;             PG8_WAIT_V(8); PG8_WAIT_L(0); PG8_BAR; PG8_MMA(0, 0, At, B0); PG8_MMA(0, 1, At, B1); PG8_BAR; PG8_SCHED;
;             PG8_LDA(At, 0, 1); PG8_STAGE(PG8_SB(0, 0), b2, voffB); PG8_STAGE(PG8_SB(0, 1), b2 + hstepB, voffB); PG8_STAGE(PG8_SA(0, 0), a2, voffA);
;     ...
;         for (int a = 0; a < 2; ++a)
; #pragma unroll
;             for (int b = 0; b < 2; ++b)
; #pragma unroll
;                 for (int m = 0; m < 4; ++m)
; #pragma unroll
;                     for (int n = 0; n < 2; ++n) acc[a][b][m][n] = (f32x4){0.f, 0.f, 0.f, 0.f};
.LBB0_1420:
	s_add_u32 s56, s38, 0x100
	v_mov_b32_e32 v0, 0
	s_addc_u32 s57, s39, 0
	s_mov_b32 s58, -2
	s_waitcnt lgkmcnt(0)
	ds_read_b128 v[128:131], v216
	ds_read_b128 v[132:135], v216 offset:1024
	ds_read_b128 v[136:139], v216 offset:2048
	ds_read_b128 v[140:143], v216 offset:3072
	ds_read_b128 v[144:147], v217
	ds_read_b128 v[148:151], v217 offset:1024
	ds_read_b128 v[152:155], v217 offset:2048
	ds_read_b128 v[156:159], v217 offset:3072
	s_add_u32 s10, s36, 0x100
	s_addc_u32 s11, s37, 0
	s_cmp_eq_u32 s58, 40
	s_cselect_b32 s41, s31, s11
	s_cselect_b32 s40, s30, s10
	s_cselect_b32 s39, s35, s57
	s_cselect_b32 s38, s34, s56
	v_lshl_add_u64 v[208:209], s[36:37], 0, v[184:185]
	s_add_i32 m0, s43, 0xc000
	ds_read_b128 v[160:163], v218
	ds_read_b128 v[164:167], v218 offset:1024
	ds_read_b128 v[168:171], v218 offset:2048
	ds_read_b128 v[172:175], v218 offset:3072
	ds_read_b128 v[192:195], v218 offset:4096
	ds_read_b128 v[196:199], v218 offset:5120
	ds_read_b128 v[200:203], v218 offset:6144
	ds_read_b128 v[204:207], v218 offset:7168
	global_load_lds_dwordx4 v[208:209], off
	v_lshl_add_u64 v[208:209], s[36:37], 0, v[186:187]
	s_add_i32 m0, s43, 0xe000
	s_nop 0
	global_load_lds_dwordx4 v[208:209], off
	s_waitcnt vmcnt(8)
	s_waitcnt lgkmcnt(0)
	s_barrier
	s_setprio 1
	s_waitcnt lgkmcnt(0)
	v_mfma_f32_16x16x32_bf16 v[124:127], v[128:131], v[160:163], 0
	v_mfma_f32_16x16x32_bf16 v[120:123], v[136:139], v[160:163], 0
	v_mfma_f32_16x16x32_bf16 v[108:111], v[128:131], v[168:171], 0
	v_mfma_f32_16x16x32_bf16 v[104:107], v[136:139], v[168:171], 0
	v_mfma_f32_16x16x32_bf16 v[92:95], v[128:131], v[192:195], 0
	v_mfma_f32_16x16x32_bf16 v[88:91], v[136:139], v[192:195], 0
	v_mfma_f32_16x16x32_bf16 v[76:79], v[128:131], v[200:203], 0
	v_mfma_f32_16x16x32_bf16 v[72:75], v[136:139], v[200:203], 0
	v_mfma_f32_16x16x32_bf16 v[124:127], v[132:135], v[164:167], v[124:127]
	v_mfma_f32_16x16x32_bf16 v[120:123], v[140:143], v[164:167], v[120:123]
	v_mfma_f32_16x16x32_bf16 v[108:111], v[132:135], v[172:175], v[108:111]
	v_mfma_f32_16x16x32_bf16 v[104:107], v[140:143], v[172:175], v[104:107]
	v_mfma_f32_16x16x32_bf16 v[92:95], v[132:135], v[196:199], v[92:95]
	v_mfma_f32_16x16x32_bf16 v[88:91], v[140:143], v[196:199], v[88:91]
	v_mfma_f32_16x16x32_bf16 v[76:79], v[132:135], v[204:207], v[76:79]
	v_mfma_f32_16x16x32_bf16 v[72:75], v[140:143], v[204:207], v[72:75]
	s_setprio 0
	s_setprio 1
	v_mfma_f32_16x16x32_bf16 v[116:119], v[144:147], v[160:163], 0
	v_mfma_f32_16x16x32_bf16 v[112:115], v[152:155], v[160:163], 0
	v_mfma_f32_16x16x32_bf16 v[100:103], v[144:147], v[168:171], 0
	v_mfma_f32_16x16x32_bf16 v[96:99], v[152:155], v[168:171], 0
	v_mfma_f32_16x16x32_bf16 v[84:87], v[144:147], v[192:195], 0
	v_mfma_f32_16x16x32_bf16 v[80:83], v[152:155], v[192:195], 0
	v_mfma_f32_16x16x32_bf16 v[68:71], v[144:147], v[200:203], 0
	v_mfma_f32_16x16x32_bf16 v[64:67], v[152:155], v[200:203], 0
	v_mfma_f32_16x16x32_bf16 v[116:119], v[148:151], v[164:167], v[116:119]
	v_mfma_f32_16x16x32_bf16 v[112:115], v[156:159], v[164:167], v[112:115]
	v_mfma_f32_16x16x32_bf16 v[100:103], v[148:151], v[172:175], v[100:103]
	v_mfma_f32_16x16x32_bf16 v[96:99], v[156:159], v[172:175], v[96:99]
	v_mfma_f32_16x16x32_bf16 v[84:87], v[148:151], v[196:199], v[84:87]
	v_mfma_f32_16x16x32_bf16 v[80:83], v[156:159], v[196:199], v[80:83]
	v_mfma_f32_16x16x32_bf16 v[68:71], v[148:151], v[204:207], v[68:71]
	v_mfma_f32_16x16x32_bf16 v[64:67], v[156:159], v[204:207], v[64:67]
	s_setprio 0
	s_barrier
	s_add_i32 s36, s50, s94
	v_lshl_add_u64 v[208:209], s[38:39], 0, v[178:179]
	s_mov_b32 m0, s36
	ds_read_b128 v[160:163], v218 offset:16384
	ds_read_b128 v[164:167], v218 offset:17408
	ds_read_b128 v[168:171], v218 offset:18432
	ds_read_b128 v[172:175], v218 offset:19456
	ds_read_b128 v[192:195], v218 offset:20480
	ds_read_b128 v[196:199], v218 offset:21504
	ds_read_b128 v[200:203], v218 offset:22528
	ds_read_b128 v[204:207], v218 offset:23552
	global_load_lds_dwordx4 v[208:209], off
	s_add_i32 m0, s36, 0x2000
	s_add_u32 s36, s38, 0xb0000
	v_lshl_add_u64 v[210:211], s[38:39], 0, v[182:183]
	s_addc_u32 s37, s39, 0
	s_add_i32 s59, s51, s94
	global_load_lds_dwordx4 v[210:211], off
	v_lshl_add_u64 v[212:213], s[36:37], 0, v[178:179]
	s_mov_b32 m0, s59
	v_lshl_add_u64 v[220:221], s[40:41], 0, v[180:181]
	global_load_lds_dwordx4 v[212:213], off
	v_lshl_add_u64 v[212:213], s[36:37], 0, v[182:183]
	s_add_i32 m0, s59, 0x2000
	s_nop 0
	global_load_lds_dwordx4 v[212:213], off
	v_lshl_add_u64 v[212:213], s[40:41], 0, v[176:177]
	s_mov_b32 m0, s43
	s_nop 0
	global_load_lds_dwordx4 v[212:213], off
	s_mov_b32 m0, s44
	s_nop 0
	global_load_lds_dwordx4 v[220:221], off
	s_waitcnt vmcnt(8)
	s_waitcnt lgkmcnt(0)
	s_barrier
; #define PG8_STAGE(bufoff, gbase, voff) do { _Pragma("unroll") for (int _i = 0; _i < 2; ++_i) \
;         __builtin_amdgcn_global_load_lds((const unsigned*)((const char*)(gbase) + (voff)[_i]), (LAS unsigned*)(lds + (bufoff) + ldsw + _i * 8192), 16, 0, 0); } while (0)
; #define PG8_LDA(dst, b, h) do { _Pragma("unroll") for (int m = 0; m < 4; ++m) _Pragma("unroll") for (int k = 0; k < 2; ++k) dst[m][k] = *(const LAS bf16x8*)(lds + PG8_SA(b, h) + aoff + m * 2048 + k * 1024); } while (0)
; #define PG8_LDB(dst, b, h) do { _Pragma("unroll") for (int n = 0; n < 2; ++n) _Pragma("unroll") for (int k = 0; k < 2; ++k) dst[n][k] = *(const LAS bf16x8*)(lds + PG8_SB(b, h) + boff + n * 2048 + k * 1024); } while (0)
; #define PG8_MMA(ai, bj, At, Bt) do { __builtin_amdgcn_s_setprio(1); _Pragma("unroll") for (int m = 0; m < 4; ++m) _Pragma("unroll") for (int n = 0; n < 2; ++n) _Pragma("unroll") for (int k = 0; k < 2; ++k) \
;         acc[ai][bj][m][n] = __builtin_amdgcn_mfma_f32_16x16x32_bf16(Bt[n][k], At[m][k], acc[ai][bj][m][n], 0, 0, 0); __builtin_amdgcn_s_setprio(0); } while (0)
; #define PG8_WAIT_V(n) asm volatile("s_waitcnt vmcnt(" #n ")" ::: "memory")
; #define PG8_WAIT_L(n) asm volatile("s_waitcnt lgkmcnt(" #n ")" ::: "memory")
; #define PG8_BAR __builtin_amdgcn_s_barrier()
; #define PG8_SCHED __builtin_amdgcn_sched_barrier(0)
; template <class Epi>
; DI void gemm_phase(LAS unsigned char* lds, const int wid, const Gemm g, const Order& S, const Epi& E) {
;     ...
;             PG8_WAIT_V(8); PG8_WAIT_L(0); PG8_BAR; PG8_MMA(1, 0, At, B0); PG8_MMA(1, 1, At, B1); PG8_BAR; PG8_SCHED;
;             PG8_LDB(B0, 1, 0); PG8_LDB(B1, 1, 1); PG8_SCHED; PG8_LDA(At, 1, 0); PG8_STAGE(PG8_SA(0, 1), a2 + hstepA, voffA);
;             PG8_WAIT_V(8); PG8_WAIT_L(0); PG8_BAR; PG8_MMA(0, 0, At, B0); PG8_MMA(0, 1, At, B1); PG8_BAR; PG8_SCHED;
	s_setprio 1
	s_waitcnt lgkmcnt(0)
	v_mfma_f32_16x16x32_bf16 v[60:63], v[128:131], v[160:163], 0
	v_mfma_f32_16x16x32_bf16 v[56:59], v[136:139], v[160:163], 0
	v_mfma_f32_16x16x32_bf16 v[44:47], v[128:131], v[168:171], 0
	v_mfma_f32_16x16x32_bf16 v[40:43], v[136:139], v[168:171], 0
	v_mfma_f32_16x16x32_bf16 v[28:31], v[128:131], v[192:195], 0
	v_mfma_f32_16x16x32_bf16 v[24:27], v[136:139], v[192:195], 0
	v_mfma_f32_16x16x32_bf16 v[12:15], v[128:131], v[200:203], 0
	v_mfma_f32_16x16x32_bf16 v[8:11], v[136:139], v[200:203], 0
	v_mfma_f32_16x16x32_bf16 v[60:63], v[132:135], v[164:167], v[60:63]
	v_mfma_f32_16x16x32_bf16 v[56:59], v[140:143], v[164:167], v[56:59]
	v_mfma_f32_16x16x32_bf16 v[44:47], v[132:135], v[172:175], v[44:47]
	v_mfma_f32_16x16x32_bf16 v[40:43], v[140:143], v[172:175], v[40:43]
	v_mfma_f32_16x16x32_bf16 v[28:31], v[132:135], v[196:199], v[28:31]
	v_mfma_f32_16x16x32_bf16 v[24:27], v[140:143], v[196:199], v[24:27]
	v_mfma_f32_16x16x32_bf16 v[12:15], v[132:135], v[204:207], v[12:15]
	v_mfma_f32_16x16x32_bf16 v[8:11], v[140:143], v[204:207], v[8:11]
	s_setprio 0
	s_setprio 1
	v_mfma_f32_16x16x32_bf16 v[52:55], v[144:147], v[160:163], 0
	v_mfma_f32_16x16x32_bf16 v[48:51], v[152:155], v[160:163], 0
	v_mfma_f32_16x16x32_bf16 v[36:39], v[144:147], v[168:171], 0
	v_mfma_f32_16x16x32_bf16 v[32:35], v[152:155], v[168:171], 0
	v_mfma_f32_16x16x32_bf16 v[20:23], v[144:147], v[192:195], 0
	v_mfma_f32_16x16x32_bf16 v[16:19], v[152:155], v[192:195], 0
	v_mfma_f32_16x16x32_bf16 v[4:7], v[144:147], v[200:203], 0
	v_mfma_f32_16x16x32_bf16 v[0:3], v[152:155], v[200:203], 0
	v_mfma_f32_16x16x32_bf16 v[52:55], v[148:151], v[164:167], v[52:55]
	v_mfma_f32_16x16x32_bf16 v[48:51], v[156:159], v[164:167], v[48:51]
	v_mfma_f32_16x16x32_bf16 v[36:39], v[148:151], v[172:175], v[36:39]
	v_mfma_f32_16x16x32_bf16 v[32:35], v[156:159], v[172:175], v[32:35]
	v_mfma_f32_16x16x32_bf16 v[20:23], v[148:151], v[196:199], v[20:23]
	v_mfma_f32_16x16x32_bf16 v[16:19], v[156:159], v[196:199], v[16:19]
	v_mfma_f32_16x16x32_bf16 v[4:7], v[148:151], v[204:207], v[4:7]
	v_mfma_f32_16x16x32_bf16 v[0:3], v[156:159], v[204:207], v[0:3]
	s_setprio 0
	s_barrier
	s_add_i32 s59, 0, 0x18000
	s_add_i32 s60, 0, 0x1c000
	v_add_u32_e32 v140, s59, v215
	v_add_u32_e32 v156, s60, v215
	ds_read_b128 v[128:131], v140
	ds_read_b128 v[132:135], v140 offset:1024
	ds_read_b128 v[136:139], v140 offset:2048
	ds_read_b128 v[140:143], v140 offset:3072
	ds_read_b128 v[144:147], v156
	ds_read_b128 v[148:151], v156 offset:1024
	ds_read_b128 v[152:155], v156 offset:2048
	ds_read_b128 v[156:159], v156 offset:3072
	s_add_u32 s36, s40, 0xb0000
	s_addc_u32 s37, s41, 0
	s_mov_b32 m0, s45
	v_lshl_add_u64 v[222:223], s[36:37], 0, v[176:177]
	ds_read_b128 v[160:163], v218 offset:32768
	ds_read_b128 v[164:167], v218 offset:33792
	ds_read_b128 v[168:171], v218 offset:34816
	ds_read_b128 v[172:175], v218 offset:35840
	ds_read_b128 v[192:195], v218 offset:36864
	ds_read_b128 v[196:199], v218 offset:37888
	ds_read_b128 v[200:203], v218 offset:38912
	ds_read_b128 v[204:207], v218 offset:39936
	global_load_lds_dwordx4 v[222:223], off
	v_lshl_add_u64 v[222:223], s[36:37], 0, v[180:181]
	s_mov_b32 m0, s46
	s_nop 0
	global_load_lds_dwordx4 v[222:223], off
	s_waitcnt vmcnt(8)
	s_waitcnt lgkmcnt(0)
	s_barrier
	s_setprio 1
	s_waitcnt lgkmcnt(0)
	v_mfma_f32_16x16x32_bf16 v[124:127], v[128:131], v[160:163], v[124:127]
	v_mfma_f32_16x16x32_bf16 v[120:123], v[136:139], v[160:163], v[120:123]
	v_mfma_f32_16x16x32_bf16 v[108:111], v[128:131], v[168:171], v[108:111]
	v_mfma_f32_16x16x32_bf16 v[104:107], v[136:139], v[168:171], v[104:107]
	v_mfma_f32_16x16x32_bf16 v[92:95], v[128:131], v[192:195], v[92:95]
	v_mfma_f32_16x16x32_bf16 v[88:91], v[136:139], v[192:195], v[88:91]
	v_mfma_f32_16x16x32_bf16 v[76:79], v[128:131], v[200:203], v[76:79]
	v_mfma_f32_16x16x32_bf16 v[72:75], v[136:139], v[200:203], v[72:75]
	v_mfma_f32_16x16x32_bf16 v[124:127], v[132:135], v[164:167], v[124:127]
	v_mfma_f32_16x16x32_bf16 v[120:123], v[140:143], v[164:167], v[120:123]
	v_mfma_f32_16x16x32_bf16 v[108:111], v[132:135], v[172:175], v[108:111]
	v_mfma_f32_16x16x32_bf16 v[104:107], v[140:143], v[172:175], v[104:107]
	v_mfma_f32_16x16x32_bf16 v[92:95], v[132:135], v[196:199], v[92:95]
	v_mfma_f32_16x16x32_bf16 v[88:91], v[140:143], v[196:199], v[88:91]
	v_mfma_f32_16x16x32_bf16 v[76:79], v[132:135], v[204:207], v[76:79]
	v_mfma_f32_16x16x32_bf16 v[72:75], v[140:143], v[204:207], v[72:75]
	s_setprio 0
	s_setprio 1
	v_mfma_f32_16x16x32_bf16 v[116:119], v[144:147], v[160:163], v[116:119]
	v_mfma_f32_16x16x32_bf16 v[112:115], v[152:155], v[160:163], v[112:115]
	v_mfma_f32_16x16x32_bf16 v[100:103], v[144:147], v[168:171], v[100:103]
	v_mfma_f32_16x16x32_bf16 v[96:99], v[152:155], v[168:171], v[96:99]
	v_mfma_f32_16x16x32_bf16 v[84:87], v[144:147], v[192:195], v[84:87]
	v_mfma_f32_16x16x32_bf16 v[80:83], v[152:155], v[192:195], v[80:83]
	v_mfma_f32_16x16x32_bf16 v[68:71], v[144:147], v[200:203], v[68:71]
	v_mfma_f32_16x16x32_bf16 v[64:67], v[152:155], v[200:203], v[64:67]
	v_mfma_f32_16x16x32_bf16 v[116:119], v[148:151], v[164:167], v[116:119]
	v_mfma_f32_16x16x32_bf16 v[112:115], v[156:159], v[164:167], v[112:115]
	v_mfma_f32_16x16x32_bf16 v[100:103], v[148:151], v[172:175], v[100:103]
	v_mfma_f32_16x16x32_bf16 v[96:99], v[156:159], v[172:175], v[96:99]
	v_mfma_f32_16x16x32_bf16 v[84:87], v[148:151], v[196:199], v[84:87]
	v_mfma_f32_16x16x32_bf16 v[80:83], v[156:159], v[196:199], v[80:83]
	v_mfma_f32_16x16x32_bf16 v[68:71], v[148:151], v[204:207], v[68:71]
	v_mfma_f32_16x16x32_bf16 v[64:67], v[156:159], v[204:207], v[64:67]
	s_setprio 0
	s_barrier
; #define PG8_STAGE(bufoff, gbase, voff) do { _Pragma("unroll") for (int _i = 0; _i < 2; ++_i) \
;         __builtin_amdgcn_global_load_lds((const unsigned*)((const char*)(gbase) + (voff)[_i]), (LAS unsigned*)(lds + (bufoff) + ldsw + _i * 8192), 16, 0, 0); } while (0)
; #define PG8_LDA(dst, b, h) do { _Pragma("unroll") for (int m = 0; m < 4; ++m) _Pragma("unroll") for (int k = 0; k < 2; ++k) dst[m][k] = *(const LAS bf16x8*)(lds + PG8_SA(b, h) + aoff + m * 2048 + k * 1024); } while (0)
; #define PG8_MMA(ai, bj, At, Bt) do { __builtin_amdgcn_s_setprio(1); _Pragma("unroll") for (int m = 0; m < 4; ++m) _Pragma("unroll") for (int n = 0; n < 2; ++n) _Pragma("unroll") for (int k = 0; k < 2; ++k) \
;         acc[ai][bj][m][n] = __builtin_amdgcn_mfma_f32_16x16x32_bf16(Bt[n][k], At[m][k], acc[ai][bj][m][n], 0, 0, 0); __builtin_amdgcn_s_setprio(0); } while (0)
; #define PG8_WAIT_V(n) asm volatile("s_waitcnt vmcnt(" #n ")" ::: "memory")
; #define PG8_WAIT_L(n) asm volatile("s_waitcnt lgkmcnt(" #n ")" ::: "memory")
; #define PG8_BAR __builtin_amdgcn_s_barrier()
; #define PG8_SCHED __builtin_amdgcn_sched_barrier(0)
; template <class Epi>
; DI void gemm_phase(LAS unsigned char* lds, const int wid, const Gemm g, const Order& S, const Epi& E) {
;     ...
;             PG8_LDA(At, 1, 1); PG8_STAGE(PG8_SB(1, 0), b3, voffB); PG8_STAGE(PG8_SB(1, 1), b3 + hstepB, voffB); PG8_STAGE(PG8_SA(1, 0), a3, voffA);
;             PG8_WAIT_V(8); PG8_WAIT_L(0); PG8_BAR; PG8_MMA(1, 0, At, B0); PG8_MMA(1, 1, At, B1); PG8_BAR; PG8_SCHED;
	s_add_i32 s36, s59, s94
	v_lshl_add_u64 v[208:209], v[208:209], 0, s[26:27]
	s_mov_b32 m0, s36
	ds_read_b128 v[160:163], v218 offset:49152
	ds_read_b128 v[164:167], v218 offset:50176
	ds_read_b128 v[168:171], v218 offset:51200
	ds_read_b128 v[172:175], v218 offset:52224
	ds_read_b128 v[192:195], v218 offset:53248
	ds_read_b128 v[196:199], v218 offset:54272
	ds_read_b128 v[200:203], v218 offset:55296
	ds_read_b128 v[204:207], v218 offset:56320
	global_load_lds_dwordx4 v[208:209], off
	s_add_i32 m0, s36, 0x2000
	s_add_u32 s36, s38, 0xb0080
	v_lshl_add_u64 v[208:209], v[210:211], 0, s[26:27]
	s_addc_u32 s37, s39, 0
	s_add_i32 s38, s60, s94
	global_load_lds_dwordx4 v[208:209], off
	v_lshl_add_u64 v[208:209], s[36:37], 0, v[178:179]
	s_mov_b32 m0, s38
	s_nop 0
	global_load_lds_dwordx4 v[208:209], off
	v_lshl_add_u64 v[208:209], s[36:37], 0, v[182:183]
	s_add_i32 m0, s38, 0x2000
	s_nop 0
	global_load_lds_dwordx4 v[208:209], off
	v_lshl_add_u64 v[208:209], v[212:213], 0, s[26:27]
	s_mov_b32 m0, s48
	s_nop 0
	global_load_lds_dwordx4 v[208:209], off
	v_lshl_add_u64 v[208:209], v[220:221], 0, s[26:27]
	s_mov_b32 m0, s49
	s_nop 0
	global_load_lds_dwordx4 v[208:209], off
	s_waitcnt vmcnt(8)
	s_waitcnt lgkmcnt(0)
	s_barrier
	s_setprio 1
	s_waitcnt lgkmcnt(0)
	v_mfma_f32_16x16x32_bf16 v[60:63], v[128:131], v[160:163], v[60:63]
	v_mfma_f32_16x16x32_bf16 v[56:59], v[136:139], v[160:163], v[56:59]
	v_mfma_f32_16x16x32_bf16 v[44:47], v[128:131], v[168:171], v[44:47]
	v_mfma_f32_16x16x32_bf16 v[40:43], v[136:139], v[168:171], v[40:43]
	v_mfma_f32_16x16x32_bf16 v[28:31], v[128:131], v[192:195], v[28:31]
	v_mfma_f32_16x16x32_bf16 v[24:27], v[136:139], v[192:195], v[24:27]
	v_mfma_f32_16x16x32_bf16 v[12:15], v[128:131], v[200:203], v[12:15]
	v_mfma_f32_16x16x32_bf16 v[8:11], v[136:139], v[200:203], v[8:11]
	v_mfma_f32_16x16x32_bf16 v[60:63], v[132:135], v[164:167], v[60:63]
	v_mfma_f32_16x16x32_bf16 v[56:59], v[140:143], v[164:167], v[56:59]
	v_mfma_f32_16x16x32_bf16 v[44:47], v[132:135], v[172:175], v[44:47]
	v_mfma_f32_16x16x32_bf16 v[40:43], v[140:143], v[172:175], v[40:43]
	v_mfma_f32_16x16x32_bf16 v[28:31], v[132:135], v[196:199], v[28:31]
	v_mfma_f32_16x16x32_bf16 v[24:27], v[140:143], v[196:199], v[24:27]
	v_mfma_f32_16x16x32_bf16 v[12:15], v[132:135], v[204:207], v[12:15]
	v_mfma_f32_16x16x32_bf16 v[8:11], v[140:143], v[204:207], v[8:11]
	s_setprio 0
	s_setprio 1
	v_mfma_f32_16x16x32_bf16 v[52:55], v[144:147], v[160:163], v[52:55]
	v_mfma_f32_16x16x32_bf16 v[48:51], v[152:155], v[160:163], v[48:51]
	v_mfma_f32_16x16x32_bf16 v[36:39], v[144:147], v[168:171], v[36:39]
	v_mfma_f32_16x16x32_bf16 v[32:35], v[152:155], v[168:171], v[32:35]
	v_mfma_f32_16x16x32_bf16 v[20:23], v[144:147], v[192:195], v[20:23]
	v_mfma_f32_16x16x32_bf16 v[16:19], v[152:155], v[192:195], v[16:19]
	v_mfma_f32_16x16x32_bf16 v[4:7], v[144:147], v[200:203], v[4:7]
	v_mfma_f32_16x16x32_bf16 v[0:3], v[152:155], v[200:203], v[0:3]
	v_mfma_f32_16x16x32_bf16 v[52:55], v[148:151], v[164:167], v[52:55]
	v_mfma_f32_16x16x32_bf16 v[48:51], v[156:159], v[164:167], v[48:51]
	v_mfma_f32_16x16x32_bf16 v[36:39], v[148:151], v[172:175], v[36:39]
	v_mfma_f32_16x16x32_bf16 v[32:35], v[156:159], v[172:175], v[32:35]
	v_mfma_f32_16x16x32_bf16 v[20:23], v[148:151], v[196:199], v[20:23]
	v_mfma_f32_16x16x32_bf16 v[16:19], v[156:159], v[196:199], v[16:19]
	v_mfma_f32_16x16x32_bf16 v[4:7], v[148:151], v[204:207], v[4:7]
	v_mfma_f32_16x16x32_bf16 v[0:3], v[156:159], v[204:207], v[0:3]
	s_setprio 0
	s_barrier
	s_add_i32 s58, s58, 2
	s_add_u32 s56, s56, 0x100
	s_addc_u32 s57, s57, 0
	s_cmp_gt_u32 s58, 41
	s_mov_b64 s[36:37], s[10:11]
	s_cbranch_scc0 .LBB0_1421
	s_branch .Lpeel_exit_10

; #define PG8_STAGE(bufoff, gbase, voff) do { _Pragma("unroll") for (int _i = 0; _i < 2; ++_i) \
;         __builtin_amdgcn_global_load_lds((const unsigned*)((const char*)(gbase) + (voff)[_i]), (LAS unsigned*)(lds + (bufoff) + ldsw + _i * 8192), 16, 0, 0); } while (0)
; #define PG8_LDA(dst, b, h) do { _Pragma("unroll") for (int m = 0; m < 4; ++m) _Pragma("unroll") for (int k = 0; k < 2; ++k) dst[m][k] = *(const LAS bf16x8*)(lds + PG8_SA(b, h) + aoff + m * 2048 + k * 1024); } while (0)
; #define PG8_LDB(dst, b, h) do { _Pragma("unroll") for (int n = 0; n < 2; ++n) _Pragma("unroll") for (int k = 0; k < 2; ++k) dst[n][k] = *(const LAS bf16x8*)(lds + PG8_SB(b, h) + boff + n * 2048 + k * 1024); } while (0)
; #define PG8_MMA(ai, bj, At, Bt) do { __builtin_amdgcn_s_setprio(1); _Pragma("unroll") for (int m = 0; m < 4; ++m) _Pragma("unroll") for (int n = 0; n < 2; ++n) _Pragma("unroll") for (int k = 0; k < 2; ++k) \
;         acc[ai][bj][m][n] = __builtin_amdgcn_mfma_f32_16x16x32_bf16(Bt[n][k], At[m][k], acc[ai][bj][m][n], 0, 0, 0); __builtin_amdgcn_s_setprio(0); } while (0)
; #define PG8_WAIT_V(n) asm volatile("s_waitcnt vmcnt(" #n ")" ::: "memory")
; #define PG8_WAIT_L(n) asm volatile("s_waitcnt lgkmcnt(" #n ")" ::: "memory")
; #define PG8_BAR __builtin_amdgcn_s_barrier()
; template <class Epi>
; DI void gemm_phase(LAS unsigned char* lds, const int wid, const Gemm g, const Order& S, const Epi& E) {
;     ...
;             const bool last = (t == nt - 2);
;             const char* a1 = cA + (size_t)(t + 1) * kstep;
;             const char* a2 = last ? nA : cA + (size_t)(t + 2) * kstep; const char* b2 = last ? nB : cB + (size_t)(t + 2) * kstep;
;             const char* a3 = a2 + kstep; const char* b3 = b2 + kstep;
;             PG8_LDB(B0, 0, 0); PG8_LDB(B1, 0, 1); PG8_SCHED; PG8_LDA(At, 0, 0); PG8_STAGE(PG8_SA(1, 1), a1 + hstepA, voffA);
;             PG8_WAIT_V(8); PG8_WAIT_L(0); PG8_BAR; PG8_MMA(0, 0, At, B0); PG8_MMA(0, 1, At, B1); PG8_BAR; PG8_SCHED;
;             PG8_LDA(At, 0, 1); PG8_STAGE(PG8_SB(0, 0), b2, voffB); PG8_STAGE(PG8_SB(0, 1), b2 + hstepB, voffB); PG8_STAGE(PG8_SA(0, 0), a2, voffA);
;     ...
;         for (int a = 0; a < 2; ++a)
; #pragma unroll
;             for (int b = 0; b < 2; ++b)
; #pragma unroll
;                 for (int m = 0; m < 4; ++m)
; #pragma unroll
;                     for (int n = 0; n < 2; ++n) acc[a][b][m][n] = (f32x4){0.f, 0.f, 0.f, 0.f};
.LBB0_1525:
	s_add_u32 s52, s26, 0x100
	v_mov_b32_e32 v0, 0
	s_addc_u32 s53, s27, 0
	s_mov_b32 s54, -2
	ds_read_b128 v[128:131], v229
	ds_read_b128 v[132:135], v229 offset:1024
	ds_read_b128 v[136:139], v229 offset:2048
	ds_read_b128 v[140:143], v229 offset:3072
	ds_read_b128 v[144:147], v230
	ds_read_b128 v[148:151], v230 offset:1024
	ds_read_b128 v[152:155], v230 offset:2048
	ds_read_b128 v[156:159], v230 offset:3072
	s_add_u32 s4, s24, 0x100
	s_addc_u32 s5, s25, 0
	s_cmp_eq_u32 s54, 40
	s_cselect_b32 s29, s21, s5
	s_cselect_b32 s28, s20, s4
	s_cselect_b32 s27, s23, s53
	s_cselect_b32 s26, s22, s52
	v_lshl_add_u64 v[208:209], s[24:25], 0, v[184:185]
	s_add_i32 m0, s36, 0xc000
	ds_read_b128 v[160:163], v231
	ds_read_b128 v[164:167], v231 offset:1024
	ds_read_b128 v[168:171], v231 offset:2048
	ds_read_b128 v[172:175], v231 offset:3072
	ds_read_b128 v[192:195], v231 offset:4096
	ds_read_b128 v[196:199], v231 offset:5120
	ds_read_b128 v[200:203], v231 offset:6144
	ds_read_b128 v[204:207], v231 offset:7168
	global_load_lds_dwordx4 v[208:209], off
	v_lshl_add_u64 v[208:209], s[24:25], 0, v[186:187]
	s_add_i32 m0, s36, 0xe000
	s_nop 0
	global_load_lds_dwordx4 v[208:209], off
	s_waitcnt vmcnt(8)
	s_waitcnt lgkmcnt(0)
	s_barrier
	s_setprio 1
	s_waitcnt lgkmcnt(0)
	v_mfma_f32_16x16x32_bf16 v[124:127], v[128:131], v[160:163], 0
	v_mfma_f32_16x16x32_bf16 v[120:123], v[136:139], v[160:163], 0
	v_mfma_f32_16x16x32_bf16 v[108:111], v[128:131], v[168:171], 0
	v_mfma_f32_16x16x32_bf16 v[104:107], v[136:139], v[168:171], 0
	v_mfma_f32_16x16x32_bf16 v[92:95], v[128:131], v[192:195], 0
	v_mfma_f32_16x16x32_bf16 v[88:91], v[136:139], v[192:195], 0
	v_mfma_f32_16x16x32_bf16 v[76:79], v[128:131], v[200:203], 0
	v_mfma_f32_16x16x32_bf16 v[72:75], v[136:139], v[200:203], 0
	v_mfma_f32_16x16x32_bf16 v[124:127], v[132:135], v[164:167], v[124:127]
	v_mfma_f32_16x16x32_bf16 v[120:123], v[140:143], v[164:167], v[120:123]
	v_mfma_f32_16x16x32_bf16 v[108:111], v[132:135], v[172:175], v[108:111]
	v_mfma_f32_16x16x32_bf16 v[104:107], v[140:143], v[172:175], v[104:107]
	v_mfma_f32_16x16x32_bf16 v[92:95], v[132:135], v[196:199], v[92:95]
	v_mfma_f32_16x16x32_bf16 v[88:91], v[140:143], v[196:199], v[88:91]
	v_mfma_f32_16x16x32_bf16 v[76:79], v[132:135], v[204:207], v[76:79]
	v_mfma_f32_16x16x32_bf16 v[72:75], v[140:143], v[204:207], v[72:75]
	s_setprio 0
	s_setprio 1
	v_mfma_f32_16x16x32_bf16 v[116:119], v[144:147], v[160:163], 0
	v_mfma_f32_16x16x32_bf16 v[112:115], v[152:155], v[160:163], 0
	v_mfma_f32_16x16x32_bf16 v[100:103], v[144:147], v[168:171], 0
	v_mfma_f32_16x16x32_bf16 v[96:99], v[152:155], v[168:171], 0
	v_mfma_f32_16x16x32_bf16 v[84:87], v[144:147], v[192:195], 0
	v_mfma_f32_16x16x32_bf16 v[80:83], v[152:155], v[192:195], 0
	v_mfma_f32_16x16x32_bf16 v[68:71], v[144:147], v[200:203], 0
	v_mfma_f32_16x16x32_bf16 v[64:67], v[152:155], v[200:203], 0
	v_mfma_f32_16x16x32_bf16 v[116:119], v[148:151], v[164:167], v[116:119]
	v_mfma_f32_16x16x32_bf16 v[112:115], v[156:159], v[164:167], v[112:115]
	v_mfma_f32_16x16x32_bf16 v[100:103], v[148:151], v[172:175], v[100:103]
	v_mfma_f32_16x16x32_bf16 v[96:99], v[156:159], v[172:175], v[96:99]
	v_mfma_f32_16x16x32_bf16 v[84:87], v[148:151], v[196:199], v[84:87]
	v_mfma_f32_16x16x32_bf16 v[80:83], v[156:159], v[196:199], v[80:83]
	v_mfma_f32_16x16x32_bf16 v[68:71], v[148:151], v[204:207], v[68:71]
	v_mfma_f32_16x16x32_bf16 v[64:67], v[156:159], v[204:207], v[64:67]
	s_setprio 0
	s_barrier
	s_add_i32 s24, s46, s94
	v_lshl_add_u64 v[208:209], s[26:27], 0, v[178:179]
	s_mov_b32 m0, s24
	ds_read_b128 v[160:163], v231 offset:16384
	ds_read_b128 v[164:167], v231 offset:17408
	ds_read_b128 v[168:171], v231 offset:18432
	ds_read_b128 v[172:175], v231 offset:19456
	ds_read_b128 v[192:195], v231 offset:20480
	ds_read_b128 v[196:199], v231 offset:21504
	ds_read_b128 v[200:203], v231 offset:22528
	ds_read_b128 v[204:207], v231 offset:23552
	global_load_lds_dwordx4 v[208:209], off
	s_add_i32 m0, s24, 0x2000
	s_add_u32 s24, s26, 0xb0000
	v_lshl_add_u64 v[210:211], s[26:27], 0, v[182:183]
	s_addc_u32 s25, s27, 0
	s_add_i32 s55, s47, s94
	global_load_lds_dwordx4 v[210:211], off
	v_lshl_add_u64 v[212:213], s[24:25], 0, v[178:179]
	s_mov_b32 m0, s55
	v_lshl_add_u64 v[214:215], s[28:29], 0, v[180:181]
	global_load_lds_dwordx4 v[212:213], off
	v_lshl_add_u64 v[212:213], s[24:25], 0, v[182:183]
	s_add_i32 m0, s55, 0x2000
	s_nop 0
	global_load_lds_dwordx4 v[212:213], off
	v_lshl_add_u64 v[212:213], s[28:29], 0, v[176:177]
	s_mov_b32 m0, s36
	s_nop 0
	global_load_lds_dwordx4 v[212:213], off
	s_mov_b32 m0, s37
	s_nop 0
	global_load_lds_dwordx4 v[214:215], off
	s_waitcnt vmcnt(8)
	s_waitcnt lgkmcnt(0)
	s_barrier
; #define PG8_STAGE(bufoff, gbase, voff) do { _Pragma("unroll") for (int _i = 0; _i < 2; ++_i) \
;         __builtin_amdgcn_global_load_lds((const unsigned*)((const char*)(gbase) + (voff)[_i]), (LAS unsigned*)(lds + (bufoff) + ldsw + _i * 8192), 16, 0, 0); } while (0)
; #define PG8_LDA(dst, b, h) do { _Pragma("unroll") for (int m = 0; m < 4; ++m) _Pragma("unroll") for (int k = 0; k < 2; ++k) dst[m][k] = *(const LAS bf16x8*)(lds + PG8_SA(b, h) + aoff + m * 2048 + k * 1024); } while (0)
; #define PG8_LDB(dst, b, h) do { _Pragma("unroll") for (int n = 0; n < 2; ++n) _Pragma("unroll") for (int k = 0; k < 2; ++k) dst[n][k] = *(const LAS bf16x8*)(lds + PG8_SB(b, h) + boff + n * 2048 + k * 1024); } while (0)
; #define PG8_MMA(ai, bj, At, Bt) do { __builtin_amdgcn_s_setprio(1); _Pragma("unroll") for (int m = 0; m < 4; ++m) _Pragma("unroll") for (int n = 0; n < 2; ++n) _Pragma("unroll") for (int k = 0; k < 2; ++k) \
;         acc[ai][bj][m][n] = __builtin_amdgcn_mfma_f32_16x16x32_bf16(Bt[n][k], At[m][k], acc[ai][bj][m][n], 0, 0, 0); __builtin_amdgcn_s_setprio(0); } while (0)
; #define PG8_WAIT_V(n) asm volatile("s_waitcnt vmcnt(" #n ")" ::: "memory")
; #define PG8_WAIT_L(n) asm volatile("s_waitcnt lgkmcnt(" #n ")" ::: "memory")
; #define PG8_BAR __builtin_amdgcn_s_barrier()
; #define PG8_SCHED __builtin_amdgcn_sched_barrier(0)
; template <class Epi>
; DI void gemm_phase(LAS unsigned char* lds, const int wid, const Gemm g, const Order& S, const Epi& E) {
;     ...
;             PG8_WAIT_V(8); PG8_WAIT_L(0); PG8_BAR; PG8_MMA(1, 0, At, B0); PG8_MMA(1, 1, At, B1); PG8_BAR; PG8_SCHED;
;             PG8_LDB(B0, 1, 0); PG8_LDB(B1, 1, 1); PG8_SCHED; PG8_LDA(At, 1, 0); PG8_STAGE(PG8_SA(0, 1), a2 + hstepA, voffA);
;             PG8_WAIT_V(8); PG8_WAIT_L(0); PG8_BAR; PG8_MMA(0, 0, At, B0); PG8_MMA(0, 1, At, B1); PG8_BAR; PG8_SCHED;
	s_setprio 1
	s_waitcnt lgkmcnt(0)
	v_mfma_f32_16x16x32_bf16 v[60:63], v[128:131], v[160:163], 0
	v_mfma_f32_16x16x32_bf16 v[56:59], v[136:139], v[160:163], 0
	v_mfma_f32_16x16x32_bf16 v[44:47], v[128:131], v[168:171], 0
	v_mfma_f32_16x16x32_bf16 v[40:43], v[136:139], v[168:171], 0
	v_mfma_f32_16x16x32_bf16 v[28:31], v[128:131], v[192:195], 0
	v_mfma_f32_16x16x32_bf16 v[24:27], v[136:139], v[192:195], 0
	v_mfma_f32_16x16x32_bf16 v[12:15], v[128:131], v[200:203], 0
	v_mfma_f32_16x16x32_bf16 v[8:11], v[136:139], v[200:203], 0
	v_mfma_f32_16x16x32_bf16 v[60:63], v[132:135], v[164:167], v[60:63]
	v_mfma_f32_16x16x32_bf16 v[56:59], v[140:143], v[164:167], v[56:59]
	v_mfma_f32_16x16x32_bf16 v[44:47], v[132:135], v[172:175], v[44:47]
	v_mfma_f32_16x16x32_bf16 v[40:43], v[140:143], v[172:175], v[40:43]
	v_mfma_f32_16x16x32_bf16 v[28:31], v[132:135], v[196:199], v[28:31]
	v_mfma_f32_16x16x32_bf16 v[24:27], v[140:143], v[196:199], v[24:27]
	v_mfma_f32_16x16x32_bf16 v[12:15], v[132:135], v[204:207], v[12:15]
	v_mfma_f32_16x16x32_bf16 v[8:11], v[140:143], v[204:207], v[8:11]
	s_setprio 0
	s_setprio 1
	v_mfma_f32_16x16x32_bf16 v[52:55], v[144:147], v[160:163], 0
	v_mfma_f32_16x16x32_bf16 v[48:51], v[152:155], v[160:163], 0
	v_mfma_f32_16x16x32_bf16 v[36:39], v[144:147], v[168:171], 0
	v_mfma_f32_16x16x32_bf16 v[32:35], v[152:155], v[168:171], 0
	v_mfma_f32_16x16x32_bf16 v[20:23], v[144:147], v[192:195], 0
	v_mfma_f32_16x16x32_bf16 v[16:19], v[152:155], v[192:195], 0
	v_mfma_f32_16x16x32_bf16 v[4:7], v[144:147], v[200:203], 0
	v_mfma_f32_16x16x32_bf16 v[0:3], v[152:155], v[200:203], 0
	v_mfma_f32_16x16x32_bf16 v[52:55], v[148:151], v[164:167], v[52:55]
	v_mfma_f32_16x16x32_bf16 v[48:51], v[156:159], v[164:167], v[48:51]
	v_mfma_f32_16x16x32_bf16 v[36:39], v[148:151], v[172:175], v[36:39]
	v_mfma_f32_16x16x32_bf16 v[32:35], v[156:159], v[172:175], v[32:35]
	v_mfma_f32_16x16x32_bf16 v[20:23], v[148:151], v[196:199], v[20:23]
	v_mfma_f32_16x16x32_bf16 v[16:19], v[156:159], v[196:199], v[16:19]
	v_mfma_f32_16x16x32_bf16 v[4:7], v[148:151], v[204:207], v[4:7]
	v_mfma_f32_16x16x32_bf16 v[0:3], v[156:159], v[204:207], v[0:3]
	s_setprio 0
	s_barrier
	s_add_i32 s55, 0, 0x18000
	s_add_i32 s56, 0, 0x1c000
	v_add_u32_e32 v140, s55, v228
	v_add_u32_e32 v156, s56, v228
	ds_read_b128 v[128:131], v140
	ds_read_b128 v[132:135], v140 offset:1024
	ds_read_b128 v[136:139], v140 offset:2048
	ds_read_b128 v[140:143], v140 offset:3072
	ds_read_b128 v[144:147], v156
	ds_read_b128 v[148:151], v156 offset:1024
	ds_read_b128 v[152:155], v156 offset:2048
	ds_read_b128 v[156:159], v156 offset:3072
	s_add_u32 s24, s28, 0xb0000
	s_addc_u32 s25, s29, 0
	s_mov_b32 m0, s38
	v_lshl_add_u64 v[216:217], s[24:25], 0, v[176:177]
	ds_read_b128 v[160:163], v231 offset:32768
	ds_read_b128 v[164:167], v231 offset:33792
	ds_read_b128 v[168:171], v231 offset:34816
	ds_read_b128 v[172:175], v231 offset:35840
	ds_read_b128 v[192:195], v231 offset:36864
	ds_read_b128 v[196:199], v231 offset:37888
	ds_read_b128 v[200:203], v231 offset:38912
	ds_read_b128 v[204:207], v231 offset:39936
	global_load_lds_dwordx4 v[216:217], off
	v_lshl_add_u64 v[216:217], s[24:25], 0, v[180:181]
	s_mov_b32 m0, s39
	s_nop 0
	global_load_lds_dwordx4 v[216:217], off
	s_waitcnt vmcnt(8)
	s_waitcnt lgkmcnt(0)
	s_barrier
	s_setprio 1
	s_waitcnt lgkmcnt(0)
	v_mfma_f32_16x16x32_bf16 v[124:127], v[128:131], v[160:163], v[124:127]
	v_mfma_f32_16x16x32_bf16 v[120:123], v[136:139], v[160:163], v[120:123]
	v_mfma_f32_16x16x32_bf16 v[108:111], v[128:131], v[168:171], v[108:111]
	v_mfma_f32_16x16x32_bf16 v[104:107], v[136:139], v[168:171], v[104:107]
	v_mfma_f32_16x16x32_bf16 v[92:95], v[128:131], v[192:195], v[92:95]
	v_mfma_f32_16x16x32_bf16 v[88:91], v[136:139], v[192:195], v[88:91]
	v_mfma_f32_16x16x32_bf16 v[76:79], v[128:131], v[200:203], v[76:79]
	v_mfma_f32_16x16x32_bf16 v[72:75], v[136:139], v[200:203], v[72:75]
	v_mfma_f32_16x16x32_bf16 v[124:127], v[132:135], v[164:167], v[124:127]
	v_mfma_f32_16x16x32_bf16 v[120:123], v[140:143], v[164:167], v[120:123]
	v_mfma_f32_16x16x32_bf16 v[108:111], v[132:135], v[172:175], v[108:111]
	v_mfma_f32_16x16x32_bf16 v[104:107], v[140:143], v[172:175], v[104:107]
	v_mfma_f32_16x16x32_bf16 v[92:95], v[132:135], v[196:199], v[92:95]
	v_mfma_f32_16x16x32_bf16 v[88:91], v[140:143], v[196:199], v[88:91]
	v_mfma_f32_16x16x32_bf16 v[76:79], v[132:135], v[204:207], v[76:79]
	v_mfma_f32_16x16x32_bf16 v[72:75], v[140:143], v[204:207], v[72:75]
	s_setprio 0
	s_setprio 1
	v_mfma_f32_16x16x32_bf16 v[116:119], v[144:147], v[160:163], v[116:119]
	v_mfma_f32_16x16x32_bf16 v[112:115], v[152:155], v[160:163], v[112:115]
	v_mfma_f32_16x16x32_bf16 v[100:103], v[144:147], v[168:171], v[100:103]
	v_mfma_f32_16x16x32_bf16 v[96:99], v[152:155], v[168:171], v[96:99]
	v_mfma_f32_16x16x32_bf16 v[84:87], v[144:147], v[192:195], v[84:87]
	v_mfma_f32_16x16x32_bf16 v[80:83], v[152:155], v[192:195], v[80:83]
	v_mfma_f32_16x16x32_bf16 v[68:71], v[144:147], v[200:203], v[68:71]
	v_mfma_f32_16x16x32_bf16 v[64:67], v[152:155], v[200:203], v[64:67]
	v_mfma_f32_16x16x32_bf16 v[116:119], v[148:151], v[164:167], v[116:119]
	v_mfma_f32_16x16x32_bf16 v[112:115], v[156:159], v[164:167], v[112:115]
	v_mfma_f32_16x16x32_bf16 v[100:103], v[148:151], v[172:175], v[100:103]
	v_mfma_f32_16x16x32_bf16 v[96:99], v[156:159], v[172:175], v[96:99]
	v_mfma_f32_16x16x32_bf16 v[84:87], v[148:151], v[196:199], v[84:87]
	v_mfma_f32_16x16x32_bf16 v[80:83], v[156:159], v[196:199], v[80:83]
	v_mfma_f32_16x16x32_bf16 v[68:71], v[148:151], v[204:207], v[68:71]
	v_mfma_f32_16x16x32_bf16 v[64:67], v[156:159], v[204:207], v[64:67]
	s_setprio 0
	s_barrier
; #define PG8_STAGE(bufoff, gbase, voff) do { _Pragma("unroll") for (int _i = 0; _i < 2; ++_i) \
;         __builtin_amdgcn_global_load_lds((const unsigned*)((const char*)(gbase) + (voff)[_i]), (LAS unsigned*)(lds + (bufoff) + ldsw + _i * 8192), 16, 0, 0); } while (0)
; #define PG8_LDA(dst, b, h) do { _Pragma("unroll") for (int m = 0; m < 4; ++m) _Pragma("unroll") for (int k = 0; k < 2; ++k) dst[m][k] = *(const LAS bf16x8*)(lds + PG8_SA(b, h) + aoff + m * 2048 + k * 1024); } while (0)
; #define PG8_MMA(ai, bj, At, Bt) do { __builtin_amdgcn_s_setprio(1); _Pragma("unroll") for (int m = 0; m < 4; ++m) _Pragma("unroll") for (int n = 0; n < 2; ++n) _Pragma("unroll") for (int k = 0; k < 2; ++k) \
;         acc[ai][bj][m][n] = __builtin_amdgcn_mfma_f32_16x16x32_bf16(Bt[n][k], At[m][k], acc[ai][bj][m][n], 0, 0, 0); __builtin_amdgcn_s_setprio(0); } while (0)
; #define PG8_WAIT_V(n) asm volatile("s_waitcnt vmcnt(" #n ")" ::: "memory")
; #define PG8_WAIT_L(n) asm volatile("s_waitcnt lgkmcnt(" #n ")" ::: "memory")
; #define PG8_BAR __builtin_amdgcn_s_barrier()
; #define PG8_SCHED __builtin_amdgcn_sched_barrier(0)
; template <class Epi>
; DI void gemm_phase(LAS unsigned char* lds, const int wid, const Gemm g, const Order& S, const Epi& E) {
;     ...
;             PG8_LDA(At, 1, 1); PG8_STAGE(PG8_SB(1, 0), b3, voffB); PG8_STAGE(PG8_SB(1, 1), b3 + hstepB, voffB); PG8_STAGE(PG8_SA(1, 0), a3, voffA);
;             PG8_WAIT_V(8); PG8_WAIT_L(0); PG8_BAR; PG8_MMA(1, 0, At, B0); PG8_MMA(1, 1, At, B1); PG8_BAR; PG8_SCHED;
	s_add_i32 s24, s55, s94
	v_lshl_add_u64 v[208:209], v[208:209], 0, s[16:17]
	s_mov_b32 m0, s24
	ds_read_b128 v[160:163], v231 offset:49152
	ds_read_b128 v[164:167], v231 offset:50176
	ds_read_b128 v[168:171], v231 offset:51200
	ds_read_b128 v[172:175], v231 offset:52224
	ds_read_b128 v[192:195], v231 offset:53248
	ds_read_b128 v[196:199], v231 offset:54272
	ds_read_b128 v[200:203], v231 offset:55296
	ds_read_b128 v[204:207], v231 offset:56320
	global_load_lds_dwordx4 v[208:209], off
	s_add_i32 m0, s24, 0x2000
	s_add_u32 s24, s26, 0xb0080
	v_lshl_add_u64 v[208:209], v[210:211], 0, s[16:17]
	s_addc_u32 s25, s27, 0
	s_add_i32 s26, s56, s94
	global_load_lds_dwordx4 v[208:209], off
	v_lshl_add_u64 v[208:209], s[24:25], 0, v[178:179]
	s_mov_b32 m0, s26
	s_nop 0
	global_load_lds_dwordx4 v[208:209], off
	v_lshl_add_u64 v[208:209], s[24:25], 0, v[182:183]
	s_add_i32 m0, s26, 0x2000
	s_nop 0
	global_load_lds_dwordx4 v[208:209], off
	v_lshl_add_u64 v[208:209], v[212:213], 0, s[16:17]
	s_mov_b32 m0, s43
	s_nop 0
	global_load_lds_dwordx4 v[208:209], off
	v_lshl_add_u64 v[208:209], v[214:215], 0, s[16:17]
	s_mov_b32 m0, s44
	s_nop 0
	global_load_lds_dwordx4 v[208:209], off
	s_waitcnt vmcnt(8)
	s_waitcnt lgkmcnt(0)
	s_barrier
	s_setprio 1
	s_waitcnt lgkmcnt(0)
	v_mfma_f32_16x16x32_bf16 v[60:63], v[128:131], v[160:163], v[60:63]
	v_mfma_f32_16x16x32_bf16 v[56:59], v[136:139], v[160:163], v[56:59]
	v_mfma_f32_16x16x32_bf16 v[44:47], v[128:131], v[168:171], v[44:47]
	v_mfma_f32_16x16x32_bf16 v[40:43], v[136:139], v[168:171], v[40:43]
	v_mfma_f32_16x16x32_bf16 v[28:31], v[128:131], v[192:195], v[28:31]
	v_mfma_f32_16x16x32_bf16 v[24:27], v[136:139], v[192:195], v[24:27]
	v_mfma_f32_16x16x32_bf16 v[12:15], v[128:131], v[200:203], v[12:15]
	v_mfma_f32_16x16x32_bf16 v[8:11], v[136:139], v[200:203], v[8:11]
	v_mfma_f32_16x16x32_bf16 v[60:63], v[132:135], v[164:167], v[60:63]
	v_mfma_f32_16x16x32_bf16 v[56:59], v[140:143], v[164:167], v[56:59]
	v_mfma_f32_16x16x32_bf16 v[44:47], v[132:135], v[172:175], v[44:47]
	v_mfma_f32_16x16x32_bf16 v[40:43], v[140:143], v[172:175], v[40:43]
	v_mfma_f32_16x16x32_bf16 v[28:31], v[132:135], v[196:199], v[28:31]
	v_mfma_f32_16x16x32_bf16 v[24:27], v[140:143], v[196:199], v[24:27]
	v_mfma_f32_16x16x32_bf16 v[12:15], v[132:135], v[204:207], v[12:15]
	v_mfma_f32_16x16x32_bf16 v[8:11], v[140:143], v[204:207], v[8:11]
	s_setprio 0
	s_setprio 1
	v_mfma_f32_16x16x32_bf16 v[52:55], v[144:147], v[160:163], v[52:55]
	v_mfma_f32_16x16x32_bf16 v[48:51], v[152:155], v[160:163], v[48:51]
	v_mfma_f32_16x16x32_bf16 v[36:39], v[144:147], v[168:171], v[36:39]
	v_mfma_f32_16x16x32_bf16 v[32:35], v[152:155], v[168:171], v[32:35]
	v_mfma_f32_16x16x32_bf16 v[20:23], v[144:147], v[192:195], v[20:23]
	v_mfma_f32_16x16x32_bf16 v[16:19], v[152:155], v[192:195], v[16:19]
	v_mfma_f32_16x16x32_bf16 v[4:7], v[144:147], v[200:203], v[4:7]
	v_mfma_f32_16x16x32_bf16 v[0:3], v[152:155], v[200:203], v[0:3]
	v_mfma_f32_16x16x32_bf16 v[52:55], v[148:151], v[164:167], v[52:55]
	v_mfma_f32_16x16x32_bf16 v[48:51], v[156:159], v[164:167], v[48:51]
	v_mfma_f32_16x16x32_bf16 v[36:39], v[148:151], v[172:175], v[36:39]
	v_mfma_f32_16x16x32_bf16 v[32:35], v[156:159], v[172:175], v[32:35]
	v_mfma_f32_16x16x32_bf16 v[20:23], v[148:151], v[196:199], v[20:23]
	v_mfma_f32_16x16x32_bf16 v[16:19], v[156:159], v[196:199], v[16:19]
	v_mfma_f32_16x16x32_bf16 v[4:7], v[148:151], v[204:207], v[4:7]
	v_mfma_f32_16x16x32_bf16 v[0:3], v[156:159], v[204:207], v[0:3]
	s_setprio 0
	s_barrier
	s_add_i32 s54, s54, 2
	s_add_u32 s52, s52, 0x100
	s_addc_u32 s53, s53, 0
	s_cmp_gt_u32 s54, 41
	s_mov_b64 s[24:25], s[4:5]
	s_cbranch_scc0 .LBB0_1526
	s_branch .Lpeel_exit_11

; #define PG8_BAR __builtin_amdgcn_s_barrier()
; template <class Epi>
; DI void gemm_phase(LAS unsigned char* lds, const int wid, const Gemm g, const Order& S, const Epi& E) {
;     ...
;         if (wr == 0) PG8_BAR;
.Lpeel_exit_11:
	s_and_b64 vcc, exec, s[18:19]
	s_cbranch_vccz .LBB0_1529
	s_barrier
